# transpose_item load ladders batched: all 32 W (+32 gain) loads issued first, one wait, then muls+ds_writes (8 of 10 instances)
# speedup vs baseline: 1.0095x; 1.0052x over previous
.LBB0_27:
	s_andn2_b64 vcc, exec, s[4:5]
	s_cbranch_vccnz .LBB0_94
	s_add_i32 s8, s24, 0xf300
	s_add_u32 s22, s40, s28
	s_addc_u32 s23, s41, 0
	s_load_dwordx4 s[4:7], s[22:23], 0xb0
	s_and_b64 s[22:23], s[20:21], exec
	s_cselect_b32 s22, 0x1000000, 0
	v_lshlrev_b32_e32 v10, 2, v8
	s_waitcnt lgkmcnt(0)
	s_add_u32 s22, s6, s22
	s_addc_u32 s23, s7, 0
	s_and_b64 s[6:7], s[20:21], exec
	s_cselect_b32 s6, 0x1000, 0
	s_add_u32 s6, s4, s6
	s_addc_u32 s7, s5, 0
	s_lshr_b32 s8, s8, 1
	s_lshl_b32 s38, s24, 5
	s_and_b32 s25, s8, 0x7fc0
	s_and_b32 s8, s38, 0xfe0
	s_lshl_b32 s38, s8, 2
	s_add_u32 s22, s22, s38
	s_addc_u32 s23, s23, 0
	v_or_b32_e32 v19, s25, v6
	v_lshl_add_u64 v[16:17], s[22:23], 0, v[10:11]
	v_lshlrev_b32_e32 v10, 14, v19
	v_lshl_add_u64 v[78:79], v[16:17], 0, v[10:11]
	s_cmp_eq_u64 s[4:5], 0
	s_cbranch_scc1 .Lladder_ng_0
	global_load_dword v82, v[78:79], off
	v_lshlrev_b32_e32 v10, 2, v19
	global_load_dword v83, v10, s[6:7]
	v_or_b32_e32 v10, s25, v5
	v_lshlrev_b32_e32 v10, 14, v10
	v_lshl_add_u64 v[78:79], v[16:17], 0, v[10:11]
	global_load_dword v84, v[78:79], off
	v_add_lshl_u32 v18, s25, v6, 2
	global_load_dword v85, v18, s[6:7] offset:8
	v_or_b32_e32 v10, s25, v13
	v_lshlrev_b32_e32 v10, 14, v10
	v_lshl_add_u64 v[78:79], v[16:17], 0, v[10:11]
	global_load_dword v86, v[78:79], off
	global_load_dword v87, v18, s[6:7] offset:16
	v_or_b32_e32 v10, s25, v21
	v_lshlrev_b32_e32 v10, 14, v10
	v_lshl_add_u64 v[78:79], v[16:17], 0, v[10:11]
	global_load_dword v88, v[78:79], off
	global_load_dword v89, v18, s[6:7] offset:24
	v_or_b32_e32 v10, s25, v23
	v_lshlrev_b32_e32 v10, 14, v10
	v_lshl_add_u64 v[78:79], v[16:17], 0, v[10:11]
	global_load_dword v90, v[78:79], off
	global_load_dword v91, v18, s[6:7] offset:32
	v_or_b32_e32 v10, s25, v25
	v_lshlrev_b32_e32 v10, 14, v10
	v_lshl_add_u64 v[78:79], v[16:17], 0, v[10:11]
	global_load_dword v92, v[78:79], off
	global_load_dword v93, v18, s[6:7] offset:40
	v_or_b32_e32 v10, s25, v27
	v_lshlrev_b32_e32 v10, 14, v10
	v_lshl_add_u64 v[78:79], v[16:17], 0, v[10:11]
	global_load_dword v94, v[78:79], off
	global_load_dword v95, v18, s[6:7] offset:48
	v_or_b32_e32 v10, s25, v29
	v_lshlrev_b32_e32 v10, 14, v10
	v_lshl_add_u64 v[78:79], v[16:17], 0, v[10:11]
	global_load_dword v96, v[78:79], off
	global_load_dword v97, v18, s[6:7] offset:56
	v_or_b32_e32 v10, s25, v31
	v_lshlrev_b32_e32 v10, 14, v10
	v_lshl_add_u64 v[78:79], v[16:17], 0, v[10:11]
	global_load_dword v98, v[78:79], off
	global_load_dword v99, v18, s[6:7] offset:64
	v_or_b32_e32 v10, s25, v33
	v_lshlrev_b32_e32 v10, 14, v10
	v_lshl_add_u64 v[78:79], v[16:17], 0, v[10:11]
	global_load_dword v100, v[78:79], off
	global_load_dword v101, v18, s[6:7] offset:72
	v_or_b32_e32 v10, s25, v35
	v_lshlrev_b32_e32 v10, 14, v10
	v_lshl_add_u64 v[78:79], v[16:17], 0, v[10:11]
	global_load_dword v102, v[78:79], off
	global_load_dword v103, v18, s[6:7] offset:80
	v_or_b32_e32 v10, s25, v37
	v_lshlrev_b32_e32 v10, 14, v10
	v_lshl_add_u64 v[78:79], v[16:17], 0, v[10:11]
	global_load_dword v104, v[78:79], off
	global_load_dword v105, v18, s[6:7] offset:88
	v_or_b32_e32 v10, s25, v39
	v_lshlrev_b32_e32 v10, 14, v10
	v_lshl_add_u64 v[78:79], v[16:17], 0, v[10:11]
	global_load_dword v106, v[78:79], off
	global_load_dword v107, v18, s[6:7] offset:96
	v_or_b32_e32 v10, s25, v41
	v_lshlrev_b32_e32 v10, 14, v10
	v_lshl_add_u64 v[78:79], v[16:17], 0, v[10:11]
	global_load_dword v108, v[78:79], off
	global_load_dword v109, v18, s[6:7] offset:104
	v_or_b32_e32 v10, s25, v43
	v_lshlrev_b32_e32 v10, 14, v10
	v_lshl_add_u64 v[78:79], v[16:17], 0, v[10:11]
	global_load_dword v110, v[78:79], off
	global_load_dword v111, v18, s[6:7] offset:112
	v_or_b32_e32 v10, s25, v45
	v_lshlrev_b32_e32 v10, 14, v10
	v_lshl_add_u64 v[78:79], v[16:17], 0, v[10:11]
	global_load_dword v112, v[78:79], off
	global_load_dword v113, v18, s[6:7] offset:120
	v_or_b32_e32 v10, s25, v47
	v_lshlrev_b32_e32 v10, 14, v10
	v_lshl_add_u64 v[78:79], v[16:17], 0, v[10:11]
	global_load_dword v114, v[78:79], off
	global_load_dword v115, v18, s[6:7] offset:128
	v_or_b32_e32 v10, s25, v49
	v_lshlrev_b32_e32 v10, 14, v10
	v_lshl_add_u64 v[78:79], v[16:17], 0, v[10:11]
	global_load_dword v116, v[78:79], off
	global_load_dword v117, v18, s[6:7] offset:136
	v_or_b32_e32 v10, s25, v51
	v_lshlrev_b32_e32 v10, 14, v10
	v_lshl_add_u64 v[78:79], v[16:17], 0, v[10:11]
	global_load_dword v118, v[78:79], off
	global_load_dword v119, v18, s[6:7] offset:144
	v_or_b32_e32 v10, s25, v61
	v_lshlrev_b32_e32 v10, 14, v10
	v_lshl_add_u64 v[78:79], v[16:17], 0, v[10:11]
	global_load_dword v120, v[78:79], off
	global_load_dword v121, v18, s[6:7] offset:152
	v_or_b32_e32 v10, s25, v62
	v_lshlrev_b32_e32 v10, 14, v10
	v_lshl_add_u64 v[78:79], v[16:17], 0, v[10:11]
	global_load_dword v122, v[78:79], off
	global_load_dword v123, v18, s[6:7] offset:160
	v_or_b32_e32 v10, s25, v63
	v_lshlrev_b32_e32 v10, 14, v10
	v_lshl_add_u64 v[78:79], v[16:17], 0, v[10:11]
	global_load_dword v124, v[78:79], off
	global_load_dword v125, v18, s[6:7] offset:168
	v_or_b32_e32 v10, s25, v64
	v_lshlrev_b32_e32 v10, 14, v10
	v_lshl_add_u64 v[78:79], v[16:17], 0, v[10:11]
	global_load_dword v126, v[78:79], off
	global_load_dword v127, v18, s[6:7] offset:176
	v_or_b32_e32 v10, s25, v65
	v_lshlrev_b32_e32 v10, 14, v10
	v_lshl_add_u64 v[78:79], v[16:17], 0, v[10:11]
	global_load_dword v128, v[78:79], off
	global_load_dword v129, v18, s[6:7] offset:184
	v_or_b32_e32 v10, s25, v66
	v_lshlrev_b32_e32 v10, 14, v10
	v_lshl_add_u64 v[78:79], v[16:17], 0, v[10:11]
	global_load_dword v130, v[78:79], off
	global_load_dword v131, v18, s[6:7] offset:192
	v_or_b32_e32 v10, s25, v67
	v_lshlrev_b32_e32 v10, 14, v10
	v_lshl_add_u64 v[78:79], v[16:17], 0, v[10:11]
	global_load_dword v132, v[78:79], off
	global_load_dword v133, v18, s[6:7] offset:200
	v_or_b32_e32 v10, s25, v68
	v_lshlrev_b32_e32 v10, 14, v10
	v_lshl_add_u64 v[80:81], v[16:17], 0, v[10:11]
	global_load_dword v134, v[80:81], off
	global_load_dword v135, v18, s[6:7] offset:208
	v_or_b32_e32 v10, s25, v69
	v_lshlrev_b32_e32 v10, 14, v10
	v_lshl_add_u64 v[78:79], v[16:17], 0, v[10:11]
	global_load_dword v136, v[78:79], off
	global_load_dword v137, v18, s[6:7] offset:216
	v_or_b32_e32 v10, s25, v70
	v_lshlrev_b32_e32 v10, 14, v10
	v_lshl_add_u64 v[80:81], v[16:17], 0, v[10:11]
	global_load_dword v138, v[80:81], off
	global_load_dword v139, v18, s[6:7] offset:224
	v_or_b32_e32 v10, s25, v71
	v_lshlrev_b32_e32 v10, 14, v10
	v_lshl_add_u64 v[78:79], v[16:17], 0, v[10:11]
	global_load_dword v140, v[78:79], off
	global_load_dword v141, v18, s[6:7] offset:232
	v_or_b32_e32 v10, s25, v72
	v_lshlrev_b32_e32 v10, 14, v10
	v_lshl_add_u64 v[80:81], v[16:17], 0, v[10:11]
	global_load_dword v142, v[80:81], off
	global_load_dword v143, v18, s[6:7] offset:240
	v_or_b32_e32 v10, s25, v73
	v_lshlrev_b32_e32 v10, 14, v10
	v_lshl_add_u64 v[16:17], v[16:17], 0, v[10:11]
	global_load_dword v144, v[16:17], off
	global_load_dword v145, v18, s[6:7] offset:248
	s_waitcnt vmcnt(0)
	v_mul_f32_e32 v82, v82, v83
	v_add_u32_e32 v146, v1, v3
	ds_write_b32 v146, v82
	v_mul_f32_e32 v84, v84, v85
	v_add_u32_e32 v147, v1, v9
	ds_write_b32 v147, v84
	v_mul_f32_e32 v86, v86, v87
	v_add_u32_e32 v148, v1, v20
	ds_write_b32 v148, v86
	v_mul_f32_e32 v88, v88, v89
	v_add_u32_e32 v149, v1, v22
	ds_write_b32 v149, v88
	v_mul_f32_e32 v90, v90, v91
	v_add_u32_e32 v150, v1, v24
	ds_write_b32 v150, v90
	v_mul_f32_e32 v92, v92, v93
	v_add_u32_e32 v151, v1, v26
	ds_write_b32 v151, v92
	v_mul_f32_e32 v94, v94, v95
	v_add_u32_e32 v152, v1, v28
	ds_write_b32 v152, v94
	v_mul_f32_e32 v96, v96, v97
	v_add_u32_e32 v153, v1, v30
	ds_write_b32 v153, v96
	v_mul_f32_e32 v98, v98, v99
	v_add_u32_e32 v154, v1, v32
	ds_write_b32 v154, v98
	v_mul_f32_e32 v100, v100, v101
	v_add_u32_e32 v155, v1, v34
	ds_write_b32 v155, v100
	v_mul_f32_e32 v102, v102, v103
	v_add_u32_e32 v156, v1, v36
	ds_write_b32 v156, v102
	v_mul_f32_e32 v104, v104, v105
	v_add_u32_e32 v157, v1, v38
	ds_write_b32 v157, v104
	v_mul_f32_e32 v106, v106, v107
	v_add_u32_e32 v158, v1, v40
	ds_write_b32 v158, v106
	v_mul_f32_e32 v108, v108, v109
	v_add_u32_e32 v159, v1, v42
	ds_write_b32 v159, v108
	v_mul_f32_e32 v110, v110, v111
	v_add_u32_e32 v160, v1, v44
	ds_write_b32 v160, v110
	v_mul_f32_e32 v112, v112, v113
	v_add_u32_e32 v161, v1, v46
	ds_write_b32 v161, v112
	v_mul_f32_e32 v114, v114, v115
	v_add_u32_e32 v162, v1, v48
	ds_write_b32 v162, v114
	v_mul_f32_e32 v116, v116, v117
	v_add_u32_e32 v163, v1, v50
	ds_write_b32 v163, v116
	v_mul_f32_e32 v118, v118, v119
	v_add_u32_e32 v164, v1, v52
	ds_write_b32 v164, v118
	v_mul_f32_e32 v120, v120, v121
	v_add_u32_e32 v165, v1, v53
	ds_write_b32 v165, v120
	v_mul_f32_e32 v122, v122, v123
	v_add_u32_e32 v166, v1, v54
	ds_write_b32 v166, v122
	v_mul_f32_e32 v124, v124, v125
	v_add_u32_e32 v167, v1, v55
	ds_write_b32 v167, v124
	v_mul_f32_e32 v126, v126, v127
	v_add_u32_e32 v168, v1, v56
	ds_write_b32 v168, v126
	v_mul_f32_e32 v128, v128, v129
	v_add_u32_e32 v169, v1, v57
	ds_write_b32 v169, v128
	v_mul_f32_e32 v130, v130, v131
	v_add_u32_e32 v170, v1, v58
	ds_write_b32 v170, v130
	v_mul_f32_e32 v132, v132, v133
	ds_write_b32 v170, v132 offset:264
	v_mul_f32_e32 v134, v134, v135
	ds_write_b32 v170, v134 offset:528
	v_mul_f32_e32 v136, v136, v137
	ds_write_b32 v170, v136 offset:792
	v_mul_f32_e32 v138, v138, v139
	ds_write_b32 v170, v138 offset:1056
	v_mul_f32_e32 v140, v140, v141
	ds_write_b32 v170, v140 offset:1320
	v_mul_f32_e32 v142, v142, v143
	ds_write_b32 v170, v142 offset:1584
	v_mul_f32_e32 v145, v144, v145
	ds_write_b32 v170, v145 offset:1848
	s_branch .Lladder_done_0
.Lladder_ng_0:
	global_load_dword v82, v[78:79], off
	v_or_b32_e32 v10, s25, v5
	v_lshlrev_b32_e32 v10, 14, v10
	v_lshl_add_u64 v[78:79], v[16:17], 0, v[10:11]
	global_load_dword v83, v[78:79], off
	v_or_b32_e32 v10, s25, v13
	v_lshlrev_b32_e32 v10, 14, v10
	v_lshl_add_u64 v[78:79], v[16:17], 0, v[10:11]
	global_load_dword v84, v[78:79], off
	v_or_b32_e32 v10, s25, v21
	v_lshlrev_b32_e32 v10, 14, v10
	v_lshl_add_u64 v[78:79], v[16:17], 0, v[10:11]
	global_load_dword v85, v[78:79], off
	v_or_b32_e32 v10, s25, v23
	v_lshlrev_b32_e32 v10, 14, v10
	v_lshl_add_u64 v[78:79], v[16:17], 0, v[10:11]
	global_load_dword v86, v[78:79], off
	v_or_b32_e32 v10, s25, v25
	v_lshlrev_b32_e32 v10, 14, v10
	v_lshl_add_u64 v[78:79], v[16:17], 0, v[10:11]
	global_load_dword v87, v[78:79], off
	v_or_b32_e32 v10, s25, v27
	v_lshlrev_b32_e32 v10, 14, v10
	v_lshl_add_u64 v[78:79], v[16:17], 0, v[10:11]
	global_load_dword v88, v[78:79], off
	v_or_b32_e32 v10, s25, v29
	v_lshlrev_b32_e32 v10, 14, v10
	v_lshl_add_u64 v[78:79], v[16:17], 0, v[10:11]
	global_load_dword v89, v[78:79], off
	v_or_b32_e32 v10, s25, v31
	v_lshlrev_b32_e32 v10, 14, v10
	v_lshl_add_u64 v[78:79], v[16:17], 0, v[10:11]
	global_load_dword v90, v[78:79], off
	v_or_b32_e32 v10, s25, v33
	v_lshlrev_b32_e32 v10, 14, v10
	v_lshl_add_u64 v[78:79], v[16:17], 0, v[10:11]
	global_load_dword v91, v[78:79], off
	v_or_b32_e32 v10, s25, v35
	v_lshlrev_b32_e32 v10, 14, v10
	v_lshl_add_u64 v[78:79], v[16:17], 0, v[10:11]
	global_load_dword v92, v[78:79], off
	v_or_b32_e32 v10, s25, v37
	v_lshlrev_b32_e32 v10, 14, v10
	v_lshl_add_u64 v[78:79], v[16:17], 0, v[10:11]
	global_load_dword v93, v[78:79], off
	v_or_b32_e32 v10, s25, v39
	v_lshlrev_b32_e32 v10, 14, v10
	v_lshl_add_u64 v[78:79], v[16:17], 0, v[10:11]
	global_load_dword v94, v[78:79], off
	v_or_b32_e32 v10, s25, v41
	v_lshlrev_b32_e32 v10, 14, v10
	v_lshl_add_u64 v[78:79], v[16:17], 0, v[10:11]
	global_load_dword v95, v[78:79], off
	v_or_b32_e32 v10, s25, v43
	v_lshlrev_b32_e32 v10, 14, v10
	v_lshl_add_u64 v[78:79], v[16:17], 0, v[10:11]
	global_load_dword v96, v[78:79], off
	v_or_b32_e32 v10, s25, v45
	v_lshlrev_b32_e32 v10, 14, v10
	v_lshl_add_u64 v[78:79], v[16:17], 0, v[10:11]
	global_load_dword v97, v[78:79], off
	v_or_b32_e32 v10, s25, v47
	v_lshlrev_b32_e32 v10, 14, v10
	v_lshl_add_u64 v[78:79], v[16:17], 0, v[10:11]
	global_load_dword v98, v[78:79], off
	v_or_b32_e32 v10, s25, v49
	v_lshlrev_b32_e32 v10, 14, v10
	v_lshl_add_u64 v[78:79], v[16:17], 0, v[10:11]
	global_load_dword v99, v[78:79], off
	v_or_b32_e32 v10, s25, v51
	v_lshlrev_b32_e32 v10, 14, v10
	v_lshl_add_u64 v[78:79], v[16:17], 0, v[10:11]
	global_load_dword v100, v[78:79], off
	v_or_b32_e32 v10, s25, v61
	v_lshlrev_b32_e32 v10, 14, v10
	v_lshl_add_u64 v[78:79], v[16:17], 0, v[10:11]
	global_load_dword v101, v[78:79], off
	v_or_b32_e32 v10, s25, v62
	v_lshlrev_b32_e32 v10, 14, v10
	v_lshl_add_u64 v[78:79], v[16:17], 0, v[10:11]
	global_load_dword v102, v[78:79], off
	v_or_b32_e32 v10, s25, v63
	v_lshlrev_b32_e32 v10, 14, v10
	v_lshl_add_u64 v[78:79], v[16:17], 0, v[10:11]
	global_load_dword v103, v[78:79], off
	v_or_b32_e32 v10, s25, v64
	v_lshlrev_b32_e32 v10, 14, v10
	v_lshl_add_u64 v[78:79], v[16:17], 0, v[10:11]
	global_load_dword v104, v[78:79], off
	v_or_b32_e32 v10, s25, v65
	v_lshlrev_b32_e32 v10, 14, v10
	v_lshl_add_u64 v[78:79], v[16:17], 0, v[10:11]
	global_load_dword v105, v[78:79], off
	v_or_b32_e32 v10, s25, v66
	v_lshlrev_b32_e32 v10, 14, v10
	v_lshl_add_u64 v[78:79], v[16:17], 0, v[10:11]
	global_load_dword v106, v[78:79], off
	v_or_b32_e32 v10, s25, v67
	v_lshlrev_b32_e32 v10, 14, v10
	v_lshl_add_u64 v[78:79], v[16:17], 0, v[10:11]
	global_load_dword v107, v[78:79], off
	v_or_b32_e32 v10, s25, v68
	v_lshlrev_b32_e32 v10, 14, v10
	v_lshl_add_u64 v[80:81], v[16:17], 0, v[10:11]
	global_load_dword v108, v[80:81], off
	v_or_b32_e32 v10, s25, v69
	v_lshlrev_b32_e32 v10, 14, v10
	v_lshl_add_u64 v[78:79], v[16:17], 0, v[10:11]
	global_load_dword v109, v[78:79], off
	v_or_b32_e32 v10, s25, v70
	v_lshlrev_b32_e32 v10, 14, v10
	v_lshl_add_u64 v[80:81], v[16:17], 0, v[10:11]
	global_load_dword v110, v[80:81], off
	v_or_b32_e32 v10, s25, v71
	v_lshlrev_b32_e32 v10, 14, v10
	v_lshl_add_u64 v[78:79], v[16:17], 0, v[10:11]
	global_load_dword v111, v[78:79], off
	v_or_b32_e32 v10, s25, v72
	v_lshlrev_b32_e32 v10, 14, v10
	v_lshl_add_u64 v[80:81], v[16:17], 0, v[10:11]
	global_load_dword v112, v[80:81], off
	v_or_b32_e32 v10, s25, v73
	v_lshlrev_b32_e32 v10, 14, v10
	v_lshl_add_u64 v[16:17], v[16:17], 0, v[10:11]
	global_load_dword v113, v[16:17], off
	s_waitcnt vmcnt(0)
	v_add_u32_e32 v114, v1, v3
	ds_write_b32 v114, v82
	v_add_lshl_u32 v115, s25, v6, 2
	v_add_u32_e32 v116, v1, v9
	ds_write_b32 v116, v83
	v_add_u32_e32 v117, v1, v20
	ds_write_b32 v117, v84
	v_add_u32_e32 v118, v1, v22
	ds_write_b32 v118, v85
	v_add_u32_e32 v119, v1, v24
	ds_write_b32 v119, v86
	v_add_u32_e32 v120, v1, v26
	ds_write_b32 v120, v87
	v_add_u32_e32 v121, v1, v28
	ds_write_b32 v121, v88
	v_add_u32_e32 v122, v1, v30
	ds_write_b32 v122, v89
	v_add_u32_e32 v123, v1, v32
	ds_write_b32 v123, v90
	v_add_u32_e32 v124, v1, v34
	ds_write_b32 v124, v91
	v_add_u32_e32 v125, v1, v36
	ds_write_b32 v125, v92
	v_add_u32_e32 v126, v1, v38
	ds_write_b32 v126, v93
	v_add_u32_e32 v127, v1, v40
	ds_write_b32 v127, v94
	v_add_u32_e32 v128, v1, v42
	ds_write_b32 v128, v95
	v_add_u32_e32 v129, v1, v44
	ds_write_b32 v129, v96
	v_add_u32_e32 v130, v1, v46
	ds_write_b32 v130, v97
	v_add_u32_e32 v131, v1, v48
	ds_write_b32 v131, v98
	v_add_u32_e32 v132, v1, v50
	ds_write_b32 v132, v99
	v_add_u32_e32 v133, v1, v52
	ds_write_b32 v133, v100
	v_add_u32_e32 v134, v1, v53
	ds_write_b32 v134, v101
	v_add_u32_e32 v135, v1, v54
	ds_write_b32 v135, v102
	v_add_u32_e32 v136, v1, v55
	ds_write_b32 v136, v103
	v_add_u32_e32 v137, v1, v56
	ds_write_b32 v137, v104
	v_add_u32_e32 v138, v1, v57
	ds_write_b32 v138, v105
	v_add_u32_e32 v139, v1, v58
	ds_write_b32 v139, v106
	ds_write_b32 v139, v107 offset:264
	ds_write_b32 v139, v108 offset:528
	ds_write_b32 v139, v109 offset:792
	ds_write_b32 v139, v110 offset:1056
	ds_write_b32 v139, v111 offset:1320
	ds_write_b32 v139, v112 offset:1584
	v_mov_b32_e32 v16, v113
	ds_write_b32 v139, v16 offset:1848
.Lladder_done_0:
.LBB0_92:
	s_waitcnt lgkmcnt(0)
	ds_read2_b32 v[78:79], v60 offset1:8
	ds_read2_b32 v[82:83], v60 offset0:33 offset1:41
	s_lshl_b32 s4, s25, 1
	s_add_u32 s4, s37, s4
	ds_read2_b32 v[84:85], v60 offset0:66 offset1:74
	s_addc_u32 s5, s36, 0
	s_waitcnt vmcnt(0)
	v_lshlrev_b32_e32 v10, 1, v12
	ds_read2_b32 v[86:87], v60 offset0:99 offset1:107
	v_lshl_add_u64 v[16:17], s[4:5], 0, v[10:11]
	s_waitcnt lgkmcnt(3)
	v_bfe_u32 v10, v78, 16, 1
	v_lshl_add_u64 v[80:81], v[16:17], 0, s[14:15]
	v_add3_u32 v10, v78, v10, s31
	s_waitcnt lgkmcnt(2)
	v_bfe_u32 v16, v82, 16, 1
	ds_read2_b32 v[88:89], v60 offset0:132 offset1:140
	v_lshrrev_b32_e32 v10, 16, v10
	v_add3_u32 v16, v82, v16, s31
	ds_read2_b32 v[90:91], v60 offset0:165 offset1:173
	v_and_or_b32 v16, v16, s33, v10
	s_waitcnt lgkmcnt(3)
	v_bfe_u32 v10, v84, 16, 1
	v_add3_u32 v10, v84, v10, s31
	s_waitcnt lgkmcnt(2)
	v_bfe_u32 v17, v86, 16, 1
	ds_read2_b32 v[92:93], v60 offset0:198 offset1:206
	v_lshrrev_b32_e32 v10, 16, v10
	v_add3_u32 v17, v86, v17, s31
	ds_read2_b32 v[94:95], v60 offset0:231 offset1:239
	v_and_or_b32 v17, v17, s33, v10
	s_waitcnt lgkmcnt(3)
	v_bfe_u32 v10, v88, 16, 1
	v_add3_u32 v10, v88, v10, s31
	s_waitcnt lgkmcnt(2)
	v_bfe_u32 v18, v90, 16, 1
	v_lshrrev_b32_e32 v10, 16, v10
	v_add3_u32 v18, v90, v18, s31
	v_and_or_b32 v18, v18, s33, v10
	s_waitcnt lgkmcnt(1)
	v_bfe_u32 v10, v92, 16, 1
	v_add3_u32 v10, v92, v10, s31
	s_waitcnt lgkmcnt(0)
	v_bfe_u32 v19, v94, 16, 1
	v_lshrrev_b32_e32 v10, 16, v10
	v_add3_u32 v19, v94, v19, s31
	v_and_or_b32 v19, v19, s33, v10
	v_or_b32_e32 v10, s8, v59
	v_lshlrev_b32_e32 v10, 11, v10
	v_lshl_add_u64 v[96:97], v[80:81], 0, v[10:11]
	v_bfe_u32 v10, v79, 16, 1
	global_store_dwordx4 v[96:97], v[16:19], off
	v_add3_u32 v10, v79, v10, s31
	v_lshrrev_b32_e32 v10, 16, v10
	v_bfe_u32 v16, v83, 16, 1
	v_add3_u32 v16, v83, v16, s31
	v_and_or_b32 v16, v16, s33, v10
	v_bfe_u32 v10, v85, 16, 1
	v_add3_u32 v10, v85, v10, s31
	v_bfe_u32 v17, v87, 16, 1
	v_lshrrev_b32_e32 v10, 16, v10
	v_add3_u32 v17, v87, v17, s31
	v_and_or_b32 v17, v17, s33, v10
	v_bfe_u32 v10, v89, 16, 1
	v_add3_u32 v10, v89, v10, s31
	v_bfe_u32 v18, v91, 16, 1
	v_lshrrev_b32_e32 v10, 16, v10
	v_add3_u32 v18, v91, v18, s31
	v_and_or_b32 v18, v18, s33, v10
	v_bfe_u32 v10, v93, 16, 1
	v_add3_u32 v10, v93, v10, s31
	v_bfe_u32 v19, v95, 16, 1
	v_lshrrev_b32_e32 v10, 16, v10
	v_add3_u32 v19, v95, v19, s31
	v_and_or_b32 v19, v19, s33, v10
	v_or_b32_e32 v10, s8, v74
	v_lshlrev_b32_e32 v10, 11, v10
	ds_read2_b32 v[78:79], v60 offset0:16 offset1:24
	v_lshl_add_u64 v[82:83], v[80:81], 0, v[10:11]
	global_store_dwordx4 v[82:83], v[16:19], off
	ds_read2_b32 v[82:83], v60 offset0:49 offset1:57
	ds_read2_b32 v[84:85], v60 offset0:82 offset1:90
	ds_read2_b32 v[86:87], v60 offset0:115 offset1:123
	s_waitcnt lgkmcnt(3)
	v_bfe_u32 v10, v78, 16, 1
	v_add3_u32 v10, v78, v10, s31
	s_waitcnt lgkmcnt(2)
	v_bfe_u32 v16, v82, 16, 1
	ds_read2_b32 v[88:89], v60 offset0:148 offset1:156
	v_lshrrev_b32_e32 v10, 16, v10
	v_add3_u32 v16, v82, v16, s31
	ds_read2_b32 v[90:91], v60 offset0:181 offset1:189
	v_and_or_b32 v16, v16, s33, v10
	s_waitcnt lgkmcnt(3)
	v_bfe_u32 v10, v84, 16, 1
	v_add3_u32 v10, v84, v10, s31
	s_waitcnt lgkmcnt(2)
	v_bfe_u32 v17, v86, 16, 1
	ds_read2_b32 v[92:93], v60 offset0:214 offset1:222
	v_lshrrev_b32_e32 v10, 16, v10
	v_add3_u32 v17, v86, v17, s31
	ds_read2_b32 v[94:95], v60 offset0:247 offset1:255
	v_and_or_b32 v17, v17, s33, v10
	s_waitcnt lgkmcnt(3)
	v_bfe_u32 v10, v88, 16, 1
	v_add3_u32 v10, v88, v10, s31
	s_waitcnt lgkmcnt(2)
	v_bfe_u32 v18, v90, 16, 1
	v_lshrrev_b32_e32 v10, 16, v10
	v_add3_u32 v18, v90, v18, s31
	v_and_or_b32 v18, v18, s33, v10
	s_waitcnt lgkmcnt(1)
	v_bfe_u32 v10, v92, 16, 1
	v_add3_u32 v10, v92, v10, s31
	s_waitcnt lgkmcnt(0)
	v_bfe_u32 v19, v94, 16, 1
	v_lshrrev_b32_e32 v10, 16, v10
	v_add3_u32 v19, v94, v19, s31
	v_and_or_b32 v19, v19, s33, v10
	v_or_b32_e32 v10, s8, v75
	v_lshlrev_b32_e32 v10, 11, v10
	v_lshl_add_u64 v[96:97], v[80:81], 0, v[10:11]
	v_bfe_u32 v10, v79, 16, 1
	global_store_dwordx4 v[96:97], v[16:19], off
	v_add3_u32 v10, v79, v10, s31
	v_lshrrev_b32_e32 v10, 16, v10
	v_bfe_u32 v16, v83, 16, 1
	v_add3_u32 v16, v83, v16, s31
	v_and_or_b32 v16, v16, s33, v10
	v_bfe_u32 v10, v85, 16, 1
	v_add3_u32 v10, v85, v10, s31
	v_bfe_u32 v17, v87, 16, 1
	v_lshrrev_b32_e32 v10, 16, v10
	v_add3_u32 v17, v87, v17, s31
	v_and_or_b32 v17, v17, s33, v10
	v_bfe_u32 v10, v89, 16, 1
	v_add3_u32 v10, v89, v10, s31
	v_bfe_u32 v18, v91, 16, 1
	v_lshrrev_b32_e32 v10, 16, v10
	v_add3_u32 v18, v91, v18, s31
	v_and_or_b32 v18, v18, s33, v10
	v_bfe_u32 v10, v93, 16, 1
	v_add3_u32 v10, v93, v10, s31
	v_bfe_u32 v19, v95, 16, 1
	v_lshrrev_b32_e32 v10, 16, v10
	v_add3_u32 v19, v95, v19, s31
	v_and_or_b32 v19, v19, s33, v10
	v_or_b32_e32 v10, s8, v76
	v_lshlrev_b32_e32 v10, 11, v10
	v_lshl_add_u64 v[78:79], v[80:81], 0, v[10:11]
	global_store_dwordx4 v[78:79], v[16:19], off
	s_waitcnt lgkmcnt(0)

.LBB0_95:
	s_andn2_b64 vcc, exec, s[4:5]
	s_cbranch_vccnz .LBB0_162
	s_add_u32 s4, s40, s28
	s_addc_u32 s5, s41, 0
	s_load_dwordx2 s[6:7], s[4:5], 0xa0
	s_load_dwordx2 s[38:39], s[4:5], 0x88
	s_and_b64 s[4:5], s[20:21], exec
	s_cselect_b32 s4, 0x400000, 0
	v_lshlrev_b32_e32 v10, 2, v8
	s_waitcnt lgkmcnt(0)
	s_add_u32 s22, s6, s4
	s_addc_u32 s23, s7, 0
	s_and_b64 s[4:5], s[20:21], exec
	s_cselect_b32 s4, 0x1000, 0
	s_add_u32 s6, s38, s4
	s_addc_u32 s7, s39, 0
	s_lshl_b32 s4, s24, 1
	s_add_i32 s4, s4, 0x1ea00
	s_and_b32 s8, s4, 0x1ffc0
	s_lshl_b32 s4, s24, 5
	s_and_b32 s25, s4, 0x3e0
	s_lshl_b32 s4, s25, 2
	s_add_u32 s4, s22, s4
	s_addc_u32 s5, s23, 0
	v_or_b32_e32 v19, s8, v6
	v_lshl_add_u64 v[16:17], s[4:5], 0, v[10:11]
	v_lshlrev_b32_e32 v10, 12, v19
	v_lshl_add_u64 v[78:79], v[16:17], 0, v[10:11]
	s_cmp_eq_u64 s[38:39], 0
	s_cbranch_scc1 .Lladder_ng_1
	global_load_dword v82, v[78:79], off
	v_lshlrev_b32_e32 v10, 2, v19
	global_load_dword v83, v10, s[6:7]
	v_or_b32_e32 v10, s8, v5
	v_lshlrev_b32_e32 v10, 12, v10
	v_lshl_add_u64 v[78:79], v[16:17], 0, v[10:11]
	global_load_dword v84, v[78:79], off
	v_add_lshl_u32 v18, s8, v6, 2
	global_load_dword v85, v18, s[6:7] offset:8
	v_or_b32_e32 v10, s8, v13
	v_lshlrev_b32_e32 v10, 12, v10
	v_lshl_add_u64 v[78:79], v[16:17], 0, v[10:11]
	global_load_dword v86, v[78:79], off
	global_load_dword v87, v18, s[6:7] offset:16
	v_or_b32_e32 v10, s8, v21
	v_lshlrev_b32_e32 v10, 12, v10
	v_lshl_add_u64 v[78:79], v[16:17], 0, v[10:11]
	global_load_dword v88, v[78:79], off
	global_load_dword v89, v18, s[6:7] offset:24
	v_or_b32_e32 v10, s8, v23
	v_lshlrev_b32_e32 v10, 12, v10
	v_lshl_add_u64 v[78:79], v[16:17], 0, v[10:11]
	global_load_dword v90, v[78:79], off
	global_load_dword v91, v18, s[6:7] offset:32
	v_or_b32_e32 v10, s8, v25
	v_lshlrev_b32_e32 v10, 12, v10
	v_lshl_add_u64 v[78:79], v[16:17], 0, v[10:11]
	global_load_dword v92, v[78:79], off
	global_load_dword v93, v18, s[6:7] offset:40
	v_or_b32_e32 v10, s8, v27
	v_lshlrev_b32_e32 v10, 12, v10
	v_lshl_add_u64 v[78:79], v[16:17], 0, v[10:11]
	global_load_dword v94, v[78:79], off
	global_load_dword v95, v18, s[6:7] offset:48
	v_or_b32_e32 v10, s8, v29
	v_lshlrev_b32_e32 v10, 12, v10
	v_lshl_add_u64 v[78:79], v[16:17], 0, v[10:11]
	global_load_dword v96, v[78:79], off
	global_load_dword v97, v18, s[6:7] offset:56
	v_or_b32_e32 v10, s8, v31
	v_lshlrev_b32_e32 v10, 12, v10
	v_lshl_add_u64 v[78:79], v[16:17], 0, v[10:11]
	global_load_dword v98, v[78:79], off
	global_load_dword v99, v18, s[6:7] offset:64
	v_or_b32_e32 v10, s8, v33
	v_lshlrev_b32_e32 v10, 12, v10
	v_lshl_add_u64 v[78:79], v[16:17], 0, v[10:11]
	global_load_dword v100, v[78:79], off
	global_load_dword v101, v18, s[6:7] offset:72
	v_or_b32_e32 v10, s8, v35
	v_lshlrev_b32_e32 v10, 12, v10
	v_lshl_add_u64 v[78:79], v[16:17], 0, v[10:11]
	global_load_dword v102, v[78:79], off
	global_load_dword v103, v18, s[6:7] offset:80
	v_or_b32_e32 v10, s8, v37
	v_lshlrev_b32_e32 v10, 12, v10
	v_lshl_add_u64 v[78:79], v[16:17], 0, v[10:11]
	global_load_dword v104, v[78:79], off
	global_load_dword v105, v18, s[6:7] offset:88
	v_or_b32_e32 v10, s8, v39
	v_lshlrev_b32_e32 v10, 12, v10
	v_lshl_add_u64 v[78:79], v[16:17], 0, v[10:11]
	global_load_dword v106, v[78:79], off
	global_load_dword v107, v18, s[6:7] offset:96
	v_or_b32_e32 v10, s8, v41
	v_lshlrev_b32_e32 v10, 12, v10
	v_lshl_add_u64 v[78:79], v[16:17], 0, v[10:11]
	global_load_dword v108, v[78:79], off
	global_load_dword v109, v18, s[6:7] offset:104
	v_or_b32_e32 v10, s8, v43
	v_lshlrev_b32_e32 v10, 12, v10
	v_lshl_add_u64 v[78:79], v[16:17], 0, v[10:11]
	global_load_dword v110, v[78:79], off
	global_load_dword v111, v18, s[6:7] offset:112
	v_or_b32_e32 v10, s8, v45
	v_lshlrev_b32_e32 v10, 12, v10
	v_lshl_add_u64 v[78:79], v[16:17], 0, v[10:11]
	global_load_dword v112, v[78:79], off
	global_load_dword v113, v18, s[6:7] offset:120
	v_or_b32_e32 v10, s8, v47
	v_lshlrev_b32_e32 v10, 12, v10
	v_lshl_add_u64 v[78:79], v[16:17], 0, v[10:11]
	global_load_dword v114, v[78:79], off
	global_load_dword v115, v18, s[6:7] offset:128
	v_or_b32_e32 v10, s8, v49
	v_lshlrev_b32_e32 v10, 12, v10
	v_lshl_add_u64 v[78:79], v[16:17], 0, v[10:11]
	global_load_dword v116, v[78:79], off
	global_load_dword v117, v18, s[6:7] offset:136
	v_or_b32_e32 v10, s8, v51
	v_lshlrev_b32_e32 v10, 12, v10
	v_lshl_add_u64 v[78:79], v[16:17], 0, v[10:11]
	global_load_dword v118, v[78:79], off
	global_load_dword v119, v18, s[6:7] offset:144
	v_or_b32_e32 v10, s8, v61
	v_lshlrev_b32_e32 v10, 12, v10
	v_lshl_add_u64 v[78:79], v[16:17], 0, v[10:11]
	global_load_dword v120, v[78:79], off
	global_load_dword v121, v18, s[6:7] offset:152
	v_or_b32_e32 v10, s8, v62
	v_lshlrev_b32_e32 v10, 12, v10
	v_lshl_add_u64 v[78:79], v[16:17], 0, v[10:11]
	global_load_dword v122, v[78:79], off
	global_load_dword v123, v18, s[6:7] offset:160
	v_or_b32_e32 v10, s8, v63
	v_lshlrev_b32_e32 v10, 12, v10
	v_lshl_add_u64 v[78:79], v[16:17], 0, v[10:11]
	global_load_dword v124, v[78:79], off
	global_load_dword v125, v18, s[6:7] offset:168
	v_or_b32_e32 v10, s8, v64
	v_lshlrev_b32_e32 v10, 12, v10
	v_lshl_add_u64 v[78:79], v[16:17], 0, v[10:11]
	global_load_dword v126, v[78:79], off
	global_load_dword v127, v18, s[6:7] offset:176
	v_or_b32_e32 v10, s8, v65
	v_lshlrev_b32_e32 v10, 12, v10
	v_lshl_add_u64 v[78:79], v[16:17], 0, v[10:11]
	global_load_dword v128, v[78:79], off
	global_load_dword v129, v18, s[6:7] offset:184
	v_or_b32_e32 v10, s8, v66
	v_lshlrev_b32_e32 v10, 12, v10
	v_lshl_add_u64 v[78:79], v[16:17], 0, v[10:11]
	global_load_dword v130, v[78:79], off
	global_load_dword v131, v18, s[6:7] offset:192
	v_or_b32_e32 v10, s8, v67
	v_lshlrev_b32_e32 v10, 12, v10
	v_lshl_add_u64 v[78:79], v[16:17], 0, v[10:11]
	global_load_dword v132, v[78:79], off
	global_load_dword v133, v18, s[6:7] offset:200
	v_or_b32_e32 v10, s8, v68
	v_lshlrev_b32_e32 v10, 12, v10
	v_lshl_add_u64 v[80:81], v[16:17], 0, v[10:11]
	global_load_dword v134, v[80:81], off
	global_load_dword v135, v18, s[6:7] offset:208
	v_or_b32_e32 v10, s8, v69
	v_lshlrev_b32_e32 v10, 12, v10
	v_lshl_add_u64 v[78:79], v[16:17], 0, v[10:11]
	global_load_dword v136, v[78:79], off
	global_load_dword v137, v18, s[6:7] offset:216
	v_or_b32_e32 v10, s8, v70
	v_lshlrev_b32_e32 v10, 12, v10
	v_lshl_add_u64 v[80:81], v[16:17], 0, v[10:11]
	global_load_dword v138, v[80:81], off
	global_load_dword v139, v18, s[6:7] offset:224
	v_or_b32_e32 v10, s8, v71
	v_lshlrev_b32_e32 v10, 12, v10
	v_lshl_add_u64 v[78:79], v[16:17], 0, v[10:11]
	global_load_dword v140, v[78:79], off
	global_load_dword v141, v18, s[6:7] offset:232
	v_or_b32_e32 v10, s8, v72
	v_lshlrev_b32_e32 v10, 12, v10
	v_lshl_add_u64 v[80:81], v[16:17], 0, v[10:11]
	global_load_dword v142, v[80:81], off
	global_load_dword v143, v18, s[6:7] offset:240
	v_or_b32_e32 v10, s8, v73
	v_lshlrev_b32_e32 v10, 12, v10
	v_lshl_add_u64 v[16:17], v[16:17], 0, v[10:11]
	global_load_dword v144, v[16:17], off
	global_load_dword v145, v18, s[6:7] offset:248
	s_waitcnt vmcnt(0)
	v_mul_f32_e32 v82, v82, v83
	v_add_u32_e32 v146, v1, v3
	ds_write_b32 v146, v82
	v_mul_f32_e32 v84, v84, v85
	v_add_u32_e32 v147, v1, v9
	ds_write_b32 v147, v84
	v_mul_f32_e32 v86, v86, v87
	v_add_u32_e32 v148, v1, v20
	ds_write_b32 v148, v86
	v_mul_f32_e32 v88, v88, v89
	v_add_u32_e32 v149, v1, v22
	ds_write_b32 v149, v88
	v_mul_f32_e32 v90, v90, v91
	v_add_u32_e32 v150, v1, v24
	ds_write_b32 v150, v90
	v_mul_f32_e32 v92, v92, v93
	v_add_u32_e32 v151, v1, v26
	ds_write_b32 v151, v92
	v_mul_f32_e32 v94, v94, v95
	v_add_u32_e32 v152, v1, v28
	ds_write_b32 v152, v94
	v_mul_f32_e32 v96, v96, v97
	v_add_u32_e32 v153, v1, v30
	ds_write_b32 v153, v96
	v_mul_f32_e32 v98, v98, v99
	v_add_u32_e32 v154, v1, v32
	ds_write_b32 v154, v98
	v_mul_f32_e32 v100, v100, v101
	v_add_u32_e32 v155, v1, v34
	ds_write_b32 v155, v100
	v_mul_f32_e32 v102, v102, v103
	v_add_u32_e32 v156, v1, v36
	ds_write_b32 v156, v102
	v_mul_f32_e32 v104, v104, v105
	v_add_u32_e32 v157, v1, v38
	ds_write_b32 v157, v104
	v_mul_f32_e32 v106, v106, v107
	v_add_u32_e32 v158, v1, v40
	ds_write_b32 v158, v106
	v_mul_f32_e32 v108, v108, v109
	v_add_u32_e32 v159, v1, v42
	ds_write_b32 v159, v108
	v_mul_f32_e32 v110, v110, v111
	v_add_u32_e32 v160, v1, v44
	ds_write_b32 v160, v110
	v_mul_f32_e32 v112, v112, v113
	v_add_u32_e32 v161, v1, v46
	ds_write_b32 v161, v112
	v_mul_f32_e32 v114, v114, v115
	v_add_u32_e32 v162, v1, v48
	ds_write_b32 v162, v114
	v_mul_f32_e32 v116, v116, v117
	v_add_u32_e32 v163, v1, v50
	ds_write_b32 v163, v116
	v_mul_f32_e32 v118, v118, v119
	v_add_u32_e32 v164, v1, v52
	ds_write_b32 v164, v118
	v_mul_f32_e32 v120, v120, v121
	v_add_u32_e32 v165, v1, v53
	ds_write_b32 v165, v120
	v_mul_f32_e32 v122, v122, v123
	v_add_u32_e32 v166, v1, v54
	ds_write_b32 v166, v122
	v_mul_f32_e32 v124, v124, v125
	v_add_u32_e32 v167, v1, v55
	ds_write_b32 v167, v124
	v_mul_f32_e32 v126, v126, v127
	v_add_u32_e32 v168, v1, v56
	ds_write_b32 v168, v126
	v_mul_f32_e32 v128, v128, v129
	v_add_u32_e32 v169, v1, v57
	ds_write_b32 v169, v128
	v_mul_f32_e32 v130, v130, v131
	v_add_u32_e32 v170, v1, v58
	ds_write_b32 v170, v130
	v_mul_f32_e32 v132, v132, v133
	ds_write_b32 v170, v132 offset:264
	v_mul_f32_e32 v134, v134, v135
	ds_write_b32 v170, v134 offset:528
	v_mul_f32_e32 v136, v136, v137
	ds_write_b32 v170, v136 offset:792
	v_mul_f32_e32 v138, v138, v139
	ds_write_b32 v170, v138 offset:1056
	v_mul_f32_e32 v140, v140, v141
	ds_write_b32 v170, v140 offset:1320
	v_mul_f32_e32 v142, v142, v143
	ds_write_b32 v170, v142 offset:1584
	v_mul_f32_e32 v145, v144, v145
	ds_write_b32 v170, v145 offset:1848
	s_branch .Lladder_done_1
.Lladder_ng_1:
	global_load_dword v82, v[78:79], off
	v_or_b32_e32 v10, s8, v5
	v_lshlrev_b32_e32 v10, 12, v10
	v_lshl_add_u64 v[78:79], v[16:17], 0, v[10:11]
	global_load_dword v83, v[78:79], off
	v_or_b32_e32 v10, s8, v13
	v_lshlrev_b32_e32 v10, 12, v10
	v_lshl_add_u64 v[78:79], v[16:17], 0, v[10:11]
	global_load_dword v84, v[78:79], off
	v_or_b32_e32 v10, s8, v21
	v_lshlrev_b32_e32 v10, 12, v10
	v_lshl_add_u64 v[78:79], v[16:17], 0, v[10:11]
	global_load_dword v85, v[78:79], off
	v_or_b32_e32 v10, s8, v23
	v_lshlrev_b32_e32 v10, 12, v10
	v_lshl_add_u64 v[78:79], v[16:17], 0, v[10:11]
	global_load_dword v86, v[78:79], off
	v_or_b32_e32 v10, s8, v25
	v_lshlrev_b32_e32 v10, 12, v10
	v_lshl_add_u64 v[78:79], v[16:17], 0, v[10:11]
	global_load_dword v87, v[78:79], off
	v_or_b32_e32 v10, s8, v27
	v_lshlrev_b32_e32 v10, 12, v10
	v_lshl_add_u64 v[78:79], v[16:17], 0, v[10:11]
	global_load_dword v88, v[78:79], off
	v_or_b32_e32 v10, s8, v29
	v_lshlrev_b32_e32 v10, 12, v10
	v_lshl_add_u64 v[78:79], v[16:17], 0, v[10:11]
	global_load_dword v89, v[78:79], off
	v_or_b32_e32 v10, s8, v31
	v_lshlrev_b32_e32 v10, 12, v10
	v_lshl_add_u64 v[78:79], v[16:17], 0, v[10:11]
	global_load_dword v90, v[78:79], off
	v_or_b32_e32 v10, s8, v33
	v_lshlrev_b32_e32 v10, 12, v10
	v_lshl_add_u64 v[78:79], v[16:17], 0, v[10:11]
	global_load_dword v91, v[78:79], off
	v_or_b32_e32 v10, s8, v35
	v_lshlrev_b32_e32 v10, 12, v10
	v_lshl_add_u64 v[78:79], v[16:17], 0, v[10:11]
	global_load_dword v92, v[78:79], off
	v_or_b32_e32 v10, s8, v37
	v_lshlrev_b32_e32 v10, 12, v10
	v_lshl_add_u64 v[78:79], v[16:17], 0, v[10:11]
	global_load_dword v93, v[78:79], off
	v_or_b32_e32 v10, s8, v39
	v_lshlrev_b32_e32 v10, 12, v10
	v_lshl_add_u64 v[78:79], v[16:17], 0, v[10:11]
	global_load_dword v94, v[78:79], off
	v_or_b32_e32 v10, s8, v41
	v_lshlrev_b32_e32 v10, 12, v10
	v_lshl_add_u64 v[78:79], v[16:17], 0, v[10:11]
	global_load_dword v95, v[78:79], off
	v_or_b32_e32 v10, s8, v43
	v_lshlrev_b32_e32 v10, 12, v10
	v_lshl_add_u64 v[78:79], v[16:17], 0, v[10:11]
	global_load_dword v96, v[78:79], off
	v_or_b32_e32 v10, s8, v45
	v_lshlrev_b32_e32 v10, 12, v10
	v_lshl_add_u64 v[78:79], v[16:17], 0, v[10:11]
	global_load_dword v97, v[78:79], off
	v_or_b32_e32 v10, s8, v47
	v_lshlrev_b32_e32 v10, 12, v10
	v_lshl_add_u64 v[78:79], v[16:17], 0, v[10:11]
	global_load_dword v98, v[78:79], off
	v_or_b32_e32 v10, s8, v49
	v_lshlrev_b32_e32 v10, 12, v10
	v_lshl_add_u64 v[78:79], v[16:17], 0, v[10:11]
	global_load_dword v99, v[78:79], off
	v_or_b32_e32 v10, s8, v51
	v_lshlrev_b32_e32 v10, 12, v10
	v_lshl_add_u64 v[78:79], v[16:17], 0, v[10:11]
	global_load_dword v100, v[78:79], off
	v_or_b32_e32 v10, s8, v61
	v_lshlrev_b32_e32 v10, 12, v10
	v_lshl_add_u64 v[78:79], v[16:17], 0, v[10:11]
	global_load_dword v101, v[78:79], off
	v_or_b32_e32 v10, s8, v62
	v_lshlrev_b32_e32 v10, 12, v10
	v_lshl_add_u64 v[78:79], v[16:17], 0, v[10:11]
	global_load_dword v102, v[78:79], off
	v_or_b32_e32 v10, s8, v63
	v_lshlrev_b32_e32 v10, 12, v10
	v_lshl_add_u64 v[78:79], v[16:17], 0, v[10:11]
	global_load_dword v103, v[78:79], off
	v_or_b32_e32 v10, s8, v64
	v_lshlrev_b32_e32 v10, 12, v10
	v_lshl_add_u64 v[78:79], v[16:17], 0, v[10:11]
	global_load_dword v104, v[78:79], off
	v_or_b32_e32 v10, s8, v65
	v_lshlrev_b32_e32 v10, 12, v10
	v_lshl_add_u64 v[78:79], v[16:17], 0, v[10:11]
	global_load_dword v105, v[78:79], off
	v_or_b32_e32 v10, s8, v66
	v_lshlrev_b32_e32 v10, 12, v10
	v_lshl_add_u64 v[78:79], v[16:17], 0, v[10:11]
	global_load_dword v106, v[78:79], off
	v_or_b32_e32 v10, s8, v67
	v_lshlrev_b32_e32 v10, 12, v10
	v_lshl_add_u64 v[78:79], v[16:17], 0, v[10:11]
	global_load_dword v107, v[78:79], off
	v_or_b32_e32 v10, s8, v68
	v_lshlrev_b32_e32 v10, 12, v10
	v_lshl_add_u64 v[80:81], v[16:17], 0, v[10:11]
	global_load_dword v108, v[80:81], off
	v_or_b32_e32 v10, s8, v69
	v_lshlrev_b32_e32 v10, 12, v10
	v_lshl_add_u64 v[78:79], v[16:17], 0, v[10:11]
	global_load_dword v109, v[78:79], off
	v_or_b32_e32 v10, s8, v70
	v_lshlrev_b32_e32 v10, 12, v10
	v_lshl_add_u64 v[80:81], v[16:17], 0, v[10:11]
	global_load_dword v110, v[80:81], off
	v_or_b32_e32 v10, s8, v71
	v_lshlrev_b32_e32 v10, 12, v10
	v_lshl_add_u64 v[78:79], v[16:17], 0, v[10:11]
	global_load_dword v111, v[78:79], off
	v_or_b32_e32 v10, s8, v72
	v_lshlrev_b32_e32 v10, 12, v10
	v_lshl_add_u64 v[80:81], v[16:17], 0, v[10:11]
	global_load_dword v112, v[80:81], off
	v_or_b32_e32 v10, s8, v73
	v_lshlrev_b32_e32 v10, 12, v10
	v_lshl_add_u64 v[16:17], v[16:17], 0, v[10:11]
	global_load_dword v113, v[16:17], off
	s_waitcnt vmcnt(0)
	v_add_u32_e32 v114, v1, v3
	ds_write_b32 v114, v82
	v_add_lshl_u32 v115, s8, v6, 2
	v_add_u32_e32 v116, v1, v9
	ds_write_b32 v116, v83
	v_add_u32_e32 v117, v1, v20
	ds_write_b32 v117, v84
	v_add_u32_e32 v118, v1, v22
	ds_write_b32 v118, v85
	v_add_u32_e32 v119, v1, v24
	ds_write_b32 v119, v86
	v_add_u32_e32 v120, v1, v26
	ds_write_b32 v120, v87
	v_add_u32_e32 v121, v1, v28
	ds_write_b32 v121, v88
	v_add_u32_e32 v122, v1, v30
	ds_write_b32 v122, v89
	v_add_u32_e32 v123, v1, v32
	ds_write_b32 v123, v90
	v_add_u32_e32 v124, v1, v34
	ds_write_b32 v124, v91
	v_add_u32_e32 v125, v1, v36
	ds_write_b32 v125, v92
	v_add_u32_e32 v126, v1, v38
	ds_write_b32 v126, v93
	v_add_u32_e32 v127, v1, v40
	ds_write_b32 v127, v94
	v_add_u32_e32 v128, v1, v42
	ds_write_b32 v128, v95
	v_add_u32_e32 v129, v1, v44
	ds_write_b32 v129, v96
	v_add_u32_e32 v130, v1, v46
	ds_write_b32 v130, v97
	v_add_u32_e32 v131, v1, v48
	ds_write_b32 v131, v98
	v_add_u32_e32 v132, v1, v50
	ds_write_b32 v132, v99
	v_add_u32_e32 v133, v1, v52
	ds_write_b32 v133, v100
	v_add_u32_e32 v134, v1, v53
	ds_write_b32 v134, v101
	v_add_u32_e32 v135, v1, v54
	ds_write_b32 v135, v102
	v_add_u32_e32 v136, v1, v55
	ds_write_b32 v136, v103
	v_add_u32_e32 v137, v1, v56
	ds_write_b32 v137, v104
	v_add_u32_e32 v138, v1, v57
	ds_write_b32 v138, v105
	v_add_u32_e32 v139, v1, v58
	ds_write_b32 v139, v106
	ds_write_b32 v139, v107 offset:264
	ds_write_b32 v139, v108 offset:528
	ds_write_b32 v139, v109 offset:792
	ds_write_b32 v139, v110 offset:1056
	ds_write_b32 v139, v111 offset:1320
	ds_write_b32 v139, v112 offset:1584
	v_mov_b32_e32 v16, v113
	ds_write_b32 v139, v16 offset:1848
.Lladder_done_1:
.LBB0_160:
	s_waitcnt lgkmcnt(0)
	ds_read2_b32 v[78:79], v60 offset1:8
	ds_read2_b32 v[82:83], v60 offset0:33 offset1:41
	ds_read2_b32 v[84:85], v60 offset0:66 offset1:74
	ds_read2_b32 v[86:87], v60 offset0:99 offset1:107
	ds_read2_b32 v[88:89], v60 offset0:132 offset1:140
	s_waitcnt vmcnt(0) lgkmcnt(4)
	v_bfe_u32 v10, v78, 16, 1
	v_add3_u32 v10, v78, v10, s31
	s_waitcnt lgkmcnt(3)
	v_bfe_u32 v16, v82, 16, 1
	v_lshrrev_b32_e32 v10, 16, v10
	v_add3_u32 v16, v82, v16, s31
	ds_read2_b32 v[90:91], v60 offset0:165 offset1:173
	v_and_or_b32 v16, v16, s33, v10
	s_waitcnt lgkmcnt(3)
	v_bfe_u32 v10, v84, 16, 1
	v_add3_u32 v10, v84, v10, s31
	s_waitcnt lgkmcnt(2)
	v_bfe_u32 v17, v86, 16, 1
	ds_read2_b32 v[92:93], v60 offset0:198 offset1:206
	v_lshrrev_b32_e32 v10, 16, v10
	v_add3_u32 v17, v86, v17, s31
	ds_read2_b32 v[94:95], v60 offset0:231 offset1:239
	v_and_or_b32 v17, v17, s33, v10
	s_waitcnt lgkmcnt(3)
	v_bfe_u32 v10, v88, 16, 1
	v_add3_u32 v10, v88, v10, s31
	s_waitcnt lgkmcnt(2)
	v_bfe_u32 v18, v90, 16, 1
	v_lshrrev_b32_e32 v10, 16, v10
	v_add3_u32 v18, v90, v18, s31
	s_and_b64 s[4:5], s[20:21], exec
	v_and_or_b32 v18, v18, s33, v10
	s_waitcnt lgkmcnt(1)
	v_bfe_u32 v10, v92, 16, 1
	s_cselect_b32 s4, s34, 0x400
	v_add3_u32 v10, v92, v10, s31
	s_waitcnt lgkmcnt(0)
	v_bfe_u32 v19, v94, 16, 1
	s_or_b32 s4, s25, s4
	v_lshrrev_b32_e32 v10, 16, v10
	v_add3_u32 v19, v94, v19, s31
	s_lshl_b32 s8, s8, 1
	v_and_or_b32 v19, v19, s33, v10
	v_or_b32_e32 v10, s4, v59
	v_lshl_add_u64 v[80:81], v[14:15], 0, s[8:9]
	v_lshlrev_b32_e32 v10, 11, v10
	v_lshl_add_u64 v[96:97], v[80:81], 0, v[10:11]
	v_bfe_u32 v10, v79, 16, 1
	global_store_dwordx4 v[96:97], v[16:19], off
	v_add3_u32 v10, v79, v10, s31
	v_lshrrev_b32_e32 v10, 16, v10
	v_bfe_u32 v16, v83, 16, 1
	v_add3_u32 v16, v83, v16, s31
	v_and_or_b32 v16, v16, s33, v10
	v_bfe_u32 v10, v85, 16, 1
	v_add3_u32 v10, v85, v10, s31
	v_bfe_u32 v17, v87, 16, 1
	v_lshrrev_b32_e32 v10, 16, v10
	v_add3_u32 v17, v87, v17, s31
	v_and_or_b32 v17, v17, s33, v10
	v_bfe_u32 v10, v89, 16, 1
	v_add3_u32 v10, v89, v10, s31
	v_bfe_u32 v18, v91, 16, 1
	v_lshrrev_b32_e32 v10, 16, v10
	v_add3_u32 v18, v91, v18, s31
	v_and_or_b32 v18, v18, s33, v10
	v_bfe_u32 v10, v93, 16, 1
	v_add3_u32 v10, v93, v10, s31
	v_bfe_u32 v19, v95, 16, 1
	v_lshrrev_b32_e32 v10, 16, v10
	v_add3_u32 v19, v95, v19, s31
	v_and_or_b32 v19, v19, s33, v10
	v_or_b32_e32 v10, s4, v74
	v_lshlrev_b32_e32 v10, 11, v10
	ds_read2_b32 v[78:79], v60 offset0:16 offset1:24
	v_lshl_add_u64 v[82:83], v[80:81], 0, v[10:11]
	global_store_dwordx4 v[82:83], v[16:19], off
	ds_read2_b32 v[82:83], v60 offset0:49 offset1:57
	ds_read2_b32 v[84:85], v60 offset0:82 offset1:90
	ds_read2_b32 v[86:87], v60 offset0:115 offset1:123
	s_waitcnt lgkmcnt(3)
	v_bfe_u32 v10, v78, 16, 1
	v_add3_u32 v10, v78, v10, s31
	s_waitcnt lgkmcnt(2)
	v_bfe_u32 v16, v82, 16, 1
	ds_read2_b32 v[88:89], v60 offset0:148 offset1:156
	v_lshrrev_b32_e32 v10, 16, v10
	v_add3_u32 v16, v82, v16, s31
	ds_read2_b32 v[90:91], v60 offset0:181 offset1:189
	v_and_or_b32 v16, v16, s33, v10
	s_waitcnt lgkmcnt(3)
	v_bfe_u32 v10, v84, 16, 1
	v_add3_u32 v10, v84, v10, s31
	s_waitcnt lgkmcnt(2)
	v_bfe_u32 v17, v86, 16, 1
	ds_read2_b32 v[92:93], v60 offset0:214 offset1:222
	v_lshrrev_b32_e32 v10, 16, v10
	v_add3_u32 v17, v86, v17, s31
	ds_read2_b32 v[94:95], v60 offset0:247 offset1:255
	v_and_or_b32 v17, v17, s33, v10
	s_waitcnt lgkmcnt(3)
	v_bfe_u32 v10, v88, 16, 1
	v_add3_u32 v10, v88, v10, s31
	s_waitcnt lgkmcnt(2)
	v_bfe_u32 v18, v90, 16, 1
	v_lshrrev_b32_e32 v10, 16, v10
	v_add3_u32 v18, v90, v18, s31
	v_and_or_b32 v18, v18, s33, v10
	s_waitcnt lgkmcnt(1)
	v_bfe_u32 v10, v92, 16, 1
	v_add3_u32 v10, v92, v10, s31
	s_waitcnt lgkmcnt(0)
	v_bfe_u32 v19, v94, 16, 1
	v_lshrrev_b32_e32 v10, 16, v10
	v_add3_u32 v19, v94, v19, s31
	v_and_or_b32 v19, v19, s33, v10
	v_or_b32_e32 v10, s4, v75
	v_lshlrev_b32_e32 v10, 11, v10
	v_lshl_add_u64 v[96:97], v[80:81], 0, v[10:11]
	v_bfe_u32 v10, v79, 16, 1
	global_store_dwordx4 v[96:97], v[16:19], off
	v_add3_u32 v10, v79, v10, s31
	v_lshrrev_b32_e32 v10, 16, v10
	v_bfe_u32 v16, v83, 16, 1
	v_add3_u32 v16, v83, v16, s31
	v_and_or_b32 v16, v16, s33, v10
	v_bfe_u32 v10, v85, 16, 1
	v_add3_u32 v10, v85, v10, s31
	v_bfe_u32 v17, v87, 16, 1
	v_lshrrev_b32_e32 v10, 16, v10
	v_add3_u32 v17, v87, v17, s31
	v_and_or_b32 v17, v17, s33, v10
	v_bfe_u32 v10, v89, 16, 1
	v_add3_u32 v10, v89, v10, s31
	v_bfe_u32 v18, v91, 16, 1
	v_lshrrev_b32_e32 v10, 16, v10
	v_add3_u32 v18, v91, v18, s31
	v_and_or_b32 v18, v18, s33, v10
	v_bfe_u32 v10, v93, 16, 1
	v_add3_u32 v10, v93, v10, s31
	v_bfe_u32 v19, v95, 16, 1
	v_lshrrev_b32_e32 v10, 16, v10
	v_add3_u32 v19, v95, v19, s31
	v_and_or_b32 v19, v19, s33, v10
	v_or_b32_e32 v10, s4, v76
	v_lshlrev_b32_e32 v10, 11, v10
	v_lshl_add_u64 v[78:79], v[80:81], 0, v[10:11]
	global_store_dwordx4 v[78:79], v[16:19], off
	s_waitcnt lgkmcnt(0)

.LBB0_163:
	s_andn2_b64 vcc, exec, s[4:5]
	s_cbranch_vccnz .LBB0_230
	s_add_u32 s4, s40, s28
	s_addc_u32 s5, s41, 0
	s_load_dwordx2 s[6:7], s[4:5], 0x98
	s_load_dwordx2 s[38:39], s[4:5], 0x88
	s_and_b64 s[4:5], s[20:21], exec
	s_cselect_b32 s4, 0x400000, 0
	v_lshlrev_b32_e32 v10, 2, v8
	s_waitcnt lgkmcnt(0)
	s_add_u32 s22, s6, s4
	s_addc_u32 s23, s7, 0
	s_and_b64 s[4:5], s[20:21], exec
	s_cselect_b32 s4, 0x1000, 0
	s_add_u32 s6, s38, s4
	s_addc_u32 s7, s39, 0
	s_lshl_b32 s4, s24, 1
	s_add_i32 s4, s4, 0x1ee00
	s_and_b32 s8, s4, 0x1ffc0
	s_lshl_b32 s4, s24, 5
	s_and_b32 s25, s4, 0x3e0
	s_lshl_b32 s4, s25, 2
	s_add_u32 s4, s22, s4
	s_addc_u32 s5, s23, 0
	v_or_b32_e32 v19, s8, v6
	v_lshl_add_u64 v[16:17], s[4:5], 0, v[10:11]
	v_lshlrev_b32_e32 v10, 12, v19
	v_lshl_add_u64 v[78:79], v[16:17], 0, v[10:11]
	s_cmp_eq_u64 s[38:39], 0
	s_cbranch_scc1 .Lladder_ng_2
	global_load_dword v82, v[78:79], off
	v_lshlrev_b32_e32 v10, 2, v19
	global_load_dword v83, v10, s[6:7]
	v_or_b32_e32 v10, s8, v5
	v_lshlrev_b32_e32 v10, 12, v10
	v_lshl_add_u64 v[78:79], v[16:17], 0, v[10:11]
	global_load_dword v84, v[78:79], off
	v_add_lshl_u32 v18, s8, v6, 2
	global_load_dword v85, v18, s[6:7] offset:8
	v_or_b32_e32 v10, s8, v13
	v_lshlrev_b32_e32 v10, 12, v10
	v_lshl_add_u64 v[78:79], v[16:17], 0, v[10:11]
	global_load_dword v86, v[78:79], off
	global_load_dword v87, v18, s[6:7] offset:16
	v_or_b32_e32 v10, s8, v21
	v_lshlrev_b32_e32 v10, 12, v10
	v_lshl_add_u64 v[78:79], v[16:17], 0, v[10:11]
	global_load_dword v88, v[78:79], off
	global_load_dword v89, v18, s[6:7] offset:24
	v_or_b32_e32 v10, s8, v23
	v_lshlrev_b32_e32 v10, 12, v10
	v_lshl_add_u64 v[78:79], v[16:17], 0, v[10:11]
	global_load_dword v90, v[78:79], off
	global_load_dword v91, v18, s[6:7] offset:32
	v_or_b32_e32 v10, s8, v25
	v_lshlrev_b32_e32 v10, 12, v10
	v_lshl_add_u64 v[78:79], v[16:17], 0, v[10:11]
	global_load_dword v92, v[78:79], off
	global_load_dword v93, v18, s[6:7] offset:40
	v_or_b32_e32 v10, s8, v27
	v_lshlrev_b32_e32 v10, 12, v10
	v_lshl_add_u64 v[78:79], v[16:17], 0, v[10:11]
	global_load_dword v94, v[78:79], off
	global_load_dword v95, v18, s[6:7] offset:48
	v_or_b32_e32 v10, s8, v29
	v_lshlrev_b32_e32 v10, 12, v10
	v_lshl_add_u64 v[78:79], v[16:17], 0, v[10:11]
	global_load_dword v96, v[78:79], off
	global_load_dword v97, v18, s[6:7] offset:56
	v_or_b32_e32 v10, s8, v31
	v_lshlrev_b32_e32 v10, 12, v10
	v_lshl_add_u64 v[78:79], v[16:17], 0, v[10:11]
	global_load_dword v98, v[78:79], off
	global_load_dword v99, v18, s[6:7] offset:64
	v_or_b32_e32 v10, s8, v33
	v_lshlrev_b32_e32 v10, 12, v10
	v_lshl_add_u64 v[78:79], v[16:17], 0, v[10:11]
	global_load_dword v100, v[78:79], off
	global_load_dword v101, v18, s[6:7] offset:72
	v_or_b32_e32 v10, s8, v35
	v_lshlrev_b32_e32 v10, 12, v10
	v_lshl_add_u64 v[78:79], v[16:17], 0, v[10:11]
	global_load_dword v102, v[78:79], off
	global_load_dword v103, v18, s[6:7] offset:80
	v_or_b32_e32 v10, s8, v37
	v_lshlrev_b32_e32 v10, 12, v10
	v_lshl_add_u64 v[78:79], v[16:17], 0, v[10:11]
	global_load_dword v104, v[78:79], off
	global_load_dword v105, v18, s[6:7] offset:88
	v_or_b32_e32 v10, s8, v39
	v_lshlrev_b32_e32 v10, 12, v10
	v_lshl_add_u64 v[78:79], v[16:17], 0, v[10:11]
	global_load_dword v106, v[78:79], off
	global_load_dword v107, v18, s[6:7] offset:96
	v_or_b32_e32 v10, s8, v41
	v_lshlrev_b32_e32 v10, 12, v10
	v_lshl_add_u64 v[78:79], v[16:17], 0, v[10:11]
	global_load_dword v108, v[78:79], off
	global_load_dword v109, v18, s[6:7] offset:104
	v_or_b32_e32 v10, s8, v43
	v_lshlrev_b32_e32 v10, 12, v10
	v_lshl_add_u64 v[78:79], v[16:17], 0, v[10:11]
	global_load_dword v110, v[78:79], off
	global_load_dword v111, v18, s[6:7] offset:112
	v_or_b32_e32 v10, s8, v45
	v_lshlrev_b32_e32 v10, 12, v10
	v_lshl_add_u64 v[78:79], v[16:17], 0, v[10:11]
	global_load_dword v112, v[78:79], off
	global_load_dword v113, v18, s[6:7] offset:120
	v_or_b32_e32 v10, s8, v47
	v_lshlrev_b32_e32 v10, 12, v10
	v_lshl_add_u64 v[78:79], v[16:17], 0, v[10:11]
	global_load_dword v114, v[78:79], off
	global_load_dword v115, v18, s[6:7] offset:128
	v_or_b32_e32 v10, s8, v49
	v_lshlrev_b32_e32 v10, 12, v10
	v_lshl_add_u64 v[78:79], v[16:17], 0, v[10:11]
	global_load_dword v116, v[78:79], off
	global_load_dword v117, v18, s[6:7] offset:136
	v_or_b32_e32 v10, s8, v51
	v_lshlrev_b32_e32 v10, 12, v10
	v_lshl_add_u64 v[78:79], v[16:17], 0, v[10:11]
	global_load_dword v118, v[78:79], off
	global_load_dword v119, v18, s[6:7] offset:144
	v_or_b32_e32 v10, s8, v61
	v_lshlrev_b32_e32 v10, 12, v10
	v_lshl_add_u64 v[78:79], v[16:17], 0, v[10:11]
	global_load_dword v120, v[78:79], off
	global_load_dword v121, v18, s[6:7] offset:152
	v_or_b32_e32 v10, s8, v62
	v_lshlrev_b32_e32 v10, 12, v10
	v_lshl_add_u64 v[78:79], v[16:17], 0, v[10:11]
	global_load_dword v122, v[78:79], off
	global_load_dword v123, v18, s[6:7] offset:160
	v_or_b32_e32 v10, s8, v63
	v_lshlrev_b32_e32 v10, 12, v10
	v_lshl_add_u64 v[78:79], v[16:17], 0, v[10:11]
	global_load_dword v124, v[78:79], off
	global_load_dword v125, v18, s[6:7] offset:168
	v_or_b32_e32 v10, s8, v64
	v_lshlrev_b32_e32 v10, 12, v10
	v_lshl_add_u64 v[78:79], v[16:17], 0, v[10:11]
	global_load_dword v126, v[78:79], off
	global_load_dword v127, v18, s[6:7] offset:176
	v_or_b32_e32 v10, s8, v65
	v_lshlrev_b32_e32 v10, 12, v10
	v_lshl_add_u64 v[78:79], v[16:17], 0, v[10:11]
	global_load_dword v128, v[78:79], off
	global_load_dword v129, v18, s[6:7] offset:184
	v_or_b32_e32 v10, s8, v66
	v_lshlrev_b32_e32 v10, 12, v10
	v_lshl_add_u64 v[78:79], v[16:17], 0, v[10:11]
	global_load_dword v130, v[78:79], off
	global_load_dword v131, v18, s[6:7] offset:192
	v_or_b32_e32 v10, s8, v67
	v_lshlrev_b32_e32 v10, 12, v10
	v_lshl_add_u64 v[78:79], v[16:17], 0, v[10:11]
	global_load_dword v132, v[78:79], off
	global_load_dword v133, v18, s[6:7] offset:200
	v_or_b32_e32 v10, s8, v68
	v_lshlrev_b32_e32 v10, 12, v10
	v_lshl_add_u64 v[80:81], v[16:17], 0, v[10:11]
	global_load_dword v134, v[80:81], off
	global_load_dword v135, v18, s[6:7] offset:208
	v_or_b32_e32 v10, s8, v69
	v_lshlrev_b32_e32 v10, 12, v10
	v_lshl_add_u64 v[78:79], v[16:17], 0, v[10:11]
	global_load_dword v136, v[78:79], off
	global_load_dword v137, v18, s[6:7] offset:216
	v_or_b32_e32 v10, s8, v70
	v_lshlrev_b32_e32 v10, 12, v10
	v_lshl_add_u64 v[80:81], v[16:17], 0, v[10:11]
	global_load_dword v138, v[80:81], off
	global_load_dword v139, v18, s[6:7] offset:224
	v_or_b32_e32 v10, s8, v71
	v_lshlrev_b32_e32 v10, 12, v10
	v_lshl_add_u64 v[78:79], v[16:17], 0, v[10:11]
	global_load_dword v140, v[78:79], off
	global_load_dword v141, v18, s[6:7] offset:232
	v_or_b32_e32 v10, s8, v72
	v_lshlrev_b32_e32 v10, 12, v10
	v_lshl_add_u64 v[80:81], v[16:17], 0, v[10:11]
	global_load_dword v142, v[80:81], off
	global_load_dword v143, v18, s[6:7] offset:240
	v_or_b32_e32 v10, s8, v73
	v_lshlrev_b32_e32 v10, 12, v10
	v_lshl_add_u64 v[16:17], v[16:17], 0, v[10:11]
	global_load_dword v144, v[16:17], off
	global_load_dword v145, v18, s[6:7] offset:248
	s_waitcnt vmcnt(0)
	v_mul_f32_e32 v82, v82, v83
	v_add_u32_e32 v146, v1, v3
	ds_write_b32 v146, v82
	v_mul_f32_e32 v84, v84, v85
	v_add_u32_e32 v147, v1, v9
	ds_write_b32 v147, v84
	v_mul_f32_e32 v86, v86, v87
	v_add_u32_e32 v148, v1, v20
	ds_write_b32 v148, v86
	v_mul_f32_e32 v88, v88, v89
	v_add_u32_e32 v149, v1, v22
	ds_write_b32 v149, v88
	v_mul_f32_e32 v90, v90, v91
	v_add_u32_e32 v150, v1, v24
	ds_write_b32 v150, v90
	v_mul_f32_e32 v92, v92, v93
	v_add_u32_e32 v151, v1, v26
	ds_write_b32 v151, v92
	v_mul_f32_e32 v94, v94, v95
	v_add_u32_e32 v152, v1, v28
	ds_write_b32 v152, v94
	v_mul_f32_e32 v96, v96, v97
	v_add_u32_e32 v153, v1, v30
	ds_write_b32 v153, v96
	v_mul_f32_e32 v98, v98, v99
	v_add_u32_e32 v154, v1, v32
	ds_write_b32 v154, v98
	v_mul_f32_e32 v100, v100, v101
	v_add_u32_e32 v155, v1, v34
	ds_write_b32 v155, v100
	v_mul_f32_e32 v102, v102, v103
	v_add_u32_e32 v156, v1, v36
	ds_write_b32 v156, v102
	v_mul_f32_e32 v104, v104, v105
	v_add_u32_e32 v157, v1, v38
	ds_write_b32 v157, v104
	v_mul_f32_e32 v106, v106, v107
	v_add_u32_e32 v158, v1, v40
	ds_write_b32 v158, v106
	v_mul_f32_e32 v108, v108, v109
	v_add_u32_e32 v159, v1, v42
	ds_write_b32 v159, v108
	v_mul_f32_e32 v110, v110, v111
	v_add_u32_e32 v160, v1, v44
	ds_write_b32 v160, v110
	v_mul_f32_e32 v112, v112, v113
	v_add_u32_e32 v161, v1, v46
	ds_write_b32 v161, v112
	v_mul_f32_e32 v114, v114, v115
	v_add_u32_e32 v162, v1, v48
	ds_write_b32 v162, v114
	v_mul_f32_e32 v116, v116, v117
	v_add_u32_e32 v163, v1, v50
	ds_write_b32 v163, v116
	v_mul_f32_e32 v118, v118, v119
	v_add_u32_e32 v164, v1, v52
	ds_write_b32 v164, v118
	v_mul_f32_e32 v120, v120, v121
	v_add_u32_e32 v165, v1, v53
	ds_write_b32 v165, v120
	v_mul_f32_e32 v122, v122, v123
	v_add_u32_e32 v166, v1, v54
	ds_write_b32 v166, v122
	v_mul_f32_e32 v124, v124, v125
	v_add_u32_e32 v167, v1, v55
	ds_write_b32 v167, v124
	v_mul_f32_e32 v126, v126, v127
	v_add_u32_e32 v168, v1, v56
	ds_write_b32 v168, v126
	v_mul_f32_e32 v128, v128, v129
	v_add_u32_e32 v169, v1, v57
	ds_write_b32 v169, v128
	v_mul_f32_e32 v130, v130, v131
	v_add_u32_e32 v170, v1, v58
	ds_write_b32 v170, v130
	v_mul_f32_e32 v132, v132, v133
	ds_write_b32 v170, v132 offset:264
	v_mul_f32_e32 v134, v134, v135
	ds_write_b32 v170, v134 offset:528
	v_mul_f32_e32 v136, v136, v137
	ds_write_b32 v170, v136 offset:792
	v_mul_f32_e32 v138, v138, v139
	ds_write_b32 v170, v138 offset:1056
	v_mul_f32_e32 v140, v140, v141
	ds_write_b32 v170, v140 offset:1320
	v_mul_f32_e32 v142, v142, v143
	ds_write_b32 v170, v142 offset:1584
	v_mul_f32_e32 v145, v144, v145
	ds_write_b32 v170, v145 offset:1848
	s_branch .Lladder_done_2

.Lladder_done_2:
.LBB0_228:
	s_waitcnt lgkmcnt(0)
	ds_read2_b32 v[78:79], v60 offset1:8
	ds_read2_b32 v[82:83], v60 offset0:33 offset1:41
	ds_read2_b32 v[84:85], v60 offset0:66 offset1:74
	ds_read2_b32 v[86:87], v60 offset0:99 offset1:107
	ds_read2_b32 v[88:89], v60 offset0:132 offset1:140
	s_waitcnt vmcnt(0) lgkmcnt(4)
	v_bfe_u32 v10, v78, 16, 1
	v_add3_u32 v10, v78, v10, s31
	s_waitcnt lgkmcnt(3)
	v_bfe_u32 v16, v82, 16, 1
	v_lshrrev_b32_e32 v10, 16, v10
	v_add3_u32 v16, v82, v16, s31
	ds_read2_b32 v[90:91], v60 offset0:165 offset1:173
	v_and_or_b32 v16, v16, s33, v10
	s_waitcnt lgkmcnt(3)
	v_bfe_u32 v10, v84, 16, 1
	v_add3_u32 v10, v84, v10, s31
	s_waitcnt lgkmcnt(2)
	v_bfe_u32 v17, v86, 16, 1
	ds_read2_b32 v[92:93], v60 offset0:198 offset1:206
	v_lshrrev_b32_e32 v10, 16, v10
	v_add3_u32 v17, v86, v17, s31
	ds_read2_b32 v[94:95], v60 offset0:231 offset1:239
	v_and_or_b32 v17, v17, s33, v10
	s_waitcnt lgkmcnt(3)
	v_bfe_u32 v10, v88, 16, 1
	v_add3_u32 v10, v88, v10, s31
	s_waitcnt lgkmcnt(2)
	v_bfe_u32 v18, v90, 16, 1
	v_lshrrev_b32_e32 v10, 16, v10
	v_add3_u32 v18, v90, v18, s31
	s_and_b64 s[4:5], s[20:21], exec
	v_and_or_b32 v18, v18, s33, v10
	s_waitcnt lgkmcnt(1)
	v_bfe_u32 v10, v92, 16, 1
	s_cselect_b32 s4, 0x800, 0
	v_add3_u32 v10, v92, v10, s31
	s_waitcnt lgkmcnt(0)
	v_bfe_u32 v19, v94, 16, 1
	s_or_b32 s4, s25, s4
	v_lshrrev_b32_e32 v10, 16, v10
	v_add3_u32 v19, v94, v19, s31
	s_lshl_b32 s8, s8, 1
	v_and_or_b32 v19, v19, s33, v10
	v_or_b32_e32 v10, s4, v59
	v_lshl_add_u64 v[80:81], v[14:15], 0, s[8:9]
	v_lshlrev_b32_e32 v10, 11, v10
	v_lshl_add_u64 v[96:97], v[80:81], 0, v[10:11]
	v_bfe_u32 v10, v79, 16, 1
	global_store_dwordx4 v[96:97], v[16:19], off
	v_add3_u32 v10, v79, v10, s31
	v_lshrrev_b32_e32 v10, 16, v10
	v_bfe_u32 v16, v83, 16, 1
	v_add3_u32 v16, v83, v16, s31
	v_and_or_b32 v16, v16, s33, v10
	v_bfe_u32 v10, v85, 16, 1
	v_add3_u32 v10, v85, v10, s31
	v_bfe_u32 v17, v87, 16, 1
	v_lshrrev_b32_e32 v10, 16, v10
	v_add3_u32 v17, v87, v17, s31
	v_and_or_b32 v17, v17, s33, v10
	v_bfe_u32 v10, v89, 16, 1
	v_add3_u32 v10, v89, v10, s31
	v_bfe_u32 v18, v91, 16, 1
	v_lshrrev_b32_e32 v10, 16, v10
	v_add3_u32 v18, v91, v18, s31
	v_and_or_b32 v18, v18, s33, v10
	v_bfe_u32 v10, v93, 16, 1
	v_add3_u32 v10, v93, v10, s31
	v_bfe_u32 v19, v95, 16, 1
	v_lshrrev_b32_e32 v10, 16, v10
	v_add3_u32 v19, v95, v19, s31
	v_and_or_b32 v19, v19, s33, v10
	v_or_b32_e32 v10, s4, v74
	v_lshlrev_b32_e32 v10, 11, v10
	ds_read2_b32 v[78:79], v60 offset0:16 offset1:24
	v_lshl_add_u64 v[82:83], v[80:81], 0, v[10:11]
	global_store_dwordx4 v[82:83], v[16:19], off
	ds_read2_b32 v[82:83], v60 offset0:49 offset1:57
	ds_read2_b32 v[84:85], v60 offset0:82 offset1:90
	ds_read2_b32 v[86:87], v60 offset0:115 offset1:123
	s_waitcnt lgkmcnt(3)
	v_bfe_u32 v10, v78, 16, 1
	v_add3_u32 v10, v78, v10, s31
	s_waitcnt lgkmcnt(2)
	v_bfe_u32 v16, v82, 16, 1
	ds_read2_b32 v[88:89], v60 offset0:148 offset1:156
	v_lshrrev_b32_e32 v10, 16, v10
	v_add3_u32 v16, v82, v16, s31
	ds_read2_b32 v[90:91], v60 offset0:181 offset1:189
	v_and_or_b32 v16, v16, s33, v10
	s_waitcnt lgkmcnt(3)
	v_bfe_u32 v10, v84, 16, 1
	v_add3_u32 v10, v84, v10, s31
	s_waitcnt lgkmcnt(2)
	v_bfe_u32 v17, v86, 16, 1
	ds_read2_b32 v[92:93], v60 offset0:214 offset1:222
	v_lshrrev_b32_e32 v10, 16, v10
	v_add3_u32 v17, v86, v17, s31
	ds_read2_b32 v[94:95], v60 offset0:247 offset1:255
	v_and_or_b32 v17, v17, s33, v10
	s_waitcnt lgkmcnt(3)
	v_bfe_u32 v10, v88, 16, 1
	v_add3_u32 v10, v88, v10, s31
	s_waitcnt lgkmcnt(2)
	v_bfe_u32 v18, v90, 16, 1
	v_lshrrev_b32_e32 v10, 16, v10
	v_add3_u32 v18, v90, v18, s31
	v_and_or_b32 v18, v18, s33, v10
	s_waitcnt lgkmcnt(1)
	v_bfe_u32 v10, v92, 16, 1
	v_add3_u32 v10, v92, v10, s31
	s_waitcnt lgkmcnt(0)
	v_bfe_u32 v19, v94, 16, 1
	v_lshrrev_b32_e32 v10, 16, v10
	v_add3_u32 v19, v94, v19, s31
	v_and_or_b32 v19, v19, s33, v10
	v_or_b32_e32 v10, s4, v75
	v_lshlrev_b32_e32 v10, 11, v10
	v_lshl_add_u64 v[96:97], v[80:81], 0, v[10:11]
	v_bfe_u32 v10, v79, 16, 1
	global_store_dwordx4 v[96:97], v[16:19], off
	v_add3_u32 v10, v79, v10, s31
	v_lshrrev_b32_e32 v10, 16, v10
	v_bfe_u32 v16, v83, 16, 1
	v_add3_u32 v16, v83, v16, s31
	v_and_or_b32 v16, v16, s33, v10
	v_bfe_u32 v10, v85, 16, 1
	v_add3_u32 v10, v85, v10, s31
	v_bfe_u32 v17, v87, 16, 1
	v_lshrrev_b32_e32 v10, 16, v10
	v_add3_u32 v17, v87, v17, s31
	v_and_or_b32 v17, v17, s33, v10
	v_bfe_u32 v10, v89, 16, 1
	v_add3_u32 v10, v89, v10, s31
	v_bfe_u32 v18, v91, 16, 1
	v_lshrrev_b32_e32 v10, 16, v10
	v_add3_u32 v18, v91, v18, s31
	v_and_or_b32 v18, v18, s33, v10
	v_bfe_u32 v10, v93, 16, 1
	v_add3_u32 v10, v93, v10, s31
	v_bfe_u32 v19, v95, 16, 1
	v_lshrrev_b32_e32 v10, 16, v10
	v_add3_u32 v19, v95, v19, s31
	v_and_or_b32 v19, v19, s33, v10
	v_or_b32_e32 v10, s4, v76
	v_lshlrev_b32_e32 v10, 11, v10
	v_lshl_add_u64 v[78:79], v[80:81], 0, v[10:11]
	global_store_dwordx4 v[78:79], v[16:19], off
	s_waitcnt lgkmcnt(0)

.LBB0_234:
	s_andn2_b64 vcc, exec, s[4:5]
	s_cbranch_vccnz .LBB0_301
	s_add_u32 s4, s40, s28
	s_addc_u32 s5, s41, 0
	s_load_dwordx2 s[6:7], s[4:5], 0x90
	s_load_dwordx2 s[38:39], s[4:5], 0x80
	s_and_b64 s[4:5], s[20:21], exec
	s_cselect_b32 s4, 0x400000, 0
	v_lshlrev_b32_e32 v10, 2, v8
	s_waitcnt lgkmcnt(0)
	s_add_u32 s22, s6, s4
	s_addc_u32 s23, s7, 0
	s_and_b64 s[4:5], s[20:21], exec
	s_cselect_b32 s4, 0x1000, 0
	s_add_u32 s6, s38, s4
	s_addc_u32 s7, s39, 0
	s_lshl_b32 s4, s24, 1
	s_add_i32 s4, s4, 0x1f600
	s_and_b32 s25, s4, 0x1ffc0
	s_lshl_b32 s4, s24, 5
	s_and_b32 s8, s4, 0x3e0
	s_lshl_b32 s4, s8, 2
	s_add_u32 s4, s22, s4
	s_addc_u32 s5, s23, 0
	v_or_b32_e32 v19, s25, v6
	v_lshl_add_u64 v[16:17], s[4:5], 0, v[10:11]
	v_lshlrev_b32_e32 v10, 12, v19
	v_lshl_add_u64 v[78:79], v[16:17], 0, v[10:11]
	s_cmp_eq_u64 s[38:39], 0
	s_cbranch_scc1 .Lladder_ng_3
	global_load_dword v82, v[78:79], off
	v_lshlrev_b32_e32 v10, 2, v19
	global_load_dword v83, v10, s[6:7]
	v_or_b32_e32 v10, s25, v5
	v_lshlrev_b32_e32 v10, 12, v10
	v_lshl_add_u64 v[78:79], v[16:17], 0, v[10:11]
	global_load_dword v84, v[78:79], off
	v_add_lshl_u32 v18, s25, v6, 2
	global_load_dword v85, v18, s[6:7] offset:8
	v_or_b32_e32 v10, s25, v13
	v_lshlrev_b32_e32 v10, 12, v10
	v_lshl_add_u64 v[78:79], v[16:17], 0, v[10:11]
	global_load_dword v86, v[78:79], off
	global_load_dword v87, v18, s[6:7] offset:16
	v_or_b32_e32 v10, s25, v21
	v_lshlrev_b32_e32 v10, 12, v10
	v_lshl_add_u64 v[78:79], v[16:17], 0, v[10:11]
	global_load_dword v88, v[78:79], off
	global_load_dword v89, v18, s[6:7] offset:24
	v_or_b32_e32 v10, s25, v23
	v_lshlrev_b32_e32 v10, 12, v10
	v_lshl_add_u64 v[78:79], v[16:17], 0, v[10:11]
	global_load_dword v90, v[78:79], off
	global_load_dword v91, v18, s[6:7] offset:32
	v_or_b32_e32 v10, s25, v25
	v_lshlrev_b32_e32 v10, 12, v10
	v_lshl_add_u64 v[78:79], v[16:17], 0, v[10:11]
	global_load_dword v92, v[78:79], off
	global_load_dword v93, v18, s[6:7] offset:40
	v_or_b32_e32 v10, s25, v27
	v_lshlrev_b32_e32 v10, 12, v10
	v_lshl_add_u64 v[78:79], v[16:17], 0, v[10:11]
	global_load_dword v94, v[78:79], off
	global_load_dword v95, v18, s[6:7] offset:48
	v_or_b32_e32 v10, s25, v29
	v_lshlrev_b32_e32 v10, 12, v10
	v_lshl_add_u64 v[78:79], v[16:17], 0, v[10:11]
	global_load_dword v96, v[78:79], off
	global_load_dword v97, v18, s[6:7] offset:56
	v_or_b32_e32 v10, s25, v31
	v_lshlrev_b32_e32 v10, 12, v10
	v_lshl_add_u64 v[78:79], v[16:17], 0, v[10:11]
	global_load_dword v98, v[78:79], off
	global_load_dword v99, v18, s[6:7] offset:64
	v_or_b32_e32 v10, s25, v33
	v_lshlrev_b32_e32 v10, 12, v10
	v_lshl_add_u64 v[78:79], v[16:17], 0, v[10:11]
	global_load_dword v100, v[78:79], off
	global_load_dword v101, v18, s[6:7] offset:72
	v_or_b32_e32 v10, s25, v35
	v_lshlrev_b32_e32 v10, 12, v10
	v_lshl_add_u64 v[78:79], v[16:17], 0, v[10:11]
	global_load_dword v102, v[78:79], off
	global_load_dword v103, v18, s[6:7] offset:80
	v_or_b32_e32 v10, s25, v37
	v_lshlrev_b32_e32 v10, 12, v10
	v_lshl_add_u64 v[78:79], v[16:17], 0, v[10:11]
	global_load_dword v104, v[78:79], off
	global_load_dword v105, v18, s[6:7] offset:88
	v_or_b32_e32 v10, s25, v39
	v_lshlrev_b32_e32 v10, 12, v10
	v_lshl_add_u64 v[78:79], v[16:17], 0, v[10:11]
	global_load_dword v106, v[78:79], off
	global_load_dword v107, v18, s[6:7] offset:96
	v_or_b32_e32 v10, s25, v41
	v_lshlrev_b32_e32 v10, 12, v10
	v_lshl_add_u64 v[78:79], v[16:17], 0, v[10:11]
	global_load_dword v108, v[78:79], off
	global_load_dword v109, v18, s[6:7] offset:104
	v_or_b32_e32 v10, s25, v43
	v_lshlrev_b32_e32 v10, 12, v10
	v_lshl_add_u64 v[78:79], v[16:17], 0, v[10:11]
	global_load_dword v110, v[78:79], off
	global_load_dword v111, v18, s[6:7] offset:112
	v_or_b32_e32 v10, s25, v45
	v_lshlrev_b32_e32 v10, 12, v10
	v_lshl_add_u64 v[78:79], v[16:17], 0, v[10:11]
	global_load_dword v112, v[78:79], off
	global_load_dword v113, v18, s[6:7] offset:120
	v_or_b32_e32 v10, s25, v47
	v_lshlrev_b32_e32 v10, 12, v10
	v_lshl_add_u64 v[78:79], v[16:17], 0, v[10:11]
	global_load_dword v114, v[78:79], off
	global_load_dword v115, v18, s[6:7] offset:128
	v_or_b32_e32 v10, s25, v49
	v_lshlrev_b32_e32 v10, 12, v10
	v_lshl_add_u64 v[78:79], v[16:17], 0, v[10:11]
	global_load_dword v116, v[78:79], off
	global_load_dword v117, v18, s[6:7] offset:136
	v_or_b32_e32 v10, s25, v51
	v_lshlrev_b32_e32 v10, 12, v10
	v_lshl_add_u64 v[78:79], v[16:17], 0, v[10:11]
	global_load_dword v118, v[78:79], off
	global_load_dword v119, v18, s[6:7] offset:144
	v_or_b32_e32 v10, s25, v61
	v_lshlrev_b32_e32 v10, 12, v10
	v_lshl_add_u64 v[78:79], v[16:17], 0, v[10:11]
	global_load_dword v120, v[78:79], off
	global_load_dword v121, v18, s[6:7] offset:152
	v_or_b32_e32 v10, s25, v62
	v_lshlrev_b32_e32 v10, 12, v10
	v_lshl_add_u64 v[78:79], v[16:17], 0, v[10:11]
	global_load_dword v122, v[78:79], off
	global_load_dword v123, v18, s[6:7] offset:160
	v_or_b32_e32 v10, s25, v63
	v_lshlrev_b32_e32 v10, 12, v10
	v_lshl_add_u64 v[78:79], v[16:17], 0, v[10:11]
	global_load_dword v124, v[78:79], off
	global_load_dword v125, v18, s[6:7] offset:168
	v_or_b32_e32 v10, s25, v64
	v_lshlrev_b32_e32 v10, 12, v10
	v_lshl_add_u64 v[78:79], v[16:17], 0, v[10:11]
	global_load_dword v126, v[78:79], off
	global_load_dword v127, v18, s[6:7] offset:176
	v_or_b32_e32 v10, s25, v65
	v_lshlrev_b32_e32 v10, 12, v10
	v_lshl_add_u64 v[78:79], v[16:17], 0, v[10:11]
	global_load_dword v128, v[78:79], off
	global_load_dword v129, v18, s[6:7] offset:184
	v_or_b32_e32 v10, s25, v66
	v_lshlrev_b32_e32 v10, 12, v10
	v_lshl_add_u64 v[78:79], v[16:17], 0, v[10:11]
	global_load_dword v130, v[78:79], off
	global_load_dword v131, v18, s[6:7] offset:192
	v_or_b32_e32 v10, s25, v67
	v_lshlrev_b32_e32 v10, 12, v10
	v_lshl_add_u64 v[78:79], v[16:17], 0, v[10:11]
	global_load_dword v132, v[78:79], off
	global_load_dword v133, v18, s[6:7] offset:200
	v_or_b32_e32 v10, s25, v68
	v_lshlrev_b32_e32 v10, 12, v10
	v_lshl_add_u64 v[80:81], v[16:17], 0, v[10:11]
	global_load_dword v134, v[80:81], off
	global_load_dword v135, v18, s[6:7] offset:208
	v_or_b32_e32 v10, s25, v69
	v_lshlrev_b32_e32 v10, 12, v10
	v_lshl_add_u64 v[78:79], v[16:17], 0, v[10:11]
	global_load_dword v136, v[78:79], off
	global_load_dword v137, v18, s[6:7] offset:216
	v_or_b32_e32 v10, s25, v70
	v_lshlrev_b32_e32 v10, 12, v10
	v_lshl_add_u64 v[80:81], v[16:17], 0, v[10:11]
	global_load_dword v138, v[80:81], off
	global_load_dword v139, v18, s[6:7] offset:224
	v_or_b32_e32 v10, s25, v71
	v_lshlrev_b32_e32 v10, 12, v10
	v_lshl_add_u64 v[78:79], v[16:17], 0, v[10:11]
	global_load_dword v140, v[78:79], off
	global_load_dword v141, v18, s[6:7] offset:232
	v_or_b32_e32 v10, s25, v72
	v_lshlrev_b32_e32 v10, 12, v10
	v_lshl_add_u64 v[80:81], v[16:17], 0, v[10:11]
	global_load_dword v142, v[80:81], off
	global_load_dword v143, v18, s[6:7] offset:240
	v_or_b32_e32 v10, s25, v73
	v_lshlrev_b32_e32 v10, 12, v10
	v_lshl_add_u64 v[16:17], v[16:17], 0, v[10:11]
	global_load_dword v144, v[16:17], off
	global_load_dword v145, v18, s[6:7] offset:248
	s_waitcnt vmcnt(0)
	v_mul_f32_e32 v82, v82, v83
	v_add_u32_e32 v146, v1, v3
	ds_write_b32 v146, v82
	v_mul_f32_e32 v84, v84, v85
	v_add_u32_e32 v147, v1, v9
	ds_write_b32 v147, v84
	v_mul_f32_e32 v86, v86, v87
	v_add_u32_e32 v148, v1, v20
	ds_write_b32 v148, v86
	v_mul_f32_e32 v88, v88, v89
	v_add_u32_e32 v149, v1, v22
	ds_write_b32 v149, v88
	v_mul_f32_e32 v90, v90, v91
	v_add_u32_e32 v150, v1, v24
	ds_write_b32 v150, v90
	v_mul_f32_e32 v92, v92, v93
	v_add_u32_e32 v151, v1, v26
	ds_write_b32 v151, v92
	v_mul_f32_e32 v94, v94, v95
	v_add_u32_e32 v152, v1, v28
	ds_write_b32 v152, v94
	v_mul_f32_e32 v96, v96, v97
	v_add_u32_e32 v153, v1, v30
	ds_write_b32 v153, v96
	v_mul_f32_e32 v98, v98, v99
	v_add_u32_e32 v154, v1, v32
	ds_write_b32 v154, v98
	v_mul_f32_e32 v100, v100, v101
	v_add_u32_e32 v155, v1, v34
	ds_write_b32 v155, v100
	v_mul_f32_e32 v102, v102, v103
	v_add_u32_e32 v156, v1, v36
	ds_write_b32 v156, v102
	v_mul_f32_e32 v104, v104, v105
	v_add_u32_e32 v157, v1, v38
	ds_write_b32 v157, v104
	v_mul_f32_e32 v106, v106, v107
	v_add_u32_e32 v158, v1, v40
	ds_write_b32 v158, v106
	v_mul_f32_e32 v108, v108, v109
	v_add_u32_e32 v159, v1, v42
	ds_write_b32 v159, v108
	v_mul_f32_e32 v110, v110, v111
	v_add_u32_e32 v160, v1, v44
	ds_write_b32 v160, v110
	v_mul_f32_e32 v112, v112, v113
	v_add_u32_e32 v161, v1, v46
	ds_write_b32 v161, v112
	v_mul_f32_e32 v114, v114, v115
	v_add_u32_e32 v162, v1, v48
	ds_write_b32 v162, v114
	v_mul_f32_e32 v116, v116, v117
	v_add_u32_e32 v163, v1, v50
	ds_write_b32 v163, v116
	v_mul_f32_e32 v118, v118, v119
	v_add_u32_e32 v164, v1, v52
	ds_write_b32 v164, v118
	v_mul_f32_e32 v120, v120, v121
	v_add_u32_e32 v165, v1, v53
	ds_write_b32 v165, v120
	v_mul_f32_e32 v122, v122, v123
	v_add_u32_e32 v166, v1, v54
	ds_write_b32 v166, v122
	v_mul_f32_e32 v124, v124, v125
	v_add_u32_e32 v167, v1, v55
	ds_write_b32 v167, v124
	v_mul_f32_e32 v126, v126, v127
	v_add_u32_e32 v168, v1, v56
	ds_write_b32 v168, v126
	v_mul_f32_e32 v128, v128, v129
	v_add_u32_e32 v169, v1, v57
	ds_write_b32 v169, v128
	v_mul_f32_e32 v130, v130, v131
	v_add_u32_e32 v170, v1, v58
	ds_write_b32 v170, v130
	v_mul_f32_e32 v132, v132, v133
	ds_write_b32 v170, v132 offset:264
	v_mul_f32_e32 v134, v134, v135
	ds_write_b32 v170, v134 offset:528
	v_mul_f32_e32 v136, v136, v137
	ds_write_b32 v170, v136 offset:792
	v_mul_f32_e32 v138, v138, v139
	ds_write_b32 v170, v138 offset:1056
	v_mul_f32_e32 v140, v140, v141
	ds_write_b32 v170, v140 offset:1320
	v_mul_f32_e32 v142, v142, v143
	ds_write_b32 v170, v142 offset:1584
	v_mul_f32_e32 v145, v144, v145
	ds_write_b32 v170, v145 offset:1848
	s_branch .Lladder_done_3
.Lladder_ng_3:
	global_load_dword v82, v[78:79], off
	v_or_b32_e32 v10, s25, v5
	v_lshlrev_b32_e32 v10, 12, v10
	v_lshl_add_u64 v[78:79], v[16:17], 0, v[10:11]
	global_load_dword v83, v[78:79], off
	v_or_b32_e32 v10, s25, v13
	v_lshlrev_b32_e32 v10, 12, v10
	v_lshl_add_u64 v[78:79], v[16:17], 0, v[10:11]
	global_load_dword v84, v[78:79], off
	v_or_b32_e32 v10, s25, v21
	v_lshlrev_b32_e32 v10, 12, v10
	v_lshl_add_u64 v[78:79], v[16:17], 0, v[10:11]
	global_load_dword v85, v[78:79], off
	v_or_b32_e32 v10, s25, v23
	v_lshlrev_b32_e32 v10, 12, v10
	v_lshl_add_u64 v[78:79], v[16:17], 0, v[10:11]
	global_load_dword v86, v[78:79], off
	v_or_b32_e32 v10, s25, v25
	v_lshlrev_b32_e32 v10, 12, v10
	v_lshl_add_u64 v[78:79], v[16:17], 0, v[10:11]
	global_load_dword v87, v[78:79], off
	v_or_b32_e32 v10, s25, v27
	v_lshlrev_b32_e32 v10, 12, v10
	v_lshl_add_u64 v[78:79], v[16:17], 0, v[10:11]
	global_load_dword v88, v[78:79], off
	v_or_b32_e32 v10, s25, v29
	v_lshlrev_b32_e32 v10, 12, v10
	v_lshl_add_u64 v[78:79], v[16:17], 0, v[10:11]
	global_load_dword v89, v[78:79], off
	v_or_b32_e32 v10, s25, v31
	v_lshlrev_b32_e32 v10, 12, v10
	v_lshl_add_u64 v[78:79], v[16:17], 0, v[10:11]
	global_load_dword v90, v[78:79], off
	v_or_b32_e32 v10, s25, v33
	v_lshlrev_b32_e32 v10, 12, v10
	v_lshl_add_u64 v[78:79], v[16:17], 0, v[10:11]
	global_load_dword v91, v[78:79], off
	v_or_b32_e32 v10, s25, v35
	v_lshlrev_b32_e32 v10, 12, v10
	v_lshl_add_u64 v[78:79], v[16:17], 0, v[10:11]
	global_load_dword v92, v[78:79], off
	v_or_b32_e32 v10, s25, v37
	v_lshlrev_b32_e32 v10, 12, v10
	v_lshl_add_u64 v[78:79], v[16:17], 0, v[10:11]
	global_load_dword v93, v[78:79], off
	v_or_b32_e32 v10, s25, v39
	v_lshlrev_b32_e32 v10, 12, v10
	v_lshl_add_u64 v[78:79], v[16:17], 0, v[10:11]
	global_load_dword v94, v[78:79], off
	v_or_b32_e32 v10, s25, v41
	v_lshlrev_b32_e32 v10, 12, v10
	v_lshl_add_u64 v[78:79], v[16:17], 0, v[10:11]
	global_load_dword v95, v[78:79], off
	v_or_b32_e32 v10, s25, v43
	v_lshlrev_b32_e32 v10, 12, v10
	v_lshl_add_u64 v[78:79], v[16:17], 0, v[10:11]
	global_load_dword v96, v[78:79], off
	v_or_b32_e32 v10, s25, v45
	v_lshlrev_b32_e32 v10, 12, v10
	v_lshl_add_u64 v[78:79], v[16:17], 0, v[10:11]
	global_load_dword v97, v[78:79], off
	v_or_b32_e32 v10, s25, v47
	v_lshlrev_b32_e32 v10, 12, v10
	v_lshl_add_u64 v[78:79], v[16:17], 0, v[10:11]
	global_load_dword v98, v[78:79], off
	v_or_b32_e32 v10, s25, v49
	v_lshlrev_b32_e32 v10, 12, v10
	v_lshl_add_u64 v[78:79], v[16:17], 0, v[10:11]
	global_load_dword v99, v[78:79], off
	v_or_b32_e32 v10, s25, v51
	v_lshlrev_b32_e32 v10, 12, v10
	v_lshl_add_u64 v[78:79], v[16:17], 0, v[10:11]
	global_load_dword v100, v[78:79], off
	v_or_b32_e32 v10, s25, v61
	v_lshlrev_b32_e32 v10, 12, v10
	v_lshl_add_u64 v[78:79], v[16:17], 0, v[10:11]
	global_load_dword v101, v[78:79], off
	v_or_b32_e32 v10, s25, v62
	v_lshlrev_b32_e32 v10, 12, v10
	v_lshl_add_u64 v[78:79], v[16:17], 0, v[10:11]
	global_load_dword v102, v[78:79], off
	v_or_b32_e32 v10, s25, v63
	v_lshlrev_b32_e32 v10, 12, v10
	v_lshl_add_u64 v[78:79], v[16:17], 0, v[10:11]
	global_load_dword v103, v[78:79], off
	v_or_b32_e32 v10, s25, v64
	v_lshlrev_b32_e32 v10, 12, v10
	v_lshl_add_u64 v[78:79], v[16:17], 0, v[10:11]
	global_load_dword v104, v[78:79], off
	v_or_b32_e32 v10, s25, v65
	v_lshlrev_b32_e32 v10, 12, v10
	v_lshl_add_u64 v[78:79], v[16:17], 0, v[10:11]
	global_load_dword v105, v[78:79], off
	v_or_b32_e32 v10, s25, v66
	v_lshlrev_b32_e32 v10, 12, v10
	v_lshl_add_u64 v[78:79], v[16:17], 0, v[10:11]
	global_load_dword v106, v[78:79], off
	v_or_b32_e32 v10, s25, v67
	v_lshlrev_b32_e32 v10, 12, v10
	v_lshl_add_u64 v[78:79], v[16:17], 0, v[10:11]
	global_load_dword v107, v[78:79], off
	v_or_b32_e32 v10, s25, v68
	v_lshlrev_b32_e32 v10, 12, v10
	v_lshl_add_u64 v[80:81], v[16:17], 0, v[10:11]
	global_load_dword v108, v[80:81], off
	v_or_b32_e32 v10, s25, v69
	v_lshlrev_b32_e32 v10, 12, v10
	v_lshl_add_u64 v[78:79], v[16:17], 0, v[10:11]
	global_load_dword v109, v[78:79], off
	v_or_b32_e32 v10, s25, v70
	v_lshlrev_b32_e32 v10, 12, v10
	v_lshl_add_u64 v[80:81], v[16:17], 0, v[10:11]
	global_load_dword v110, v[80:81], off
	v_or_b32_e32 v10, s25, v71
	v_lshlrev_b32_e32 v10, 12, v10
	v_lshl_add_u64 v[78:79], v[16:17], 0, v[10:11]
	global_load_dword v111, v[78:79], off
	v_or_b32_e32 v10, s25, v72
	v_lshlrev_b32_e32 v10, 12, v10
	v_lshl_add_u64 v[80:81], v[16:17], 0, v[10:11]
	global_load_dword v112, v[80:81], off
	v_or_b32_e32 v10, s25, v73
	v_lshlrev_b32_e32 v10, 12, v10
	v_lshl_add_u64 v[16:17], v[16:17], 0, v[10:11]
	global_load_dword v113, v[16:17], off
	s_waitcnt vmcnt(0)
	v_add_u32_e32 v114, v1, v3
	ds_write_b32 v114, v82
	v_add_lshl_u32 v115, s25, v6, 2
	v_add_u32_e32 v116, v1, v9
	ds_write_b32 v116, v83
	v_add_u32_e32 v117, v1, v20
	ds_write_b32 v117, v84
	v_add_u32_e32 v118, v1, v22
	ds_write_b32 v118, v85
	v_add_u32_e32 v119, v1, v24
	ds_write_b32 v119, v86
	v_add_u32_e32 v120, v1, v26
	ds_write_b32 v120, v87
	v_add_u32_e32 v121, v1, v28
	ds_write_b32 v121, v88
	v_add_u32_e32 v122, v1, v30
	ds_write_b32 v122, v89
	v_add_u32_e32 v123, v1, v32
	ds_write_b32 v123, v90
	v_add_u32_e32 v124, v1, v34
	ds_write_b32 v124, v91
	v_add_u32_e32 v125, v1, v36
	ds_write_b32 v125, v92
	v_add_u32_e32 v126, v1, v38
	ds_write_b32 v126, v93
	v_add_u32_e32 v127, v1, v40
	ds_write_b32 v127, v94
	v_add_u32_e32 v128, v1, v42
	ds_write_b32 v128, v95
	v_add_u32_e32 v129, v1, v44
	ds_write_b32 v129, v96
	v_add_u32_e32 v130, v1, v46
	ds_write_b32 v130, v97
	v_add_u32_e32 v131, v1, v48
	ds_write_b32 v131, v98
	v_add_u32_e32 v132, v1, v50
	ds_write_b32 v132, v99
	v_add_u32_e32 v133, v1, v52
	ds_write_b32 v133, v100
	v_add_u32_e32 v134, v1, v53
	ds_write_b32 v134, v101
	v_add_u32_e32 v135, v1, v54
	ds_write_b32 v135, v102
	v_add_u32_e32 v136, v1, v55
	ds_write_b32 v136, v103
	v_add_u32_e32 v137, v1, v56
	ds_write_b32 v137, v104
	v_add_u32_e32 v138, v1, v57
	ds_write_b32 v138, v105
	v_add_u32_e32 v139, v1, v58
	ds_write_b32 v139, v106
	ds_write_b32 v139, v107 offset:264
	ds_write_b32 v139, v108 offset:528
	ds_write_b32 v139, v109 offset:792
	ds_write_b32 v139, v110 offset:1056
	ds_write_b32 v139, v111 offset:1320
	ds_write_b32 v139, v112 offset:1584
	v_mov_b32_e32 v16, v113
	ds_write_b32 v139, v16 offset:1848
.Lladder_done_3:
.LBB0_299:
	s_waitcnt lgkmcnt(0)
	ds_read2_b32 v[78:79], v60 offset1:8
	ds_read2_b32 v[82:83], v60 offset0:33 offset1:41
	s_lshl_b32 s4, s25, 1
	s_add_u32 s4, s37, s4
	ds_read2_b32 v[84:85], v60 offset0:66 offset1:74
	s_addc_u32 s5, s36, 0
	s_waitcnt vmcnt(0)
	v_lshlrev_b32_e32 v10, 1, v12
	ds_read2_b32 v[86:87], v60 offset0:99 offset1:107
	v_lshl_add_u64 v[16:17], s[4:5], 0, v[10:11]
	s_waitcnt lgkmcnt(3)
	v_bfe_u32 v10, v78, 16, 1
	v_lshl_add_u64 v[80:81], v[16:17], 0, s[18:19]
	v_add3_u32 v10, v78, v10, s31
	s_waitcnt lgkmcnt(2)
	v_bfe_u32 v16, v82, 16, 1
	ds_read2_b32 v[88:89], v60 offset0:132 offset1:140
	v_lshrrev_b32_e32 v10, 16, v10
	v_add3_u32 v16, v82, v16, s31
	ds_read2_b32 v[90:91], v60 offset0:165 offset1:173
	v_and_or_b32 v16, v16, s33, v10
	s_waitcnt lgkmcnt(3)
	v_bfe_u32 v10, v84, 16, 1
	v_add3_u32 v10, v84, v10, s31
	s_waitcnt lgkmcnt(2)
	v_bfe_u32 v17, v86, 16, 1
	ds_read2_b32 v[92:93], v60 offset0:198 offset1:206
	v_lshrrev_b32_e32 v10, 16, v10
	v_add3_u32 v17, v86, v17, s31
	ds_read2_b32 v[94:95], v60 offset0:231 offset1:239
	v_and_or_b32 v17, v17, s33, v10
	s_waitcnt lgkmcnt(3)
	v_bfe_u32 v10, v88, 16, 1
	v_add3_u32 v10, v88, v10, s31
	s_waitcnt lgkmcnt(2)
	v_bfe_u32 v18, v90, 16, 1
	v_lshrrev_b32_e32 v10, 16, v10
	v_add3_u32 v18, v90, v18, s31
	v_and_or_b32 v18, v18, s33, v10
	s_waitcnt lgkmcnt(1)
	v_bfe_u32 v10, v92, 16, 1
	v_add3_u32 v10, v92, v10, s31
	s_waitcnt lgkmcnt(0)
	v_bfe_u32 v19, v94, 16, 1
	v_lshrrev_b32_e32 v10, 16, v10
	v_add3_u32 v19, v94, v19, s31
	v_and_or_b32 v19, v19, s33, v10
	v_or_b32_e32 v10, s8, v59
	v_lshlrev_b32_e32 v10, 11, v10
	v_lshl_add_u64 v[96:97], v[80:81], 0, v[10:11]
	v_bfe_u32 v10, v79, 16, 1
	global_store_dwordx4 v[96:97], v[16:19], off
	v_add3_u32 v10, v79, v10, s31
	v_lshrrev_b32_e32 v10, 16, v10
	v_bfe_u32 v16, v83, 16, 1
	v_add3_u32 v16, v83, v16, s31
	v_and_or_b32 v16, v16, s33, v10
	v_bfe_u32 v10, v85, 16, 1
	v_add3_u32 v10, v85, v10, s31
	v_bfe_u32 v17, v87, 16, 1
	v_lshrrev_b32_e32 v10, 16, v10
	v_add3_u32 v17, v87, v17, s31
	v_and_or_b32 v17, v17, s33, v10
	v_bfe_u32 v10, v89, 16, 1
	v_add3_u32 v10, v89, v10, s31
	v_bfe_u32 v18, v91, 16, 1
	v_lshrrev_b32_e32 v10, 16, v10
	v_add3_u32 v18, v91, v18, s31
	v_and_or_b32 v18, v18, s33, v10
	v_bfe_u32 v10, v93, 16, 1
	v_add3_u32 v10, v93, v10, s31
	v_bfe_u32 v19, v95, 16, 1
	v_lshrrev_b32_e32 v10, 16, v10
	v_add3_u32 v19, v95, v19, s31
	v_and_or_b32 v19, v19, s33, v10
	v_or_b32_e32 v10, s8, v74
	v_lshlrev_b32_e32 v10, 11, v10
	ds_read2_b32 v[78:79], v60 offset0:16 offset1:24
	v_lshl_add_u64 v[82:83], v[80:81], 0, v[10:11]
	global_store_dwordx4 v[82:83], v[16:19], off
	ds_read2_b32 v[82:83], v60 offset0:49 offset1:57
	ds_read2_b32 v[84:85], v60 offset0:82 offset1:90
	ds_read2_b32 v[86:87], v60 offset0:115 offset1:123
	s_waitcnt lgkmcnt(3)
	v_bfe_u32 v10, v78, 16, 1
	v_add3_u32 v10, v78, v10, s31
	s_waitcnt lgkmcnt(2)
	v_bfe_u32 v16, v82, 16, 1
	ds_read2_b32 v[88:89], v60 offset0:148 offset1:156
	v_lshrrev_b32_e32 v10, 16, v10
	v_add3_u32 v16, v82, v16, s31
	ds_read2_b32 v[90:91], v60 offset0:181 offset1:189
	v_and_or_b32 v16, v16, s33, v10
	s_waitcnt lgkmcnt(3)
	v_bfe_u32 v10, v84, 16, 1
	v_add3_u32 v10, v84, v10, s31
	s_waitcnt lgkmcnt(2)
	v_bfe_u32 v17, v86, 16, 1
	ds_read2_b32 v[92:93], v60 offset0:214 offset1:222
	v_lshrrev_b32_e32 v10, 16, v10
	v_add3_u32 v17, v86, v17, s31
	ds_read2_b32 v[94:95], v60 offset0:247 offset1:255
	v_and_or_b32 v17, v17, s33, v10
	s_waitcnt lgkmcnt(3)
	v_bfe_u32 v10, v88, 16, 1
	v_add3_u32 v10, v88, v10, s31
	s_waitcnt lgkmcnt(2)
	v_bfe_u32 v18, v90, 16, 1
	v_lshrrev_b32_e32 v10, 16, v10
	v_add3_u32 v18, v90, v18, s31
	v_and_or_b32 v18, v18, s33, v10
	s_waitcnt lgkmcnt(1)
	v_bfe_u32 v10, v92, 16, 1
	v_add3_u32 v10, v92, v10, s31
	s_waitcnt lgkmcnt(0)
	v_bfe_u32 v19, v94, 16, 1
	v_lshrrev_b32_e32 v10, 16, v10
	v_add3_u32 v19, v94, v19, s31
	v_and_or_b32 v19, v19, s33, v10
	v_or_b32_e32 v10, s8, v75
	v_lshlrev_b32_e32 v10, 11, v10
	v_lshl_add_u64 v[96:97], v[80:81], 0, v[10:11]
	v_bfe_u32 v10, v79, 16, 1
	global_store_dwordx4 v[96:97], v[16:19], off
	v_add3_u32 v10, v79, v10, s31
	v_lshrrev_b32_e32 v10, 16, v10
	v_bfe_u32 v16, v83, 16, 1
	v_add3_u32 v16, v83, v16, s31
	v_and_or_b32 v16, v16, s33, v10
	v_bfe_u32 v10, v85, 16, 1
	v_add3_u32 v10, v85, v10, s31
	v_bfe_u32 v17, v87, 16, 1
	v_lshrrev_b32_e32 v10, 16, v10
	v_add3_u32 v17, v87, v17, s31
	v_and_or_b32 v17, v17, s33, v10
	v_bfe_u32 v10, v89, 16, 1
	v_add3_u32 v10, v89, v10, s31
	v_bfe_u32 v18, v91, 16, 1
	v_lshrrev_b32_e32 v10, 16, v10
	v_add3_u32 v18, v91, v18, s31
	v_and_or_b32 v18, v18, s33, v10
	v_bfe_u32 v10, v93, 16, 1
	v_add3_u32 v10, v93, v10, s31
	v_bfe_u32 v19, v95, 16, 1
	v_lshrrev_b32_e32 v10, 16, v10
	v_add3_u32 v19, v95, v19, s31
	v_and_or_b32 v19, v19, s33, v10
	v_or_b32_e32 v10, s8, v76
	v_lshlrev_b32_e32 v10, 11, v10
	v_lshl_add_u64 v[78:79], v[80:81], 0, v[10:11]
	global_store_dwordx4 v[78:79], v[16:19], off
	s_waitcnt lgkmcnt(0)

.LBB0_1678:
	s_andn2_b64 vcc, exec, s[4:5]
	s_cbranch_vccnz .LBB0_1744
	s_load_dwordx4 s[40:43], s[62:63], 0xb0
	s_add_i32 s4, s29, 0xf300
	v_lshlrev_b32_e32 v2, 2, v4
	s_waitcnt lgkmcnt(0)
	s_add_u32 s6, s40, 0x1000
	s_addc_u32 s7, s41, 0
	s_lshl_b32 s5, s29, 5
	s_lshr_b32 s4, s4, 1
	s_and_b32 s28, s5, 0xfe0
	s_and_b32 s30, s4, 0x7fc0
	s_lshl_b32 s4, s28, 2
	s_add_u32 s4, s42, s4
	s_addc_u32 s5, s43, 0
	v_lshl_add_u64 v[20:21], s[4:5], 0, v[2:3]
	s_mov_b64 s[4:5], 0x1000000
	v_or_b32_e32 v22, s30, v1
	v_lshl_add_u64 v[20:21], v[20:21], 0, s[4:5]
	v_lshlrev_b32_e32 v2, 14, v22
	v_lshl_add_u64 v[86:87], v[20:21], 0, v[2:3]
	s_cmp_eq_u64 s[40:41], 0
	s_cbranch_scc1 .Lladder_ng_4
	global_load_dword v88, v[86:87], off
	v_lshlrev_b32_e32 v22, 2, v22
	global_load_dword v89, v22, s[6:7]
	v_or_b32_e32 v22, s30, v25
	v_lshlrev_b32_e32 v2, 14, v22
	v_lshl_add_u64 v[86:87], v[20:21], 0, v[2:3]
	global_load_dword v90, v[86:87], off
	v_lshlrev_b32_e32 v22, 2, v22
	global_load_dword v91, v22, s[6:7]
	v_or_b32_e32 v22, s30, v27
	v_lshlrev_b32_e32 v2, 14, v22
	v_lshl_add_u64 v[86:87], v[20:21], 0, v[2:3]
	global_load_dword v92, v[86:87], off
	v_lshlrev_b32_e32 v22, 2, v22
	global_load_dword v93, v22, s[6:7]
	v_or_b32_e32 v22, s30, v29
	v_lshlrev_b32_e32 v2, 14, v22
	v_lshl_add_u64 v[86:87], v[20:21], 0, v[2:3]
	global_load_dword v94, v[86:87], off
	v_lshlrev_b32_e32 v22, 2, v22
	global_load_dword v95, v22, s[6:7]
	v_or_b32_e32 v22, s30, v31
	v_lshlrev_b32_e32 v2, 14, v22
	v_lshl_add_u64 v[86:87], v[20:21], 0, v[2:3]
	global_load_dword v96, v[86:87], off
	v_lshlrev_b32_e32 v22, 2, v22
	global_load_dword v97, v22, s[6:7]
	v_or_b32_e32 v22, s30, v33
	v_lshlrev_b32_e32 v2, 14, v22
	v_lshl_add_u64 v[86:87], v[20:21], 0, v[2:3]
	global_load_dword v98, v[86:87], off
	v_lshlrev_b32_e32 v22, 2, v22
	global_load_dword v99, v22, s[6:7]
	v_or_b32_e32 v22, s30, v35
	v_lshlrev_b32_e32 v2, 14, v22
	v_lshl_add_u64 v[86:87], v[20:21], 0, v[2:3]
	global_load_dword v100, v[86:87], off
	v_lshlrev_b32_e32 v22, 2, v22
	global_load_dword v101, v22, s[6:7]
	v_or_b32_e32 v22, s30, v37
	v_lshlrev_b32_e32 v2, 14, v22
	v_lshl_add_u64 v[86:87], v[20:21], 0, v[2:3]
	global_load_dword v102, v[86:87], off
	v_lshlrev_b32_e32 v22, 2, v22
	global_load_dword v103, v22, s[6:7]
	v_or_b32_e32 v22, s30, v39
	v_lshlrev_b32_e32 v2, 14, v22
	v_lshl_add_u64 v[86:87], v[20:21], 0, v[2:3]
	global_load_dword v104, v[86:87], off
	v_lshlrev_b32_e32 v22, 2, v22
	global_load_dword v105, v22, s[6:7]
	v_or_b32_e32 v22, s30, v41
	v_lshlrev_b32_e32 v2, 14, v22
	v_lshl_add_u64 v[86:87], v[20:21], 0, v[2:3]
	global_load_dword v148, v[86:87], off
	v_lshlrev_b32_e32 v22, 2, v22
	global_load_dword v149, v22, s[6:7]
	v_or_b32_e32 v22, s30, v43
	v_lshlrev_b32_e32 v2, 14, v22
	v_lshl_add_u64 v[86:87], v[20:21], 0, v[2:3]
	global_load_dword v150, v[86:87], off
	v_lshlrev_b32_e32 v22, 2, v22
	global_load_dword v151, v22, s[6:7]
	v_or_b32_e32 v22, s30, v45
	v_lshlrev_b32_e32 v2, 14, v22
	v_lshl_add_u64 v[86:87], v[20:21], 0, v[2:3]
	global_load_dword v152, v[86:87], off
	v_lshlrev_b32_e32 v22, 2, v22
	global_load_dword v153, v22, s[6:7]
	v_or_b32_e32 v22, s30, v47
	v_lshlrev_b32_e32 v2, 14, v22
	v_lshl_add_u64 v[86:87], v[20:21], 0, v[2:3]
	global_load_dword v154, v[86:87], off
	v_lshlrev_b32_e32 v22, 2, v22
	global_load_dword v155, v22, s[6:7]
	v_or_b32_e32 v22, s30, v49
	v_lshlrev_b32_e32 v2, 14, v22
	v_lshl_add_u64 v[86:87], v[20:21], 0, v[2:3]
	global_load_dword v156, v[86:87], off
	v_lshlrev_b32_e32 v22, 2, v22
	global_load_dword v157, v22, s[6:7]
	v_or_b32_e32 v22, s30, v51
	v_lshlrev_b32_e32 v2, 14, v22
	v_lshl_add_u64 v[86:87], v[20:21], 0, v[2:3]
	global_load_dword v158, v[86:87], off
	v_lshlrev_b32_e32 v22, 2, v22
	global_load_dword v159, v22, s[6:7]
	v_or_b32_e32 v22, s30, v53
	v_lshlrev_b32_e32 v2, 14, v22
	v_lshl_add_u64 v[86:87], v[20:21], 0, v[2:3]
	global_load_dword v160, v[86:87], off
	v_lshlrev_b32_e32 v22, 2, v22
	global_load_dword v161, v22, s[6:7]
	v_or_b32_e32 v22, s30, v55
	v_lshlrev_b32_e32 v2, 14, v22
	v_lshl_add_u64 v[86:87], v[20:21], 0, v[2:3]
	global_load_dword v162, v[86:87], off
	v_lshlrev_b32_e32 v22, 2, v22
	global_load_dword v163, v22, s[6:7]
	v_or_b32_e32 v22, s30, v57
	v_lshlrev_b32_e32 v2, 14, v22
	v_lshl_add_u64 v[86:87], v[20:21], 0, v[2:3]
	global_load_dword v165, v[86:87], off
	v_lshlrev_b32_e32 v22, 2, v22
	global_load_dword v166, v22, s[6:7]
	v_or_b32_e32 v22, s30, v59
	v_lshlrev_b32_e32 v2, 14, v22
	v_lshl_add_u64 v[86:87], v[20:21], 0, v[2:3]
	global_load_dword v167, v[86:87], off
	v_lshlrev_b32_e32 v22, 2, v22
	global_load_dword v168, v22, s[6:7]
	v_or_b32_e32 v22, s30, v61
	v_lshlrev_b32_e32 v2, 14, v22
	v_lshl_add_u64 v[86:87], v[20:21], 0, v[2:3]
	global_load_dword v169, v[86:87], off
	v_lshlrev_b32_e32 v22, 2, v22
	global_load_dword v170, v22, s[6:7]
	v_or_b32_e32 v22, s30, v63
	v_lshlrev_b32_e32 v2, 14, v22
	v_lshl_add_u64 v[86:87], v[20:21], 0, v[2:3]
	global_load_dword v171, v[86:87], off
	v_lshlrev_b32_e32 v22, 2, v22
	global_load_dword v172, v22, s[6:7]
	v_or_b32_e32 v22, s30, v65
	v_lshlrev_b32_e32 v2, 14, v22
	v_lshl_add_u64 v[86:87], v[20:21], 0, v[2:3]
	global_load_dword v173, v[86:87], off
	v_lshlrev_b32_e32 v22, 2, v22
	global_load_dword v174, v22, s[6:7]
	v_or_b32_e32 v22, s30, v67
	v_lshlrev_b32_e32 v2, 14, v22
	v_lshl_add_u64 v[86:87], v[20:21], 0, v[2:3]
	global_load_dword v175, v[86:87], off
	v_lshlrev_b32_e32 v22, 2, v22
	global_load_dword v176, v22, s[6:7]
	v_or_b32_e32 v22, s30, v69
	v_lshlrev_b32_e32 v2, 14, v22
	v_lshl_add_u64 v[86:87], v[20:21], 0, v[2:3]
	global_load_dword v177, v[86:87], off
	v_lshlrev_b32_e32 v22, 2, v22
	global_load_dword v178, v22, s[6:7]
	v_or_b32_e32 v22, s30, v71
	v_lshlrev_b32_e32 v2, 14, v22
	v_lshl_add_u64 v[86:87], v[20:21], 0, v[2:3]
	global_load_dword v179, v[86:87], off
	v_lshlrev_b32_e32 v2, 2, v22
	global_load_dword v180, v2, s[6:7]
	v_or_b32_e32 v85, s30, v73
	v_lshlrev_b32_e32 v2, 14, v85
	v_lshl_add_u64 v[86:87], v[20:21], 0, v[2:3]
	global_load_dword v181, v[86:87], off
	v_lshlrev_b32_e32 v23, 2, v85
	global_load_dword v182, v23, s[6:7]
	v_or_b32_e32 v23, s30, v74
	v_lshlrev_b32_e32 v2, 14, v23
	v_lshl_add_u64 v[86:87], v[20:21], 0, v[2:3]
	global_load_dword v183, v[86:87], off
	v_lshlrev_b32_e32 v23, 2, v23
	global_load_dword v184, v23, s[6:7]
	v_or_b32_e32 v23, s30, v75
	v_lshlrev_b32_e32 v2, 14, v23
	v_lshl_add_u64 v[86:87], v[20:21], 0, v[2:3]
	global_load_dword v185, v[86:87], off
	v_lshlrev_b32_e32 v23, 2, v23
	global_load_dword v186, v23, s[6:7]
	v_or_b32_e32 v23, s30, v76
	v_lshlrev_b32_e32 v2, 14, v23
	v_lshl_add_u64 v[86:87], v[20:21], 0, v[2:3]
	global_load_dword v187, v[86:87], off
	v_lshlrev_b32_e32 v23, 2, v23
	global_load_dword v188, v23, s[6:7]
	v_or_b32_e32 v23, s30, v77
	v_lshlrev_b32_e32 v2, 14, v23
	v_lshl_add_u64 v[86:87], v[20:21], 0, v[2:3]
	global_load_dword v189, v[86:87], off
	v_lshlrev_b32_e32 v23, 2, v23
	global_load_dword v190, v23, s[6:7]
	v_or_b32_e32 v23, s30, v78
	v_lshlrev_b32_e32 v2, 14, v23
	v_lshl_add_u64 v[86:87], v[20:21], 0, v[2:3]
	global_load_dword v191, v[86:87], off
	v_lshlrev_b32_e32 v23, 2, v23
	global_load_dword v192, v23, s[6:7]
	v_or_b32_e32 v23, s30, v79
	v_lshlrev_b32_e32 v2, 14, v23
	v_lshl_add_u64 v[20:21], v[20:21], 0, v[2:3]
	global_load_dword v193, v[20:21], off
	v_lshlrev_b32_e32 v20, 2, v23
	global_load_dword v194, v20, s[6:7]
	s_waitcnt vmcnt(0)
	v_mul_f32_e32 v88, v88, v89
	v_add_u32_e32 v195, v5, v24
	ds_write_b32 v195, v88
	s_movk_i32 s42, 0x4000
	v_mul_f32_e32 v90, v90, v91
	v_add_u32_e32 v196, v5, v26
	ds_write_b32 v196, v90
	v_mul_f32_e32 v92, v92, v93
	v_add_u32_e32 v197, v5, v28
	ds_write_b32 v197, v92
	v_mul_f32_e32 v94, v94, v95
	v_add_u32_e32 v198, v5, v30
	ds_write_b32 v198, v94
	v_mul_f32_e32 v96, v96, v97
	v_add_u32_e32 v199, v5, v32
	ds_write_b32 v199, v96
	v_mul_f32_e32 v98, v98, v99
	v_add_u32_e32 v200, v5, v34
	ds_write_b32 v200, v98
	v_mul_f32_e32 v100, v100, v101
	v_add_u32_e32 v201, v5, v36
	ds_write_b32 v201, v100
	v_mul_f32_e32 v102, v102, v103
	v_add_u32_e32 v202, v5, v38
	ds_write_b32 v202, v102
	v_mul_f32_e32 v104, v104, v105
	v_add_u32_e32 v203, v5, v40
	ds_write_b32 v203, v104
	v_mul_f32_e32 v148, v148, v149
	v_add_u32_e32 v204, v5, v42
	ds_write_b32 v204, v148
	v_mul_f32_e32 v150, v150, v151
	v_add_u32_e32 v205, v5, v44
	ds_write_b32 v205, v150
	v_mul_f32_e32 v152, v152, v153
	v_add_u32_e32 v206, v5, v46
	ds_write_b32 v206, v152
	v_mul_f32_e32 v154, v154, v155
	v_add_u32_e32 v207, v5, v48
	ds_write_b32 v207, v154
	v_mul_f32_e32 v156, v156, v157
	v_add_u32_e32 v210, v5, v50
	ds_write_b32 v210, v156
	v_mul_f32_e32 v158, v158, v159
	v_add_u32_e32 v211, v5, v52
	ds_write_b32 v211, v158
	v_mul_f32_e32 v160, v160, v161
	v_add_u32_e32 v212, v5, v54
	ds_write_b32 v212, v160
	v_mul_f32_e32 v162, v162, v163
	v_add_u32_e32 v213, v5, v56
	ds_write_b32 v213, v162
	v_mul_f32_e32 v165, v165, v166
	v_add_u32_e32 v217, v5, v58
	ds_write_b32 v217, v165
	v_mul_f32_e32 v167, v167, v168
	v_add_u32_e32 v218, v5, v60
	ds_write_b32 v218, v167
	v_mul_f32_e32 v169, v169, v170
	v_add_u32_e32 v219, v5, v62
	ds_write_b32 v219, v169
	v_mul_f32_e32 v171, v171, v172
	v_add_u32_e32 v220, v5, v64
	ds_write_b32 v220, v171
	v_mul_f32_e32 v173, v173, v174
	v_add_u32_e32 v221, v5, v66
	ds_write_b32 v221, v173
	v_mul_f32_e32 v175, v175, v176
	v_add_u32_e32 v222, v5, v68
	ds_write_b32 v222, v175
	v_mul_f32_e32 v177, v177, v178
	v_add_u32_e32 v223, v5, v70
	ds_write_b32 v223, v177
	v_mul_f32_e32 v179, v179, v180
	v_add_u32_e32 v224, v5, v72
	ds_write_b32 v224, v179
	v_mul_f32_e32 v181, v181, v182
	ds_write_b32 v224, v181 offset:264
	v_mul_f32_e32 v183, v183, v184
	ds_write_b32 v224, v183 offset:528
	v_mul_f32_e32 v185, v185, v186
	ds_write_b32 v224, v185 offset:792
	v_mul_f32_e32 v187, v187, v188
	ds_write_b32 v224, v187 offset:1056
	v_mul_f32_e32 v189, v189, v190
	ds_write_b32 v224, v189 offset:1320
	v_mul_f32_e32 v191, v191, v192
	ds_write_b32 v224, v191 offset:1584
	v_mul_f32_e32 v193, v193, v194
	ds_write_b32 v224, v193 offset:1848
	s_branch .Lladder_done_4
.Lladder_ng_4:
	global_load_dword v88, v[86:87], off
	v_or_b32_e32 v22, s30, v25
	v_lshlrev_b32_e32 v2, 14, v22
	v_lshl_add_u64 v[86:87], v[20:21], 0, v[2:3]
	global_load_dword v89, v[86:87], off
	v_or_b32_e32 v22, s30, v27
	v_lshlrev_b32_e32 v2, 14, v22
	v_lshl_add_u64 v[86:87], v[20:21], 0, v[2:3]
	global_load_dword v90, v[86:87], off
	v_or_b32_e32 v22, s30, v29
	v_lshlrev_b32_e32 v2, 14, v22
	v_lshl_add_u64 v[86:87], v[20:21], 0, v[2:3]
	global_load_dword v91, v[86:87], off
	v_or_b32_e32 v22, s30, v31
	v_lshlrev_b32_e32 v2, 14, v22
	v_lshl_add_u64 v[86:87], v[20:21], 0, v[2:3]
	global_load_dword v92, v[86:87], off
	v_or_b32_e32 v22, s30, v33
	v_lshlrev_b32_e32 v2, 14, v22
	v_lshl_add_u64 v[86:87], v[20:21], 0, v[2:3]
	global_load_dword v93, v[86:87], off
	v_or_b32_e32 v22, s30, v35
	v_lshlrev_b32_e32 v2, 14, v22
	v_lshl_add_u64 v[86:87], v[20:21], 0, v[2:3]
	global_load_dword v94, v[86:87], off
	v_or_b32_e32 v22, s30, v37
	v_lshlrev_b32_e32 v2, 14, v22
	v_lshl_add_u64 v[86:87], v[20:21], 0, v[2:3]
	global_load_dword v95, v[86:87], off
	v_or_b32_e32 v22, s30, v39
	v_lshlrev_b32_e32 v2, 14, v22
	v_lshl_add_u64 v[86:87], v[20:21], 0, v[2:3]
	global_load_dword v96, v[86:87], off
	v_or_b32_e32 v22, s30, v41
	v_lshlrev_b32_e32 v2, 14, v22
	v_lshl_add_u64 v[86:87], v[20:21], 0, v[2:3]
	global_load_dword v97, v[86:87], off
	v_or_b32_e32 v22, s30, v43
	v_lshlrev_b32_e32 v2, 14, v22
	v_lshl_add_u64 v[86:87], v[20:21], 0, v[2:3]
	global_load_dword v98, v[86:87], off
	v_or_b32_e32 v22, s30, v45
	v_lshlrev_b32_e32 v2, 14, v22
	v_lshl_add_u64 v[86:87], v[20:21], 0, v[2:3]
	global_load_dword v99, v[86:87], off
	v_or_b32_e32 v22, s30, v47
	v_lshlrev_b32_e32 v2, 14, v22
	v_lshl_add_u64 v[86:87], v[20:21], 0, v[2:3]
	global_load_dword v100, v[86:87], off
	v_or_b32_e32 v22, s30, v49
	v_lshlrev_b32_e32 v2, 14, v22
	v_lshl_add_u64 v[86:87], v[20:21], 0, v[2:3]
	global_load_dword v101, v[86:87], off
	v_or_b32_e32 v22, s30, v51
	v_lshlrev_b32_e32 v2, 14, v22
	v_lshl_add_u64 v[86:87], v[20:21], 0, v[2:3]
	global_load_dword v102, v[86:87], off
	v_or_b32_e32 v22, s30, v53
	v_lshlrev_b32_e32 v2, 14, v22
	v_lshl_add_u64 v[86:87], v[20:21], 0, v[2:3]
	global_load_dword v103, v[86:87], off
	v_or_b32_e32 v22, s30, v55
	v_lshlrev_b32_e32 v2, 14, v22
	v_lshl_add_u64 v[86:87], v[20:21], 0, v[2:3]
	global_load_dword v104, v[86:87], off
	v_or_b32_e32 v22, s30, v57
	v_lshlrev_b32_e32 v2, 14, v22
	v_lshl_add_u64 v[86:87], v[20:21], 0, v[2:3]
	global_load_dword v105, v[86:87], off
	v_or_b32_e32 v22, s30, v59
	v_lshlrev_b32_e32 v2, 14, v22
	v_lshl_add_u64 v[86:87], v[20:21], 0, v[2:3]
	global_load_dword v148, v[86:87], off
	v_or_b32_e32 v22, s30, v61
	v_lshlrev_b32_e32 v2, 14, v22
	v_lshl_add_u64 v[86:87], v[20:21], 0, v[2:3]
	global_load_dword v149, v[86:87], off
	v_or_b32_e32 v22, s30, v63
	v_lshlrev_b32_e32 v2, 14, v22
	v_lshl_add_u64 v[86:87], v[20:21], 0, v[2:3]
	global_load_dword v150, v[86:87], off
	v_or_b32_e32 v22, s30, v65
	v_lshlrev_b32_e32 v2, 14, v22
	v_lshl_add_u64 v[86:87], v[20:21], 0, v[2:3]
	global_load_dword v151, v[86:87], off
	v_or_b32_e32 v22, s30, v67
	v_lshlrev_b32_e32 v2, 14, v22
	v_lshl_add_u64 v[86:87], v[20:21], 0, v[2:3]
	global_load_dword v152, v[86:87], off
	v_or_b32_e32 v22, s30, v69
	v_lshlrev_b32_e32 v2, 14, v22
	v_lshl_add_u64 v[86:87], v[20:21], 0, v[2:3]
	global_load_dword v153, v[86:87], off
	v_or_b32_e32 v22, s30, v71
	v_lshlrev_b32_e32 v2, 14, v22
	v_lshl_add_u64 v[86:87], v[20:21], 0, v[2:3]
	global_load_dword v154, v[86:87], off
	v_or_b32_e32 v85, s30, v73
	v_lshlrev_b32_e32 v2, 14, v85
	v_lshl_add_u64 v[86:87], v[20:21], 0, v[2:3]
	global_load_dword v155, v[86:87], off
	v_or_b32_e32 v23, s30, v74
	v_lshlrev_b32_e32 v2, 14, v23
	v_lshl_add_u64 v[86:87], v[20:21], 0, v[2:3]
	global_load_dword v156, v[86:87], off
	v_or_b32_e32 v23, s30, v75
	v_lshlrev_b32_e32 v2, 14, v23
	v_lshl_add_u64 v[86:87], v[20:21], 0, v[2:3]
	global_load_dword v157, v[86:87], off
	v_or_b32_e32 v23, s30, v76
	v_lshlrev_b32_e32 v2, 14, v23
	v_lshl_add_u64 v[86:87], v[20:21], 0, v[2:3]
	global_load_dword v158, v[86:87], off
	v_or_b32_e32 v23, s30, v77
	v_lshlrev_b32_e32 v2, 14, v23
	v_lshl_add_u64 v[86:87], v[20:21], 0, v[2:3]
	global_load_dword v159, v[86:87], off
	v_or_b32_e32 v23, s30, v78
	v_lshlrev_b32_e32 v2, 14, v23
	v_lshl_add_u64 v[86:87], v[20:21], 0, v[2:3]
	global_load_dword v160, v[86:87], off
	v_or_b32_e32 v23, s30, v79
	v_lshlrev_b32_e32 v2, 14, v23
	v_lshl_add_u64 v[20:21], v[20:21], 0, v[2:3]
	global_load_dword v161, v[20:21], off
	s_waitcnt vmcnt(0)
	v_add_u32_e32 v162, v5, v24
	ds_write_b32 v162, v88
	s_movk_i32 s42, 0x4000
	v_add_u32_e32 v163, v5, v26
	ds_write_b32 v163, v89
	v_add_u32_e32 v165, v5, v28
	ds_write_b32 v165, v90
	v_add_u32_e32 v166, v5, v30
	ds_write_b32 v166, v91
	v_add_u32_e32 v167, v5, v32
	ds_write_b32 v167, v92
	v_add_u32_e32 v168, v5, v34
	ds_write_b32 v168, v93
	v_add_u32_e32 v169, v5, v36
	ds_write_b32 v169, v94
	v_add_u32_e32 v170, v5, v38
	ds_write_b32 v170, v95
	v_add_u32_e32 v171, v5, v40
	ds_write_b32 v171, v96
	v_add_u32_e32 v172, v5, v42
	ds_write_b32 v172, v97
	v_add_u32_e32 v173, v5, v44
	ds_write_b32 v173, v98
	v_add_u32_e32 v174, v5, v46
	ds_write_b32 v174, v99
	v_add_u32_e32 v175, v5, v48
	ds_write_b32 v175, v100
	v_add_u32_e32 v176, v5, v50
	ds_write_b32 v176, v101
	v_add_u32_e32 v177, v5, v52
	ds_write_b32 v177, v102
	v_add_u32_e32 v178, v5, v54
	ds_write_b32 v178, v103
	v_add_u32_e32 v179, v5, v56
	ds_write_b32 v179, v104
	v_add_u32_e32 v180, v5, v58
	ds_write_b32 v180, v105
	v_add_u32_e32 v181, v5, v60
	ds_write_b32 v181, v148
	v_add_u32_e32 v182, v5, v62
	ds_write_b32 v182, v149
	v_add_u32_e32 v183, v5, v64
	ds_write_b32 v183, v150
	v_add_u32_e32 v184, v5, v66
	ds_write_b32 v184, v151
	v_add_u32_e32 v185, v5, v68
	ds_write_b32 v185, v152
	v_add_u32_e32 v186, v5, v70
	ds_write_b32 v186, v153
	v_add_u32_e32 v187, v5, v72
	ds_write_b32 v187, v154
	ds_write_b32 v187, v155 offset:264
	ds_write_b32 v187, v156 offset:528
	ds_write_b32 v187, v157 offset:792
	ds_write_b32 v187, v158 offset:1056
	ds_write_b32 v187, v159 offset:1320
	ds_write_b32 v187, v160 offset:1584
	ds_write_b32 v187, v161 offset:1848
.Lladder_done_4:
	s_waitcnt lgkmcnt(0)
	ds_read2_b32 v[86:87], v81 offset1:8
	ds_read2_b32 v[90:91], v81 offset0:33 offset1:41
	ds_read2_b32 v[92:93], v81 offset0:66 offset1:74
	ds_read2_b32 v[94:95], v81 offset0:99 offset1:107
	ds_read2_b32 v[96:97], v81 offset0:132 offset1:140
	ds_read2_b32 v[98:99], v81 offset0:165 offset1:173
	s_waitcnt lgkmcnt(5)
	v_bfe_u32 v2, v86, 16, 1
	v_add3_u32 v2, v86, v2, s93
	s_waitcnt lgkmcnt(4)
	v_bfe_u32 v20, v90, 16, 1
	v_lshrrev_b32_e32 v2, 16, v2
	v_add3_u32 v20, v90, v20, s93
	v_and_or_b32 v20, v20, s33, v2
	s_waitcnt lgkmcnt(3)
	v_bfe_u32 v2, v92, 16, 1
	v_add3_u32 v2, v92, v2, s93
	s_waitcnt lgkmcnt(2)
	v_bfe_u32 v21, v94, 16, 1
	ds_read2_b32 v[100:101], v81 offset0:198 offset1:206
	v_lshrrev_b32_e32 v2, 16, v2
	v_add3_u32 v21, v94, v21, s93
	ds_read2_b32 v[102:103], v81 offset0:231 offset1:239
	v_and_or_b32 v21, v21, s33, v2
	s_waitcnt lgkmcnt(3)
	v_bfe_u32 v2, v96, 16, 1
	v_add3_u32 v2, v96, v2, s93
	s_waitcnt lgkmcnt(2)
	v_bfe_u32 v22, v98, 16, 1
	v_lshrrev_b32_e32 v2, 16, v2
	v_add3_u32 v22, v98, v22, s93
	v_and_or_b32 v22, v22, s33, v2
	s_waitcnt lgkmcnt(1)
	v_bfe_u32 v2, v100, 16, 1
	v_add3_u32 v2, v100, v2, s93
	s_waitcnt lgkmcnt(0)
	v_bfe_u32 v23, v102, 16, 1
	v_lshrrev_b32_e32 v2, 16, v2
	v_add3_u32 v23, v102, v23, s93
	s_lshl_b32 s46, s30, 1
	v_and_or_b32 v23, v23, s33, v2
	v_or_b32_e32 v2, s28, v80
	v_lshl_add_u64 v[88:89], v[8:9], 0, s[46:47]
	v_lshlrev_b32_e32 v2, 11, v2
	v_lshl_add_u64 v[104:105], v[88:89], 0, v[2:3]
	v_bfe_u32 v2, v87, 16, 1
	global_store_dwordx4 v[104:105], v[20:23], off
	v_add3_u32 v2, v87, v2, s93
	v_lshrrev_b32_e32 v2, 16, v2
	v_bfe_u32 v20, v91, 16, 1
	v_add3_u32 v20, v91, v20, s93
	v_and_or_b32 v20, v20, s33, v2
	v_bfe_u32 v2, v93, 16, 1
	v_add3_u32 v2, v93, v2, s93
	v_bfe_u32 v21, v95, 16, 1
	v_lshrrev_b32_e32 v2, 16, v2
	v_add3_u32 v21, v95, v21, s93
	v_and_or_b32 v21, v21, s33, v2
	v_bfe_u32 v2, v97, 16, 1
	v_add3_u32 v2, v97, v2, s93
	v_bfe_u32 v22, v99, 16, 1
	v_lshrrev_b32_e32 v2, 16, v2
	v_add3_u32 v22, v99, v22, s93
	v_and_or_b32 v22, v22, s33, v2
	v_bfe_u32 v2, v101, 16, 1
	v_add3_u32 v2, v101, v2, s93
	v_bfe_u32 v23, v103, 16, 1
	v_lshrrev_b32_e32 v2, 16, v2
	v_add3_u32 v23, v103, v23, s93
	v_and_or_b32 v23, v23, s33, v2
	v_or_b32_e32 v2, s28, v82
	v_lshlrev_b32_e32 v2, 11, v2
	ds_read2_b32 v[86:87], v81 offset0:16 offset1:24
	v_lshl_add_u64 v[90:91], v[88:89], 0, v[2:3]
	global_store_dwordx4 v[90:91], v[20:23], off
	ds_read2_b32 v[90:91], v81 offset0:49 offset1:57
	ds_read2_b32 v[92:93], v81 offset0:82 offset1:90
	ds_read2_b32 v[94:95], v81 offset0:115 offset1:123
	s_waitcnt lgkmcnt(3)
	v_bfe_u32 v2, v86, 16, 1
	v_add3_u32 v2, v86, v2, s93
	s_waitcnt lgkmcnt(2)
	v_bfe_u32 v20, v90, 16, 1
	ds_read2_b32 v[96:97], v81 offset0:148 offset1:156
	v_lshrrev_b32_e32 v2, 16, v2
	v_add3_u32 v20, v90, v20, s93
	ds_read2_b32 v[98:99], v81 offset0:181 offset1:189
	v_and_or_b32 v20, v20, s33, v2
	s_waitcnt lgkmcnt(3)
	v_bfe_u32 v2, v92, 16, 1
	v_add3_u32 v2, v92, v2, s93
	s_waitcnt lgkmcnt(2)
	v_bfe_u32 v21, v94, 16, 1
	ds_read2_b32 v[100:101], v81 offset0:214 offset1:222
	v_lshrrev_b32_e32 v2, 16, v2
	v_add3_u32 v21, v94, v21, s93
	ds_read2_b32 v[102:103], v81 offset0:247 offset1:255
	v_and_or_b32 v21, v21, s33, v2
	s_waitcnt lgkmcnt(3)
	v_bfe_u32 v2, v96, 16, 1
	v_add3_u32 v2, v96, v2, s93
	s_waitcnt lgkmcnt(2)
	v_bfe_u32 v22, v98, 16, 1
	v_lshrrev_b32_e32 v2, 16, v2
	v_add3_u32 v22, v98, v22, s93
	v_and_or_b32 v22, v22, s33, v2
	s_waitcnt lgkmcnt(1)
	v_bfe_u32 v2, v100, 16, 1
	v_add3_u32 v2, v100, v2, s93
	s_waitcnt lgkmcnt(0)
	v_bfe_u32 v23, v102, 16, 1
	v_lshrrev_b32_e32 v2, 16, v2
	v_add3_u32 v23, v102, v23, s93
	v_and_or_b32 v23, v23, s33, v2
	v_or_b32_e32 v2, s28, v83
	v_lshlrev_b32_e32 v2, 11, v2
	v_lshl_add_u64 v[104:105], v[88:89], 0, v[2:3]
	v_bfe_u32 v2, v87, 16, 1
	global_store_dwordx4 v[104:105], v[20:23], off
	v_add3_u32 v2, v87, v2, s93
	v_lshrrev_b32_e32 v2, 16, v2
	v_bfe_u32 v20, v91, 16, 1
	v_add3_u32 v20, v91, v20, s93
	v_and_or_b32 v20, v20, s33, v2
	v_bfe_u32 v2, v93, 16, 1
	v_add3_u32 v2, v93, v2, s93
	v_bfe_u32 v21, v95, 16, 1
	v_lshrrev_b32_e32 v2, 16, v2
	v_add3_u32 v21, v95, v21, s93
	v_and_or_b32 v21, v21, s33, v2
	v_bfe_u32 v2, v97, 16, 1
	v_add3_u32 v2, v97, v2, s93
	v_bfe_u32 v22, v99, 16, 1
	v_lshrrev_b32_e32 v2, 16, v2
	v_add3_u32 v22, v99, v22, s93
	v_and_or_b32 v22, v22, s33, v2
	v_bfe_u32 v2, v101, 16, 1
	v_add3_u32 v2, v101, v2, s93
	v_bfe_u32 v23, v103, 16, 1
	v_lshrrev_b32_e32 v2, 16, v2
	v_add3_u32 v23, v103, v23, s93
	v_and_or_b32 v23, v23, s33, v2
	v_or_b32_e32 v2, s28, v84
	v_lshlrev_b32_e32 v2, 11, v2
	v_lshl_add_u64 v[86:87], v[88:89], 0, v[2:3]
	global_store_dwordx4 v[86:87], v[20:23], off
	s_waitcnt lgkmcnt(0)
	s_mov_b64 s[30:31], 0x4000

.LBB0_1745:
	s_andn2_b64 vcc, exec, s[4:5]
	s_cbranch_vccnz .LBB0_1811
	s_load_dwordx2 s[4:5], s[62:63], 0x88
	s_load_dwordx2 s[26:27], s[62:63], 0xa0
	v_lshlrev_b32_e32 v2, 2, v4
	s_waitcnt lgkmcnt(0)
	s_add_u32 s6, s4, 0x1000
	s_addc_u32 s7, s5, 0
	s_lshl_b32 s28, s29, 1
	s_lshl_b32 s30, s29, 5
	s_add_i32 s28, s28, 0x1ea00
	s_and_b32 s30, s30, 0x3e0
	s_and_b32 s28, s28, 0x1ffc0
	s_lshl_b32 s31, s30, 2
	s_add_u32 s26, s26, s31
	s_addc_u32 s27, s27, 0
	v_lshl_add_u64 v[20:21], s[26:27], 0, v[2:3]
	v_or_b32_e32 v22, s28, v1
	v_lshl_add_u64 v[20:21], v[20:21], 0, s[96:97]
	v_lshlrev_b32_e32 v2, 12, v22
	v_lshl_add_u64 v[86:87], v[20:21], 0, v[2:3]
	s_cmp_eq_u64 s[4:5], 0
	s_cbranch_scc1 .Lladder_ng_5
	global_load_dword v88, v[86:87], off
	v_lshlrev_b32_e32 v22, 2, v22
	global_load_dword v89, v22, s[6:7]
	v_or_b32_e32 v22, s28, v25
	v_lshlrev_b32_e32 v2, 12, v22
	v_lshl_add_u64 v[86:87], v[20:21], 0, v[2:3]
	global_load_dword v90, v[86:87], off
	v_lshlrev_b32_e32 v22, 2, v22
	global_load_dword v91, v22, s[6:7]
	v_or_b32_e32 v22, s28, v27
	v_lshlrev_b32_e32 v2, 12, v22
	v_lshl_add_u64 v[86:87], v[20:21], 0, v[2:3]
	global_load_dword v92, v[86:87], off
	v_lshlrev_b32_e32 v22, 2, v22
	global_load_dword v93, v22, s[6:7]
	v_or_b32_e32 v22, s28, v29
	v_lshlrev_b32_e32 v2, 12, v22
	v_lshl_add_u64 v[86:87], v[20:21], 0, v[2:3]
	global_load_dword v94, v[86:87], off
	v_lshlrev_b32_e32 v22, 2, v22
	global_load_dword v95, v22, s[6:7]
	v_or_b32_e32 v22, s28, v31
	v_lshlrev_b32_e32 v2, 12, v22
	v_lshl_add_u64 v[86:87], v[20:21], 0, v[2:3]
	global_load_dword v96, v[86:87], off
	v_lshlrev_b32_e32 v22, 2, v22
	global_load_dword v97, v22, s[6:7]
	v_or_b32_e32 v22, s28, v33
	v_lshlrev_b32_e32 v2, 12, v22
	v_lshl_add_u64 v[86:87], v[20:21], 0, v[2:3]
	global_load_dword v98, v[86:87], off
	v_lshlrev_b32_e32 v22, 2, v22
	global_load_dword v99, v22, s[6:7]
	v_or_b32_e32 v22, s28, v35
	v_lshlrev_b32_e32 v2, 12, v22
	v_lshl_add_u64 v[86:87], v[20:21], 0, v[2:3]
	global_load_dword v100, v[86:87], off
	v_lshlrev_b32_e32 v22, 2, v22
	global_load_dword v101, v22, s[6:7]
	v_or_b32_e32 v22, s28, v37
	v_lshlrev_b32_e32 v2, 12, v22
	v_lshl_add_u64 v[86:87], v[20:21], 0, v[2:3]
	global_load_dword v102, v[86:87], off
	v_lshlrev_b32_e32 v22, 2, v22
	global_load_dword v103, v22, s[6:7]
	v_or_b32_e32 v22, s28, v39
	v_lshlrev_b32_e32 v2, 12, v22
	v_lshl_add_u64 v[86:87], v[20:21], 0, v[2:3]
	global_load_dword v104, v[86:87], off
	v_lshlrev_b32_e32 v22, 2, v22
	global_load_dword v105, v22, s[6:7]
	v_or_b32_e32 v22, s28, v41
	v_lshlrev_b32_e32 v2, 12, v22
	v_lshl_add_u64 v[86:87], v[20:21], 0, v[2:3]
	global_load_dword v148, v[86:87], off
	v_lshlrev_b32_e32 v22, 2, v22
	global_load_dword v149, v22, s[6:7]
	v_or_b32_e32 v22, s28, v43
	v_lshlrev_b32_e32 v2, 12, v22
	v_lshl_add_u64 v[86:87], v[20:21], 0, v[2:3]
	global_load_dword v150, v[86:87], off
	v_lshlrev_b32_e32 v22, 2, v22
	global_load_dword v151, v22, s[6:7]
	v_or_b32_e32 v22, s28, v45
	v_lshlrev_b32_e32 v2, 12, v22
	v_lshl_add_u64 v[86:87], v[20:21], 0, v[2:3]
	global_load_dword v152, v[86:87], off
	v_lshlrev_b32_e32 v22, 2, v22
	global_load_dword v153, v22, s[6:7]
	v_or_b32_e32 v22, s28, v47
	v_lshlrev_b32_e32 v2, 12, v22
	v_lshl_add_u64 v[86:87], v[20:21], 0, v[2:3]
	global_load_dword v154, v[86:87], off
	v_lshlrev_b32_e32 v22, 2, v22
	global_load_dword v155, v22, s[6:7]
	v_or_b32_e32 v22, s28, v49
	v_lshlrev_b32_e32 v2, 12, v22
	v_lshl_add_u64 v[86:87], v[20:21], 0, v[2:3]
	global_load_dword v156, v[86:87], off
	v_lshlrev_b32_e32 v22, 2, v22
	global_load_dword v157, v22, s[6:7]
	v_or_b32_e32 v22, s28, v51
	v_lshlrev_b32_e32 v2, 12, v22
	v_lshl_add_u64 v[86:87], v[20:21], 0, v[2:3]
	global_load_dword v158, v[86:87], off
	v_lshlrev_b32_e32 v22, 2, v22
	global_load_dword v159, v22, s[6:7]
	v_or_b32_e32 v22, s28, v53
	v_lshlrev_b32_e32 v2, 12, v22
	v_lshl_add_u64 v[86:87], v[20:21], 0, v[2:3]
	global_load_dword v160, v[86:87], off
	v_lshlrev_b32_e32 v22, 2, v22
	global_load_dword v161, v22, s[6:7]
	v_or_b32_e32 v22, s28, v55
	v_lshlrev_b32_e32 v2, 12, v22
	v_lshl_add_u64 v[86:87], v[20:21], 0, v[2:3]
	global_load_dword v162, v[86:87], off
	v_lshlrev_b32_e32 v22, 2, v22
	global_load_dword v163, v22, s[6:7]
	v_or_b32_e32 v22, s28, v57
	v_lshlrev_b32_e32 v2, 12, v22
	v_lshl_add_u64 v[86:87], v[20:21], 0, v[2:3]
	global_load_dword v165, v[86:87], off
	v_lshlrev_b32_e32 v22, 2, v22
	global_load_dword v166, v22, s[6:7]
	v_or_b32_e32 v22, s28, v59
	v_lshlrev_b32_e32 v2, 12, v22
	v_lshl_add_u64 v[86:87], v[20:21], 0, v[2:3]
	global_load_dword v167, v[86:87], off
	v_lshlrev_b32_e32 v22, 2, v22
	global_load_dword v168, v22, s[6:7]
	v_or_b32_e32 v22, s28, v61
	v_lshlrev_b32_e32 v2, 12, v22
	v_lshl_add_u64 v[86:87], v[20:21], 0, v[2:3]
	global_load_dword v169, v[86:87], off
	v_lshlrev_b32_e32 v22, 2, v22
	global_load_dword v170, v22, s[6:7]
	v_or_b32_e32 v22, s28, v63
	v_lshlrev_b32_e32 v2, 12, v22
	v_lshl_add_u64 v[86:87], v[20:21], 0, v[2:3]
	global_load_dword v171, v[86:87], off
	v_lshlrev_b32_e32 v22, 2, v22
	global_load_dword v172, v22, s[6:7]
	v_or_b32_e32 v22, s28, v65
	v_lshlrev_b32_e32 v2, 12, v22
	v_lshl_add_u64 v[86:87], v[20:21], 0, v[2:3]
	global_load_dword v173, v[86:87], off
	v_lshlrev_b32_e32 v22, 2, v22
	global_load_dword v174, v22, s[6:7]
	v_or_b32_e32 v22, s28, v67
	v_lshlrev_b32_e32 v2, 12, v22
	v_lshl_add_u64 v[86:87], v[20:21], 0, v[2:3]
	global_load_dword v175, v[86:87], off
	v_lshlrev_b32_e32 v22, 2, v22
	global_load_dword v176, v22, s[6:7]
	v_or_b32_e32 v22, s28, v69
	v_lshlrev_b32_e32 v2, 12, v22
	v_lshl_add_u64 v[86:87], v[20:21], 0, v[2:3]
	global_load_dword v177, v[86:87], off
	v_lshlrev_b32_e32 v22, 2, v22
	global_load_dword v178, v22, s[6:7]
	v_or_b32_e32 v22, s28, v71
	v_lshlrev_b32_e32 v2, 12, v22
	v_lshl_add_u64 v[86:87], v[20:21], 0, v[2:3]
	global_load_dword v179, v[86:87], off
	v_lshlrev_b32_e32 v2, 2, v22
	global_load_dword v180, v2, s[6:7]
	v_or_b32_e32 v85, s28, v73
	v_lshlrev_b32_e32 v2, 12, v85
	v_lshl_add_u64 v[86:87], v[20:21], 0, v[2:3]
	global_load_dword v181, v[86:87], off
	v_lshlrev_b32_e32 v23, 2, v85
	global_load_dword v182, v23, s[6:7]
	v_or_b32_e32 v23, s28, v74
	v_lshlrev_b32_e32 v2, 12, v23
	v_lshl_add_u64 v[86:87], v[20:21], 0, v[2:3]
	global_load_dword v183, v[86:87], off
	v_lshlrev_b32_e32 v23, 2, v23
	global_load_dword v184, v23, s[6:7]
	v_or_b32_e32 v23, s28, v75
	v_lshlrev_b32_e32 v2, 12, v23
	v_lshl_add_u64 v[86:87], v[20:21], 0, v[2:3]
	global_load_dword v185, v[86:87], off
	v_lshlrev_b32_e32 v23, 2, v23
	global_load_dword v186, v23, s[6:7]
	v_or_b32_e32 v23, s28, v76
	v_lshlrev_b32_e32 v2, 12, v23
	v_lshl_add_u64 v[86:87], v[20:21], 0, v[2:3]
	global_load_dword v187, v[86:87], off
	v_lshlrev_b32_e32 v23, 2, v23
	global_load_dword v188, v23, s[6:7]
	v_or_b32_e32 v23, s28, v77
	v_lshlrev_b32_e32 v2, 12, v23
	v_lshl_add_u64 v[86:87], v[20:21], 0, v[2:3]
	global_load_dword v189, v[86:87], off
	v_lshlrev_b32_e32 v23, 2, v23
	global_load_dword v190, v23, s[6:7]
	v_or_b32_e32 v23, s28, v78
	v_lshlrev_b32_e32 v2, 12, v23
	v_lshl_add_u64 v[86:87], v[20:21], 0, v[2:3]
	global_load_dword v191, v[86:87], off
	v_lshlrev_b32_e32 v23, 2, v23
	global_load_dword v192, v23, s[6:7]
	v_or_b32_e32 v23, s28, v79
	v_lshlrev_b32_e32 v2, 12, v23
	v_lshl_add_u64 v[20:21], v[20:21], 0, v[2:3]
	global_load_dword v193, v[20:21], off
	v_lshlrev_b32_e32 v20, 2, v23
	global_load_dword v194, v20, s[6:7]
	s_waitcnt vmcnt(0)
	v_mul_f32_e32 v88, v88, v89
	v_add_u32_e32 v195, v5, v24
	ds_write_b32 v195, v88
	v_mul_f32_e32 v90, v90, v91
	v_add_u32_e32 v196, v5, v26
	ds_write_b32 v196, v90
	v_mul_f32_e32 v92, v92, v93
	v_add_u32_e32 v197, v5, v28
	ds_write_b32 v197, v92
	v_mul_f32_e32 v94, v94, v95
	v_add_u32_e32 v198, v5, v30
	ds_write_b32 v198, v94
	v_mul_f32_e32 v96, v96, v97
	v_add_u32_e32 v199, v5, v32
	ds_write_b32 v199, v96
	v_mul_f32_e32 v98, v98, v99
	v_add_u32_e32 v200, v5, v34
	ds_write_b32 v200, v98
	v_mul_f32_e32 v100, v100, v101
	v_add_u32_e32 v201, v5, v36
	ds_write_b32 v201, v100
	v_mul_f32_e32 v102, v102, v103
	v_add_u32_e32 v202, v5, v38
	ds_write_b32 v202, v102
	v_mul_f32_e32 v104, v104, v105
	v_add_u32_e32 v203, v5, v40
	ds_write_b32 v203, v104
	v_mul_f32_e32 v148, v148, v149
	v_add_u32_e32 v204, v5, v42
	ds_write_b32 v204, v148
	v_mul_f32_e32 v150, v150, v151
	v_add_u32_e32 v205, v5, v44
	ds_write_b32 v205, v150
	v_mul_f32_e32 v152, v152, v153
	v_add_u32_e32 v206, v5, v46
	ds_write_b32 v206, v152
	v_mul_f32_e32 v154, v154, v155
	v_add_u32_e32 v207, v5, v48
	ds_write_b32 v207, v154
	v_mul_f32_e32 v156, v156, v157
	v_add_u32_e32 v210, v5, v50
	ds_write_b32 v210, v156
	v_mul_f32_e32 v158, v158, v159
	v_add_u32_e32 v211, v5, v52
	ds_write_b32 v211, v158
	v_mul_f32_e32 v160, v160, v161
	v_add_u32_e32 v212, v5, v54
	ds_write_b32 v212, v160
	v_mul_f32_e32 v162, v162, v163
	v_add_u32_e32 v213, v5, v56
	ds_write_b32 v213, v162
	v_mul_f32_e32 v165, v165, v166
	v_add_u32_e32 v217, v5, v58
	ds_write_b32 v217, v165
	v_mul_f32_e32 v167, v167, v168
	v_add_u32_e32 v218, v5, v60
	ds_write_b32 v218, v167
	v_mul_f32_e32 v169, v169, v170
	v_add_u32_e32 v219, v5, v62
	ds_write_b32 v219, v169
	v_mul_f32_e32 v171, v171, v172
	v_add_u32_e32 v220, v5, v64
	ds_write_b32 v220, v171
	v_mul_f32_e32 v173, v173, v174
	v_add_u32_e32 v221, v5, v66
	ds_write_b32 v221, v173
	v_mul_f32_e32 v175, v175, v176
	v_add_u32_e32 v222, v5, v68
	ds_write_b32 v222, v175
	v_mul_f32_e32 v177, v177, v178
	v_add_u32_e32 v223, v5, v70
	ds_write_b32 v223, v177
	v_mul_f32_e32 v179, v179, v180
	v_add_u32_e32 v224, v5, v72
	ds_write_b32 v224, v179
	v_mul_f32_e32 v181, v181, v182
	ds_write_b32 v224, v181 offset:264
	v_mul_f32_e32 v183, v183, v184
	ds_write_b32 v224, v183 offset:528
	v_mul_f32_e32 v185, v185, v186
	ds_write_b32 v224, v185 offset:792
	v_mul_f32_e32 v187, v187, v188
	ds_write_b32 v224, v187 offset:1056
	v_mul_f32_e32 v189, v189, v190
	ds_write_b32 v224, v189 offset:1320
	v_mul_f32_e32 v191, v191, v192
	ds_write_b32 v224, v191 offset:1584
	v_mul_f32_e32 v193, v193, v194
	ds_write_b32 v224, v193 offset:1848
	s_branch .Lladder_done_5
.Lladder_ng_5:
	global_load_dword v88, v[86:87], off
	v_or_b32_e32 v22, s28, v25
	v_lshlrev_b32_e32 v2, 12, v22
	v_lshl_add_u64 v[86:87], v[20:21], 0, v[2:3]
	global_load_dword v89, v[86:87], off
	v_or_b32_e32 v22, s28, v27
	v_lshlrev_b32_e32 v2, 12, v22
	v_lshl_add_u64 v[86:87], v[20:21], 0, v[2:3]
	global_load_dword v90, v[86:87], off
	v_or_b32_e32 v22, s28, v29
	v_lshlrev_b32_e32 v2, 12, v22
	v_lshl_add_u64 v[86:87], v[20:21], 0, v[2:3]
	global_load_dword v91, v[86:87], off
	v_or_b32_e32 v22, s28, v31
	v_lshlrev_b32_e32 v2, 12, v22
	v_lshl_add_u64 v[86:87], v[20:21], 0, v[2:3]
	global_load_dword v92, v[86:87], off
	v_or_b32_e32 v22, s28, v33
	v_lshlrev_b32_e32 v2, 12, v22
	v_lshl_add_u64 v[86:87], v[20:21], 0, v[2:3]
	global_load_dword v93, v[86:87], off
	v_or_b32_e32 v22, s28, v35
	v_lshlrev_b32_e32 v2, 12, v22
	v_lshl_add_u64 v[86:87], v[20:21], 0, v[2:3]
	global_load_dword v94, v[86:87], off
	v_or_b32_e32 v22, s28, v37
	v_lshlrev_b32_e32 v2, 12, v22
	v_lshl_add_u64 v[86:87], v[20:21], 0, v[2:3]
	global_load_dword v95, v[86:87], off
	v_or_b32_e32 v22, s28, v39
	v_lshlrev_b32_e32 v2, 12, v22
	v_lshl_add_u64 v[86:87], v[20:21], 0, v[2:3]
	global_load_dword v96, v[86:87], off
	v_or_b32_e32 v22, s28, v41
	v_lshlrev_b32_e32 v2, 12, v22
	v_lshl_add_u64 v[86:87], v[20:21], 0, v[2:3]
	global_load_dword v97, v[86:87], off
	v_or_b32_e32 v22, s28, v43
	v_lshlrev_b32_e32 v2, 12, v22
	v_lshl_add_u64 v[86:87], v[20:21], 0, v[2:3]
	global_load_dword v98, v[86:87], off
	v_or_b32_e32 v22, s28, v45
	v_lshlrev_b32_e32 v2, 12, v22
	v_lshl_add_u64 v[86:87], v[20:21], 0, v[2:3]
	global_load_dword v99, v[86:87], off
	v_or_b32_e32 v22, s28, v47
	v_lshlrev_b32_e32 v2, 12, v22
	v_lshl_add_u64 v[86:87], v[20:21], 0, v[2:3]
	global_load_dword v100, v[86:87], off
	v_or_b32_e32 v22, s28, v49
	v_lshlrev_b32_e32 v2, 12, v22
	v_lshl_add_u64 v[86:87], v[20:21], 0, v[2:3]
	global_load_dword v101, v[86:87], off
	v_or_b32_e32 v22, s28, v51
	v_lshlrev_b32_e32 v2, 12, v22
	v_lshl_add_u64 v[86:87], v[20:21], 0, v[2:3]
	global_load_dword v102, v[86:87], off
	v_or_b32_e32 v22, s28, v53
	v_lshlrev_b32_e32 v2, 12, v22
	v_lshl_add_u64 v[86:87], v[20:21], 0, v[2:3]
	global_load_dword v103, v[86:87], off
	v_or_b32_e32 v22, s28, v55
	v_lshlrev_b32_e32 v2, 12, v22
	v_lshl_add_u64 v[86:87], v[20:21], 0, v[2:3]
	global_load_dword v104, v[86:87], off
	v_or_b32_e32 v22, s28, v57
	v_lshlrev_b32_e32 v2, 12, v22
	v_lshl_add_u64 v[86:87], v[20:21], 0, v[2:3]
	global_load_dword v105, v[86:87], off
	v_or_b32_e32 v22, s28, v59
	v_lshlrev_b32_e32 v2, 12, v22
	v_lshl_add_u64 v[86:87], v[20:21], 0, v[2:3]
	global_load_dword v148, v[86:87], off
	v_or_b32_e32 v22, s28, v61
	v_lshlrev_b32_e32 v2, 12, v22
	v_lshl_add_u64 v[86:87], v[20:21], 0, v[2:3]
	global_load_dword v149, v[86:87], off
	v_or_b32_e32 v22, s28, v63
	v_lshlrev_b32_e32 v2, 12, v22
	v_lshl_add_u64 v[86:87], v[20:21], 0, v[2:3]
	global_load_dword v150, v[86:87], off
	v_or_b32_e32 v22, s28, v65
	v_lshlrev_b32_e32 v2, 12, v22
	v_lshl_add_u64 v[86:87], v[20:21], 0, v[2:3]
	global_load_dword v151, v[86:87], off
	v_or_b32_e32 v22, s28, v67
	v_lshlrev_b32_e32 v2, 12, v22
	v_lshl_add_u64 v[86:87], v[20:21], 0, v[2:3]
	global_load_dword v152, v[86:87], off
	v_or_b32_e32 v22, s28, v69
	v_lshlrev_b32_e32 v2, 12, v22
	v_lshl_add_u64 v[86:87], v[20:21], 0, v[2:3]
	global_load_dword v153, v[86:87], off
	v_or_b32_e32 v22, s28, v71
	v_lshlrev_b32_e32 v2, 12, v22
	v_lshl_add_u64 v[86:87], v[20:21], 0, v[2:3]
	global_load_dword v154, v[86:87], off
	v_or_b32_e32 v85, s28, v73
	v_lshlrev_b32_e32 v2, 12, v85
	v_lshl_add_u64 v[86:87], v[20:21], 0, v[2:3]
	global_load_dword v155, v[86:87], off
	v_or_b32_e32 v23, s28, v74
	v_lshlrev_b32_e32 v2, 12, v23
	v_lshl_add_u64 v[86:87], v[20:21], 0, v[2:3]
	global_load_dword v156, v[86:87], off
	v_or_b32_e32 v23, s28, v75
	v_lshlrev_b32_e32 v2, 12, v23
	v_lshl_add_u64 v[86:87], v[20:21], 0, v[2:3]
	global_load_dword v157, v[86:87], off
	v_or_b32_e32 v23, s28, v76
	v_lshlrev_b32_e32 v2, 12, v23
	v_lshl_add_u64 v[86:87], v[20:21], 0, v[2:3]
	global_load_dword v158, v[86:87], off
	v_or_b32_e32 v23, s28, v77
	v_lshlrev_b32_e32 v2, 12, v23
	v_lshl_add_u64 v[86:87], v[20:21], 0, v[2:3]
	global_load_dword v159, v[86:87], off
	v_or_b32_e32 v23, s28, v78
	v_lshlrev_b32_e32 v2, 12, v23
	v_lshl_add_u64 v[86:87], v[20:21], 0, v[2:3]
	global_load_dword v160, v[86:87], off
	v_or_b32_e32 v23, s28, v79
	v_lshlrev_b32_e32 v2, 12, v23
	v_lshl_add_u64 v[20:21], v[20:21], 0, v[2:3]
	global_load_dword v161, v[20:21], off
	s_waitcnt vmcnt(0)
	v_add_u32_e32 v162, v5, v24
	ds_write_b32 v162, v88
	v_add_u32_e32 v163, v5, v26
	ds_write_b32 v163, v89
	v_add_u32_e32 v165, v5, v28
	ds_write_b32 v165, v90
	v_add_u32_e32 v166, v5, v30
	ds_write_b32 v166, v91
	v_add_u32_e32 v167, v5, v32
	ds_write_b32 v167, v92
	v_add_u32_e32 v168, v5, v34
	ds_write_b32 v168, v93
	v_add_u32_e32 v169, v5, v36
	ds_write_b32 v169, v94
	v_add_u32_e32 v170, v5, v38
	ds_write_b32 v170, v95
	v_add_u32_e32 v171, v5, v40
	ds_write_b32 v171, v96
	v_add_u32_e32 v172, v5, v42
	ds_write_b32 v172, v97
	v_add_u32_e32 v173, v5, v44
	ds_write_b32 v173, v98
	v_add_u32_e32 v174, v5, v46
	ds_write_b32 v174, v99
	v_add_u32_e32 v175, v5, v48
	ds_write_b32 v175, v100
	v_add_u32_e32 v176, v5, v50
	ds_write_b32 v176, v101
	v_add_u32_e32 v177, v5, v52
	ds_write_b32 v177, v102
	v_add_u32_e32 v178, v5, v54
	ds_write_b32 v178, v103
	v_add_u32_e32 v179, v5, v56
	ds_write_b32 v179, v104
	v_add_u32_e32 v180, v5, v58
	ds_write_b32 v180, v105
	v_add_u32_e32 v181, v5, v60
	ds_write_b32 v181, v148
	v_add_u32_e32 v182, v5, v62
	ds_write_b32 v182, v149
	v_add_u32_e32 v183, v5, v64
	ds_write_b32 v183, v150
	v_add_u32_e32 v184, v5, v66
	ds_write_b32 v184, v151
	v_add_u32_e32 v185, v5, v68
	ds_write_b32 v185, v152
	v_add_u32_e32 v186, v5, v70
	ds_write_b32 v186, v153
	v_add_u32_e32 v187, v5, v72
	ds_write_b32 v187, v154
	ds_write_b32 v187, v155 offset:264
	ds_write_b32 v187, v156 offset:528
	ds_write_b32 v187, v157 offset:792
	ds_write_b32 v187, v158 offset:1056
	ds_write_b32 v187, v159 offset:1320
	ds_write_b32 v187, v160 offset:1584
	ds_write_b32 v187, v161 offset:1848
.Lladder_done_5:
	s_waitcnt lgkmcnt(0)
	ds_read2_b32 v[86:87], v81 offset1:8
	ds_read2_b32 v[90:91], v81 offset0:33 offset1:41
	ds_read2_b32 v[92:93], v81 offset0:66 offset1:74
	ds_read2_b32 v[94:95], v81 offset0:99 offset1:107
	ds_read2_b32 v[96:97], v81 offset0:132 offset1:140
	s_waitcnt lgkmcnt(4)
	v_bfe_u32 v2, v86, 16, 1
	v_add3_u32 v2, v86, v2, s93
	s_waitcnt lgkmcnt(3)
	v_bfe_u32 v20, v90, 16, 1
	v_lshrrev_b32_e32 v2, 16, v2
	v_add3_u32 v20, v90, v20, s93
	ds_read2_b32 v[98:99], v81 offset0:165 offset1:173
	v_and_or_b32 v20, v20, s33, v2
	s_waitcnt lgkmcnt(3)
	v_bfe_u32 v2, v92, 16, 1
	v_add3_u32 v2, v92, v2, s93
	s_waitcnt lgkmcnt(2)
	v_bfe_u32 v21, v94, 16, 1
	ds_read2_b32 v[100:101], v81 offset0:198 offset1:206
	v_lshrrev_b32_e32 v2, 16, v2
	v_add3_u32 v21, v94, v21, s93
	ds_read2_b32 v[102:103], v81 offset0:231 offset1:239
	v_and_or_b32 v21, v21, s33, v2
	s_waitcnt lgkmcnt(3)
	v_bfe_u32 v2, v96, 16, 1
	v_add3_u32 v2, v96, v2, s93
	s_waitcnt lgkmcnt(2)
	v_bfe_u32 v22, v98, 16, 1
	v_lshrrev_b32_e32 v2, 16, v2
	v_add3_u32 v22, v98, v22, s93
	v_and_or_b32 v22, v22, s33, v2
	s_waitcnt lgkmcnt(1)
	v_bfe_u32 v2, v100, 16, 1
	v_add3_u32 v2, v100, v2, s93
	s_waitcnt lgkmcnt(0)
	v_bfe_u32 v23, v102, 16, 1
	s_or_b32 s4, s30, 0xc00
	v_lshrrev_b32_e32 v2, 16, v2
	v_add3_u32 v23, v102, v23, s93
	s_lshl_b32 s46, s28, 1
	v_and_or_b32 v23, v23, s33, v2
	v_or_b32_e32 v2, s4, v80
	v_lshl_add_u64 v[88:89], v[10:11], 0, s[46:47]
	v_lshlrev_b32_e32 v2, 11, v2
	v_lshl_add_u64 v[104:105], v[88:89], 0, v[2:3]
	v_bfe_u32 v2, v87, 16, 1
	global_store_dwordx4 v[104:105], v[20:23], off
	v_add3_u32 v2, v87, v2, s93
	v_lshrrev_b32_e32 v2, 16, v2
	v_bfe_u32 v20, v91, 16, 1
	v_add3_u32 v20, v91, v20, s93
	v_and_or_b32 v20, v20, s33, v2
	v_bfe_u32 v2, v93, 16, 1
	v_add3_u32 v2, v93, v2, s93
	v_bfe_u32 v21, v95, 16, 1
	v_lshrrev_b32_e32 v2, 16, v2
	v_add3_u32 v21, v95, v21, s93
	v_and_or_b32 v21, v21, s33, v2
	v_bfe_u32 v2, v97, 16, 1
	v_add3_u32 v2, v97, v2, s93
	v_bfe_u32 v22, v99, 16, 1
	v_lshrrev_b32_e32 v2, 16, v2
	v_add3_u32 v22, v99, v22, s93
	v_and_or_b32 v22, v22, s33, v2
	v_bfe_u32 v2, v101, 16, 1
	v_add3_u32 v2, v101, v2, s93
	v_bfe_u32 v23, v103, 16, 1
	v_lshrrev_b32_e32 v2, 16, v2
	v_add3_u32 v23, v103, v23, s93
	v_and_or_b32 v23, v23, s33, v2
	v_or_b32_e32 v2, s4, v82
	v_lshlrev_b32_e32 v2, 11, v2
	ds_read2_b32 v[86:87], v81 offset0:16 offset1:24
	v_lshl_add_u64 v[90:91], v[88:89], 0, v[2:3]
	global_store_dwordx4 v[90:91], v[20:23], off
	ds_read2_b32 v[90:91], v81 offset0:49 offset1:57
	ds_read2_b32 v[92:93], v81 offset0:82 offset1:90
	ds_read2_b32 v[94:95], v81 offset0:115 offset1:123
	s_waitcnt lgkmcnt(3)
	v_bfe_u32 v2, v86, 16, 1
	v_add3_u32 v2, v86, v2, s93
	s_waitcnt lgkmcnt(2)
	v_bfe_u32 v20, v90, 16, 1
	ds_read2_b32 v[96:97], v81 offset0:148 offset1:156
	v_lshrrev_b32_e32 v2, 16, v2
	v_add3_u32 v20, v90, v20, s93
	ds_read2_b32 v[98:99], v81 offset0:181 offset1:189
	v_and_or_b32 v20, v20, s33, v2
	s_waitcnt lgkmcnt(3)
	v_bfe_u32 v2, v92, 16, 1
	v_add3_u32 v2, v92, v2, s93
	s_waitcnt lgkmcnt(2)
	v_bfe_u32 v21, v94, 16, 1
	ds_read2_b32 v[100:101], v81 offset0:214 offset1:222
	v_lshrrev_b32_e32 v2, 16, v2
	v_add3_u32 v21, v94, v21, s93
	ds_read2_b32 v[102:103], v81 offset0:247 offset1:255
	v_and_or_b32 v21, v21, s33, v2
	s_waitcnt lgkmcnt(3)
	v_bfe_u32 v2, v96, 16, 1
	v_add3_u32 v2, v96, v2, s93
	s_waitcnt lgkmcnt(2)
	v_bfe_u32 v22, v98, 16, 1
	v_lshrrev_b32_e32 v2, 16, v2
	v_add3_u32 v22, v98, v22, s93
	v_and_or_b32 v22, v22, s33, v2
	s_waitcnt lgkmcnt(1)
	v_bfe_u32 v2, v100, 16, 1
	v_add3_u32 v2, v100, v2, s93
	s_waitcnt lgkmcnt(0)
	v_bfe_u32 v23, v102, 16, 1
	v_lshrrev_b32_e32 v2, 16, v2
	v_add3_u32 v23, v102, v23, s93
	v_and_or_b32 v23, v23, s33, v2
	v_or_b32_e32 v2, s4, v83
	v_lshlrev_b32_e32 v2, 11, v2
	v_lshl_add_u64 v[104:105], v[88:89], 0, v[2:3]
	v_bfe_u32 v2, v87, 16, 1
	global_store_dwordx4 v[104:105], v[20:23], off
	v_add3_u32 v2, v87, v2, s93
	v_lshrrev_b32_e32 v2, 16, v2
	v_bfe_u32 v20, v91, 16, 1
	v_add3_u32 v20, v91, v20, s93
	v_and_or_b32 v20, v20, s33, v2
	v_bfe_u32 v2, v93, 16, 1
	v_add3_u32 v2, v93, v2, s93
	v_bfe_u32 v21, v95, 16, 1
	v_lshrrev_b32_e32 v2, 16, v2
	v_add3_u32 v21, v95, v21, s93
	v_and_or_b32 v21, v21, s33, v2
	v_bfe_u32 v2, v97, 16, 1
	v_add3_u32 v2, v97, v2, s93
	v_bfe_u32 v22, v99, 16, 1
	v_lshrrev_b32_e32 v2, 16, v2
	v_add3_u32 v22, v99, v22, s93
	v_and_or_b32 v22, v22, s33, v2
	v_bfe_u32 v2, v101, 16, 1
	v_add3_u32 v2, v101, v2, s93
	v_bfe_u32 v23, v103, 16, 1
	v_lshrrev_b32_e32 v2, 16, v2
	v_add3_u32 v23, v103, v23, s93
	v_and_or_b32 v23, v23, s33, v2
	v_or_b32_e32 v2, s4, v84
	v_lshlrev_b32_e32 v2, 11, v2
	v_lshl_add_u64 v[86:87], v[88:89], 0, v[2:3]
	global_store_dwordx4 v[86:87], v[20:23], off
	s_waitcnt lgkmcnt(0)
	s_mov_b64 s[30:31], 0x4000

.LBB0_1812:
	s_andn2_b64 vcc, exec, s[4:5]
	s_cbranch_vccnz .LBB0_1878
	s_load_dwordx2 s[4:5], s[62:63], 0x88
	s_load_dwordx2 s[26:27], s[62:63], 0x98
	v_lshlrev_b32_e32 v2, 2, v4
	s_waitcnt lgkmcnt(0)
	s_add_u32 s6, s4, 0x1000
	s_addc_u32 s7, s5, 0
	s_lshl_b32 s28, s29, 1
	s_lshl_b32 s30, s29, 5
	s_add_i32 s28, s28, 0x1ee00
	s_and_b32 s30, s30, 0x3e0
	s_and_b32 s28, s28, 0x1ffc0
	s_lshl_b32 s31, s30, 2
	s_add_u32 s26, s26, s31
	s_addc_u32 s27, s27, 0
	v_lshl_add_u64 v[20:21], s[26:27], 0, v[2:3]
	v_or_b32_e32 v22, s28, v1
	v_lshl_add_u64 v[20:21], v[20:21], 0, s[96:97]
	v_lshlrev_b32_e32 v2, 12, v22
	v_lshl_add_u64 v[86:87], v[20:21], 0, v[2:3]
	s_cmp_eq_u64 s[4:5], 0
	s_cbranch_scc1 .Lladder_ng_6
	global_load_dword v88, v[86:87], off
	v_lshlrev_b32_e32 v22, 2, v22
	global_load_dword v89, v22, s[6:7]
	v_or_b32_e32 v22, s28, v25
	v_lshlrev_b32_e32 v2, 12, v22
	v_lshl_add_u64 v[86:87], v[20:21], 0, v[2:3]
	global_load_dword v90, v[86:87], off
	v_lshlrev_b32_e32 v22, 2, v22
	global_load_dword v91, v22, s[6:7]
	v_or_b32_e32 v22, s28, v27
	v_lshlrev_b32_e32 v2, 12, v22
	v_lshl_add_u64 v[86:87], v[20:21], 0, v[2:3]
	global_load_dword v92, v[86:87], off
	v_lshlrev_b32_e32 v22, 2, v22
	global_load_dword v93, v22, s[6:7]
	v_or_b32_e32 v22, s28, v29
	v_lshlrev_b32_e32 v2, 12, v22
	v_lshl_add_u64 v[86:87], v[20:21], 0, v[2:3]
	global_load_dword v94, v[86:87], off
	v_lshlrev_b32_e32 v22, 2, v22
	global_load_dword v95, v22, s[6:7]
	v_or_b32_e32 v22, s28, v31
	v_lshlrev_b32_e32 v2, 12, v22
	v_lshl_add_u64 v[86:87], v[20:21], 0, v[2:3]
	global_load_dword v96, v[86:87], off
	v_lshlrev_b32_e32 v22, 2, v22
	global_load_dword v97, v22, s[6:7]
	v_or_b32_e32 v22, s28, v33
	v_lshlrev_b32_e32 v2, 12, v22
	v_lshl_add_u64 v[86:87], v[20:21], 0, v[2:3]
	global_load_dword v98, v[86:87], off
	v_lshlrev_b32_e32 v22, 2, v22
	global_load_dword v99, v22, s[6:7]
	v_or_b32_e32 v22, s28, v35
	v_lshlrev_b32_e32 v2, 12, v22
	v_lshl_add_u64 v[86:87], v[20:21], 0, v[2:3]
	global_load_dword v100, v[86:87], off
	v_lshlrev_b32_e32 v22, 2, v22
	global_load_dword v101, v22, s[6:7]
	v_or_b32_e32 v22, s28, v37
	v_lshlrev_b32_e32 v2, 12, v22
	v_lshl_add_u64 v[86:87], v[20:21], 0, v[2:3]
	global_load_dword v102, v[86:87], off
	v_lshlrev_b32_e32 v22, 2, v22
	global_load_dword v103, v22, s[6:7]
	v_or_b32_e32 v22, s28, v39
	v_lshlrev_b32_e32 v2, 12, v22
	v_lshl_add_u64 v[86:87], v[20:21], 0, v[2:3]
	global_load_dword v104, v[86:87], off
	v_lshlrev_b32_e32 v22, 2, v22
	global_load_dword v105, v22, s[6:7]
	v_or_b32_e32 v22, s28, v41
	v_lshlrev_b32_e32 v2, 12, v22
	v_lshl_add_u64 v[86:87], v[20:21], 0, v[2:3]
	global_load_dword v148, v[86:87], off
	v_lshlrev_b32_e32 v22, 2, v22
	global_load_dword v149, v22, s[6:7]
	v_or_b32_e32 v22, s28, v43
	v_lshlrev_b32_e32 v2, 12, v22
	v_lshl_add_u64 v[86:87], v[20:21], 0, v[2:3]
	global_load_dword v150, v[86:87], off
	v_lshlrev_b32_e32 v22, 2, v22
	global_load_dword v151, v22, s[6:7]
	v_or_b32_e32 v22, s28, v45
	v_lshlrev_b32_e32 v2, 12, v22
	v_lshl_add_u64 v[86:87], v[20:21], 0, v[2:3]
	global_load_dword v152, v[86:87], off
	v_lshlrev_b32_e32 v22, 2, v22
	global_load_dword v153, v22, s[6:7]
	v_or_b32_e32 v22, s28, v47
	v_lshlrev_b32_e32 v2, 12, v22
	v_lshl_add_u64 v[86:87], v[20:21], 0, v[2:3]
	global_load_dword v154, v[86:87], off
	v_lshlrev_b32_e32 v22, 2, v22
	global_load_dword v155, v22, s[6:7]
	v_or_b32_e32 v22, s28, v49
	v_lshlrev_b32_e32 v2, 12, v22
	v_lshl_add_u64 v[86:87], v[20:21], 0, v[2:3]
	global_load_dword v156, v[86:87], off
	v_lshlrev_b32_e32 v22, 2, v22
	global_load_dword v157, v22, s[6:7]
	v_or_b32_e32 v22, s28, v51
	v_lshlrev_b32_e32 v2, 12, v22
	v_lshl_add_u64 v[86:87], v[20:21], 0, v[2:3]
	global_load_dword v158, v[86:87], off
	v_lshlrev_b32_e32 v22, 2, v22
	global_load_dword v159, v22, s[6:7]
	v_or_b32_e32 v22, s28, v53
	v_lshlrev_b32_e32 v2, 12, v22
	v_lshl_add_u64 v[86:87], v[20:21], 0, v[2:3]
	global_load_dword v160, v[86:87], off
	v_lshlrev_b32_e32 v22, 2, v22
	global_load_dword v161, v22, s[6:7]
	v_or_b32_e32 v22, s28, v55
	v_lshlrev_b32_e32 v2, 12, v22
	v_lshl_add_u64 v[86:87], v[20:21], 0, v[2:3]
	global_load_dword v162, v[86:87], off
	v_lshlrev_b32_e32 v22, 2, v22
	global_load_dword v163, v22, s[6:7]
	v_or_b32_e32 v22, s28, v57
	v_lshlrev_b32_e32 v2, 12, v22
	v_lshl_add_u64 v[86:87], v[20:21], 0, v[2:3]
	global_load_dword v165, v[86:87], off
	v_lshlrev_b32_e32 v22, 2, v22
	global_load_dword v166, v22, s[6:7]
	v_or_b32_e32 v22, s28, v59
	v_lshlrev_b32_e32 v2, 12, v22
	v_lshl_add_u64 v[86:87], v[20:21], 0, v[2:3]
	global_load_dword v167, v[86:87], off
	v_lshlrev_b32_e32 v22, 2, v22
	global_load_dword v168, v22, s[6:7]
	v_or_b32_e32 v22, s28, v61
	v_lshlrev_b32_e32 v2, 12, v22
	v_lshl_add_u64 v[86:87], v[20:21], 0, v[2:3]
	global_load_dword v169, v[86:87], off
	v_lshlrev_b32_e32 v22, 2, v22
	global_load_dword v170, v22, s[6:7]
	v_or_b32_e32 v22, s28, v63
	v_lshlrev_b32_e32 v2, 12, v22
	v_lshl_add_u64 v[86:87], v[20:21], 0, v[2:3]
	global_load_dword v171, v[86:87], off
	v_lshlrev_b32_e32 v22, 2, v22
	global_load_dword v172, v22, s[6:7]
	v_or_b32_e32 v22, s28, v65
	v_lshlrev_b32_e32 v2, 12, v22
	v_lshl_add_u64 v[86:87], v[20:21], 0, v[2:3]
	global_load_dword v173, v[86:87], off
	v_lshlrev_b32_e32 v22, 2, v22
	global_load_dword v174, v22, s[6:7]
	v_or_b32_e32 v22, s28, v67
	v_lshlrev_b32_e32 v2, 12, v22
	v_lshl_add_u64 v[86:87], v[20:21], 0, v[2:3]
	global_load_dword v175, v[86:87], off
	v_lshlrev_b32_e32 v22, 2, v22
	global_load_dword v176, v22, s[6:7]
	v_or_b32_e32 v22, s28, v69
	v_lshlrev_b32_e32 v2, 12, v22
	v_lshl_add_u64 v[86:87], v[20:21], 0, v[2:3]
	global_load_dword v177, v[86:87], off
	v_lshlrev_b32_e32 v22, 2, v22
	global_load_dword v178, v22, s[6:7]
	v_or_b32_e32 v22, s28, v71
	v_lshlrev_b32_e32 v2, 12, v22
	v_lshl_add_u64 v[86:87], v[20:21], 0, v[2:3]
	global_load_dword v179, v[86:87], off
	v_lshlrev_b32_e32 v2, 2, v22
	global_load_dword v180, v2, s[6:7]
	v_or_b32_e32 v85, s28, v73
	v_lshlrev_b32_e32 v2, 12, v85
	v_lshl_add_u64 v[86:87], v[20:21], 0, v[2:3]
	global_load_dword v181, v[86:87], off
	v_lshlrev_b32_e32 v23, 2, v85
	global_load_dword v182, v23, s[6:7]
	v_or_b32_e32 v23, s28, v74
	v_lshlrev_b32_e32 v2, 12, v23
	v_lshl_add_u64 v[86:87], v[20:21], 0, v[2:3]
	global_load_dword v183, v[86:87], off
	v_lshlrev_b32_e32 v23, 2, v23
	global_load_dword v184, v23, s[6:7]
	v_or_b32_e32 v23, s28, v75
	v_lshlrev_b32_e32 v2, 12, v23
	v_lshl_add_u64 v[86:87], v[20:21], 0, v[2:3]
	global_load_dword v185, v[86:87], off
	v_lshlrev_b32_e32 v23, 2, v23
	global_load_dword v186, v23, s[6:7]
	v_or_b32_e32 v23, s28, v76
	v_lshlrev_b32_e32 v2, 12, v23
	v_lshl_add_u64 v[86:87], v[20:21], 0, v[2:3]
	global_load_dword v187, v[86:87], off
	v_lshlrev_b32_e32 v23, 2, v23
	global_load_dword v188, v23, s[6:7]
	v_or_b32_e32 v23, s28, v77
	v_lshlrev_b32_e32 v2, 12, v23
	v_lshl_add_u64 v[86:87], v[20:21], 0, v[2:3]
	global_load_dword v189, v[86:87], off
	v_lshlrev_b32_e32 v23, 2, v23
	global_load_dword v190, v23, s[6:7]
	v_or_b32_e32 v23, s28, v78
	v_lshlrev_b32_e32 v2, 12, v23
	v_lshl_add_u64 v[86:87], v[20:21], 0, v[2:3]
	global_load_dword v191, v[86:87], off
	v_lshlrev_b32_e32 v23, 2, v23
	global_load_dword v192, v23, s[6:7]
	v_or_b32_e32 v23, s28, v79
	v_lshlrev_b32_e32 v2, 12, v23
	v_lshl_add_u64 v[20:21], v[20:21], 0, v[2:3]
	global_load_dword v193, v[20:21], off
	v_lshlrev_b32_e32 v20, 2, v23
	global_load_dword v194, v20, s[6:7]
	s_waitcnt vmcnt(0)
	v_mul_f32_e32 v88, v88, v89
	v_add_u32_e32 v195, v5, v24
	ds_write_b32 v195, v88
	v_mul_f32_e32 v90, v90, v91
	v_add_u32_e32 v196, v5, v26
	ds_write_b32 v196, v90
	v_mul_f32_e32 v92, v92, v93
	v_add_u32_e32 v197, v5, v28
	ds_write_b32 v197, v92
	v_mul_f32_e32 v94, v94, v95
	v_add_u32_e32 v198, v5, v30
	ds_write_b32 v198, v94
	v_mul_f32_e32 v96, v96, v97
	v_add_u32_e32 v199, v5, v32
	ds_write_b32 v199, v96
	v_mul_f32_e32 v98, v98, v99
	v_add_u32_e32 v200, v5, v34
	ds_write_b32 v200, v98
	v_mul_f32_e32 v100, v100, v101
	v_add_u32_e32 v201, v5, v36
	ds_write_b32 v201, v100
	v_mul_f32_e32 v102, v102, v103
	v_add_u32_e32 v202, v5, v38
	ds_write_b32 v202, v102
	v_mul_f32_e32 v104, v104, v105
	v_add_u32_e32 v203, v5, v40
	ds_write_b32 v203, v104
	v_mul_f32_e32 v148, v148, v149
	v_add_u32_e32 v204, v5, v42
	ds_write_b32 v204, v148
	v_mul_f32_e32 v150, v150, v151
	v_add_u32_e32 v205, v5, v44
	ds_write_b32 v205, v150
	v_mul_f32_e32 v152, v152, v153
	v_add_u32_e32 v206, v5, v46
	ds_write_b32 v206, v152
	v_mul_f32_e32 v154, v154, v155
	v_add_u32_e32 v207, v5, v48
	ds_write_b32 v207, v154
	v_mul_f32_e32 v156, v156, v157
	v_add_u32_e32 v210, v5, v50
	ds_write_b32 v210, v156
	v_mul_f32_e32 v158, v158, v159
	v_add_u32_e32 v211, v5, v52
	ds_write_b32 v211, v158
	v_mul_f32_e32 v160, v160, v161
	v_add_u32_e32 v212, v5, v54
	ds_write_b32 v212, v160
	v_mul_f32_e32 v162, v162, v163
	v_add_u32_e32 v213, v5, v56
	ds_write_b32 v213, v162
	v_mul_f32_e32 v165, v165, v166
	v_add_u32_e32 v217, v5, v58
	ds_write_b32 v217, v165
	v_mul_f32_e32 v167, v167, v168
	v_add_u32_e32 v218, v5, v60
	ds_write_b32 v218, v167
	v_mul_f32_e32 v169, v169, v170
	v_add_u32_e32 v219, v5, v62
	ds_write_b32 v219, v169
	v_mul_f32_e32 v171, v171, v172
	v_add_u32_e32 v220, v5, v64
	ds_write_b32 v220, v171
	v_mul_f32_e32 v173, v173, v174
	v_add_u32_e32 v221, v5, v66
	ds_write_b32 v221, v173
	v_mul_f32_e32 v175, v175, v176
	v_add_u32_e32 v222, v5, v68
	ds_write_b32 v222, v175
	v_mul_f32_e32 v177, v177, v178
	v_add_u32_e32 v223, v5, v70
	ds_write_b32 v223, v177
	v_mul_f32_e32 v179, v179, v180
	v_add_u32_e32 v224, v5, v72
	ds_write_b32 v224, v179
	v_mul_f32_e32 v181, v181, v182
	ds_write_b32 v224, v181 offset:264
	v_mul_f32_e32 v183, v183, v184
	ds_write_b32 v224, v183 offset:528
	v_mul_f32_e32 v185, v185, v186
	ds_write_b32 v224, v185 offset:792
	v_mul_f32_e32 v187, v187, v188
	ds_write_b32 v224, v187 offset:1056
	v_mul_f32_e32 v189, v189, v190
	ds_write_b32 v224, v189 offset:1320
	v_mul_f32_e32 v191, v191, v192
	ds_write_b32 v224, v191 offset:1584
	v_mul_f32_e32 v193, v193, v194
	ds_write_b32 v224, v193 offset:1848
	s_branch .Lladder_done_6

.Lladder_done_6:
	s_waitcnt lgkmcnt(0)
	ds_read2_b32 v[86:87], v81 offset1:8
	ds_read2_b32 v[90:91], v81 offset0:33 offset1:41
	ds_read2_b32 v[92:93], v81 offset0:66 offset1:74
	ds_read2_b32 v[94:95], v81 offset0:99 offset1:107
	ds_read2_b32 v[96:97], v81 offset0:132 offset1:140
	s_waitcnt lgkmcnt(4)
	v_bfe_u32 v2, v86, 16, 1
	v_add3_u32 v2, v86, v2, s93
	s_waitcnt lgkmcnt(3)
	v_bfe_u32 v20, v90, 16, 1
	v_lshrrev_b32_e32 v2, 16, v2
	v_add3_u32 v20, v90, v20, s93
	ds_read2_b32 v[98:99], v81 offset0:165 offset1:173
	v_and_or_b32 v20, v20, s33, v2
	s_waitcnt lgkmcnt(3)
	v_bfe_u32 v2, v92, 16, 1
	v_add3_u32 v2, v92, v2, s93
	s_waitcnt lgkmcnt(2)
	v_bfe_u32 v21, v94, 16, 1
	ds_read2_b32 v[100:101], v81 offset0:198 offset1:206
	v_lshrrev_b32_e32 v2, 16, v2
	v_add3_u32 v21, v94, v21, s93
	ds_read2_b32 v[102:103], v81 offset0:231 offset1:239
	v_and_or_b32 v21, v21, s33, v2
	s_waitcnt lgkmcnt(3)
	v_bfe_u32 v2, v96, 16, 1
	v_add3_u32 v2, v96, v2, s93
	s_waitcnt lgkmcnt(2)
	v_bfe_u32 v22, v98, 16, 1
	v_lshrrev_b32_e32 v2, 16, v2
	v_add3_u32 v22, v98, v22, s93
	v_and_or_b32 v22, v22, s33, v2
	s_waitcnt lgkmcnt(1)
	v_bfe_u32 v2, v100, 16, 1
	v_add3_u32 v2, v100, v2, s93
	s_waitcnt lgkmcnt(0)
	v_bfe_u32 v23, v102, 16, 1
	s_bitset1_b32 s30, 11
	v_lshrrev_b32_e32 v2, 16, v2
	v_add3_u32 v23, v102, v23, s93
	s_lshl_b32 s46, s28, 1
	v_and_or_b32 v23, v23, s33, v2
	v_or_b32_e32 v2, s30, v80
	v_lshl_add_u64 v[88:89], v[10:11], 0, s[46:47]
	v_lshlrev_b32_e32 v2, 11, v2
	v_lshl_add_u64 v[104:105], v[88:89], 0, v[2:3]
	v_bfe_u32 v2, v87, 16, 1
	global_store_dwordx4 v[104:105], v[20:23], off
	v_add3_u32 v2, v87, v2, s93
	v_lshrrev_b32_e32 v2, 16, v2
	v_bfe_u32 v20, v91, 16, 1
	v_add3_u32 v20, v91, v20, s93
	v_and_or_b32 v20, v20, s33, v2
	v_bfe_u32 v2, v93, 16, 1
	v_add3_u32 v2, v93, v2, s93
	v_bfe_u32 v21, v95, 16, 1
	v_lshrrev_b32_e32 v2, 16, v2
	v_add3_u32 v21, v95, v21, s93
	v_and_or_b32 v21, v21, s33, v2
	v_bfe_u32 v2, v97, 16, 1
	v_add3_u32 v2, v97, v2, s93
	v_bfe_u32 v22, v99, 16, 1
	v_lshrrev_b32_e32 v2, 16, v2
	v_add3_u32 v22, v99, v22, s93
	v_and_or_b32 v22, v22, s33, v2
	v_bfe_u32 v2, v101, 16, 1
	v_add3_u32 v2, v101, v2, s93
	v_bfe_u32 v23, v103, 16, 1
	v_lshrrev_b32_e32 v2, 16, v2
	v_add3_u32 v23, v103, v23, s93
	v_and_or_b32 v23, v23, s33, v2
	v_or_b32_e32 v2, s30, v82
	v_lshlrev_b32_e32 v2, 11, v2
	ds_read2_b32 v[86:87], v81 offset0:16 offset1:24
	v_lshl_add_u64 v[90:91], v[88:89], 0, v[2:3]
	global_store_dwordx4 v[90:91], v[20:23], off
	ds_read2_b32 v[90:91], v81 offset0:49 offset1:57
	ds_read2_b32 v[92:93], v81 offset0:82 offset1:90
	ds_read2_b32 v[94:95], v81 offset0:115 offset1:123
	s_waitcnt lgkmcnt(3)
	v_bfe_u32 v2, v86, 16, 1
	v_add3_u32 v2, v86, v2, s93
	s_waitcnt lgkmcnt(2)
	v_bfe_u32 v20, v90, 16, 1
	ds_read2_b32 v[96:97], v81 offset0:148 offset1:156
	v_lshrrev_b32_e32 v2, 16, v2
	v_add3_u32 v20, v90, v20, s93
	ds_read2_b32 v[98:99], v81 offset0:181 offset1:189
	v_and_or_b32 v20, v20, s33, v2
	s_waitcnt lgkmcnt(3)
	v_bfe_u32 v2, v92, 16, 1
	v_add3_u32 v2, v92, v2, s93
	s_waitcnt lgkmcnt(2)
	v_bfe_u32 v21, v94, 16, 1
	ds_read2_b32 v[100:101], v81 offset0:214 offset1:222
	v_lshrrev_b32_e32 v2, 16, v2
	v_add3_u32 v21, v94, v21, s93
	ds_read2_b32 v[102:103], v81 offset0:247 offset1:255
	v_and_or_b32 v21, v21, s33, v2
	s_waitcnt lgkmcnt(3)
	v_bfe_u32 v2, v96, 16, 1
	v_add3_u32 v2, v96, v2, s93
	s_waitcnt lgkmcnt(2)
	v_bfe_u32 v22, v98, 16, 1
	v_lshrrev_b32_e32 v2, 16, v2
	v_add3_u32 v22, v98, v22, s93
	v_and_or_b32 v22, v22, s33, v2
	s_waitcnt lgkmcnt(1)
	v_bfe_u32 v2, v100, 16, 1
	v_add3_u32 v2, v100, v2, s93
	s_waitcnt lgkmcnt(0)
	v_bfe_u32 v23, v102, 16, 1
	v_lshrrev_b32_e32 v2, 16, v2
	v_add3_u32 v23, v102, v23, s93
	v_and_or_b32 v23, v23, s33, v2
	v_or_b32_e32 v2, s30, v83
	v_lshlrev_b32_e32 v2, 11, v2
	v_lshl_add_u64 v[104:105], v[88:89], 0, v[2:3]
	v_bfe_u32 v2, v87, 16, 1
	global_store_dwordx4 v[104:105], v[20:23], off
	v_add3_u32 v2, v87, v2, s93
	v_lshrrev_b32_e32 v2, 16, v2
	v_bfe_u32 v20, v91, 16, 1
	v_add3_u32 v20, v91, v20, s93
	v_and_or_b32 v20, v20, s33, v2
	v_bfe_u32 v2, v93, 16, 1
	v_add3_u32 v2, v93, v2, s93
	v_bfe_u32 v21, v95, 16, 1
	v_lshrrev_b32_e32 v2, 16, v2
	v_add3_u32 v21, v95, v21, s93
	v_and_or_b32 v21, v21, s33, v2
	v_bfe_u32 v2, v97, 16, 1
	v_add3_u32 v2, v97, v2, s93
	v_bfe_u32 v22, v99, 16, 1
	v_lshrrev_b32_e32 v2, 16, v2
	v_add3_u32 v22, v99, v22, s93
	v_and_or_b32 v22, v22, s33, v2
	v_bfe_u32 v2, v101, 16, 1
	v_add3_u32 v2, v101, v2, s93
	v_bfe_u32 v23, v103, 16, 1
	v_lshrrev_b32_e32 v2, 16, v2
	v_add3_u32 v23, v103, v23, s93
	v_and_or_b32 v23, v23, s33, v2
	v_or_b32_e32 v2, s30, v84
	v_lshlrev_b32_e32 v2, 11, v2
	v_lshl_add_u64 v[86:87], v[88:89], 0, v[2:3]
	global_store_dwordx4 v[86:87], v[20:23], off
	s_waitcnt lgkmcnt(0)
	s_mov_b64 s[30:31], 0x4000

.LBB0_1882:
	s_andn2_b64 vcc, exec, s[4:5]
	s_cbranch_vccnz .LBB0_1948
	s_load_dwordx2 s[4:5], s[62:63], 0x80
	s_load_dwordx2 s[26:27], s[62:63], 0x90
	v_lshlrev_b32_e32 v2, 2, v4
	s_waitcnt lgkmcnt(0)
	s_add_u32 s6, s4, 0x1000
	s_addc_u32 s7, s5, 0
	s_lshl_b32 s28, s29, 1
	s_lshl_b32 s30, s29, 5
	s_add_i32 s31, s28, 0x1f600
	s_and_b32 s28, s30, 0x3e0
	s_and_b32 s30, s31, 0x1ffc0
	s_lshl_b32 s31, s28, 2
	s_add_u32 s26, s26, s31
	s_addc_u32 s27, s27, 0
	v_lshl_add_u64 v[20:21], s[26:27], 0, v[2:3]
	v_or_b32_e32 v22, s30, v1
	v_lshl_add_u64 v[20:21], v[20:21], 0, s[96:97]
	v_lshlrev_b32_e32 v2, 12, v22
	v_lshl_add_u64 v[86:87], v[20:21], 0, v[2:3]
	s_cmp_eq_u64 s[4:5], 0
	s_cbranch_scc1 .Lladder_ng_7
	global_load_dword v88, v[86:87], off
	v_lshlrev_b32_e32 v22, 2, v22
	global_load_dword v89, v22, s[6:7]
	v_or_b32_e32 v22, s30, v25
	v_lshlrev_b32_e32 v2, 12, v22
	v_lshl_add_u64 v[86:87], v[20:21], 0, v[2:3]
	global_load_dword v90, v[86:87], off
	v_lshlrev_b32_e32 v22, 2, v22
	global_load_dword v91, v22, s[6:7]
	v_or_b32_e32 v22, s30, v27
	v_lshlrev_b32_e32 v2, 12, v22
	v_lshl_add_u64 v[86:87], v[20:21], 0, v[2:3]
	global_load_dword v92, v[86:87], off
	v_lshlrev_b32_e32 v22, 2, v22
	global_load_dword v93, v22, s[6:7]
	v_or_b32_e32 v22, s30, v29
	v_lshlrev_b32_e32 v2, 12, v22
	v_lshl_add_u64 v[86:87], v[20:21], 0, v[2:3]
	global_load_dword v94, v[86:87], off
	v_lshlrev_b32_e32 v22, 2, v22
	global_load_dword v95, v22, s[6:7]
	v_or_b32_e32 v22, s30, v31
	v_lshlrev_b32_e32 v2, 12, v22
	v_lshl_add_u64 v[86:87], v[20:21], 0, v[2:3]
	global_load_dword v96, v[86:87], off
	v_lshlrev_b32_e32 v22, 2, v22
	global_load_dword v97, v22, s[6:7]
	v_or_b32_e32 v22, s30, v33
	v_lshlrev_b32_e32 v2, 12, v22
	v_lshl_add_u64 v[86:87], v[20:21], 0, v[2:3]
	global_load_dword v98, v[86:87], off
	v_lshlrev_b32_e32 v22, 2, v22
	global_load_dword v99, v22, s[6:7]
	v_or_b32_e32 v22, s30, v35
	v_lshlrev_b32_e32 v2, 12, v22
	v_lshl_add_u64 v[86:87], v[20:21], 0, v[2:3]
	global_load_dword v100, v[86:87], off
	v_lshlrev_b32_e32 v22, 2, v22
	global_load_dword v101, v22, s[6:7]
	v_or_b32_e32 v22, s30, v37
	v_lshlrev_b32_e32 v2, 12, v22
	v_lshl_add_u64 v[86:87], v[20:21], 0, v[2:3]
	global_load_dword v102, v[86:87], off
	v_lshlrev_b32_e32 v22, 2, v22
	global_load_dword v103, v22, s[6:7]
	v_or_b32_e32 v22, s30, v39
	v_lshlrev_b32_e32 v2, 12, v22
	v_lshl_add_u64 v[86:87], v[20:21], 0, v[2:3]
	global_load_dword v104, v[86:87], off
	v_lshlrev_b32_e32 v22, 2, v22
	global_load_dword v105, v22, s[6:7]
	v_or_b32_e32 v22, s30, v41
	v_lshlrev_b32_e32 v2, 12, v22
	v_lshl_add_u64 v[86:87], v[20:21], 0, v[2:3]
	global_load_dword v148, v[86:87], off
	v_lshlrev_b32_e32 v22, 2, v22
	global_load_dword v149, v22, s[6:7]
	v_or_b32_e32 v22, s30, v43
	v_lshlrev_b32_e32 v2, 12, v22
	v_lshl_add_u64 v[86:87], v[20:21], 0, v[2:3]
	global_load_dword v150, v[86:87], off
	v_lshlrev_b32_e32 v22, 2, v22
	global_load_dword v151, v22, s[6:7]
	v_or_b32_e32 v22, s30, v45
	v_lshlrev_b32_e32 v2, 12, v22
	v_lshl_add_u64 v[86:87], v[20:21], 0, v[2:3]
	global_load_dword v152, v[86:87], off
	v_lshlrev_b32_e32 v22, 2, v22
	global_load_dword v153, v22, s[6:7]
	v_or_b32_e32 v22, s30, v47
	v_lshlrev_b32_e32 v2, 12, v22
	v_lshl_add_u64 v[86:87], v[20:21], 0, v[2:3]
	global_load_dword v154, v[86:87], off
	v_lshlrev_b32_e32 v22, 2, v22
	global_load_dword v155, v22, s[6:7]
	v_or_b32_e32 v22, s30, v49
	v_lshlrev_b32_e32 v2, 12, v22
	v_lshl_add_u64 v[86:87], v[20:21], 0, v[2:3]
	global_load_dword v156, v[86:87], off
	v_lshlrev_b32_e32 v22, 2, v22
	global_load_dword v157, v22, s[6:7]
	v_or_b32_e32 v22, s30, v51
	v_lshlrev_b32_e32 v2, 12, v22
	v_lshl_add_u64 v[86:87], v[20:21], 0, v[2:3]
	global_load_dword v158, v[86:87], off
	v_lshlrev_b32_e32 v22, 2, v22
	global_load_dword v159, v22, s[6:7]
	v_or_b32_e32 v22, s30, v53
	v_lshlrev_b32_e32 v2, 12, v22
	v_lshl_add_u64 v[86:87], v[20:21], 0, v[2:3]
	global_load_dword v160, v[86:87], off
	v_lshlrev_b32_e32 v22, 2, v22
	global_load_dword v161, v22, s[6:7]
	v_or_b32_e32 v22, s30, v55
	v_lshlrev_b32_e32 v2, 12, v22
	v_lshl_add_u64 v[86:87], v[20:21], 0, v[2:3]
	global_load_dword v162, v[86:87], off
	v_lshlrev_b32_e32 v22, 2, v22
	global_load_dword v163, v22, s[6:7]
	v_or_b32_e32 v22, s30, v57
	v_lshlrev_b32_e32 v2, 12, v22
	v_lshl_add_u64 v[86:87], v[20:21], 0, v[2:3]
	global_load_dword v165, v[86:87], off
	v_lshlrev_b32_e32 v22, 2, v22
	global_load_dword v166, v22, s[6:7]
	v_or_b32_e32 v22, s30, v59
	v_lshlrev_b32_e32 v2, 12, v22
	v_lshl_add_u64 v[86:87], v[20:21], 0, v[2:3]
	global_load_dword v167, v[86:87], off
	v_lshlrev_b32_e32 v22, 2, v22
	global_load_dword v168, v22, s[6:7]
	v_or_b32_e32 v22, s30, v61
	v_lshlrev_b32_e32 v2, 12, v22
	v_lshl_add_u64 v[86:87], v[20:21], 0, v[2:3]
	global_load_dword v169, v[86:87], off
	v_lshlrev_b32_e32 v22, 2, v22
	global_load_dword v170, v22, s[6:7]
	v_or_b32_e32 v22, s30, v63
	v_lshlrev_b32_e32 v2, 12, v22
	v_lshl_add_u64 v[86:87], v[20:21], 0, v[2:3]
	global_load_dword v171, v[86:87], off
	v_lshlrev_b32_e32 v22, 2, v22
	global_load_dword v172, v22, s[6:7]
	v_or_b32_e32 v22, s30, v65
	v_lshlrev_b32_e32 v2, 12, v22
	v_lshl_add_u64 v[86:87], v[20:21], 0, v[2:3]
	global_load_dword v173, v[86:87], off
	v_lshlrev_b32_e32 v22, 2, v22
	global_load_dword v174, v22, s[6:7]
	v_or_b32_e32 v22, s30, v67
	v_lshlrev_b32_e32 v2, 12, v22
	v_lshl_add_u64 v[86:87], v[20:21], 0, v[2:3]
	global_load_dword v175, v[86:87], off
	v_lshlrev_b32_e32 v22, 2, v22
	global_load_dword v176, v22, s[6:7]
	v_or_b32_e32 v22, s30, v69
	v_lshlrev_b32_e32 v2, 12, v22
	v_lshl_add_u64 v[86:87], v[20:21], 0, v[2:3]
	global_load_dword v177, v[86:87], off
	v_lshlrev_b32_e32 v22, 2, v22
	global_load_dword v178, v22, s[6:7]
	v_or_b32_e32 v22, s30, v71
	v_lshlrev_b32_e32 v2, 12, v22
	v_lshl_add_u64 v[86:87], v[20:21], 0, v[2:3]
	global_load_dword v179, v[86:87], off
	v_lshlrev_b32_e32 v2, 2, v22
	global_load_dword v180, v2, s[6:7]
	v_or_b32_e32 v85, s30, v73
	v_lshlrev_b32_e32 v2, 12, v85
	v_lshl_add_u64 v[86:87], v[20:21], 0, v[2:3]
	global_load_dword v181, v[86:87], off
	v_lshlrev_b32_e32 v23, 2, v85
	global_load_dword v182, v23, s[6:7]
	v_or_b32_e32 v23, s30, v74
	v_lshlrev_b32_e32 v2, 12, v23
	v_lshl_add_u64 v[86:87], v[20:21], 0, v[2:3]
	global_load_dword v183, v[86:87], off
	v_lshlrev_b32_e32 v23, 2, v23
	global_load_dword v184, v23, s[6:7]
	v_or_b32_e32 v23, s30, v75
	v_lshlrev_b32_e32 v2, 12, v23
	v_lshl_add_u64 v[86:87], v[20:21], 0, v[2:3]
	global_load_dword v185, v[86:87], off
	v_lshlrev_b32_e32 v23, 2, v23
	global_load_dword v186, v23, s[6:7]
	v_or_b32_e32 v23, s30, v76
	v_lshlrev_b32_e32 v2, 12, v23
	v_lshl_add_u64 v[86:87], v[20:21], 0, v[2:3]
	global_load_dword v187, v[86:87], off
	v_lshlrev_b32_e32 v23, 2, v23
	global_load_dword v188, v23, s[6:7]
	v_or_b32_e32 v23, s30, v77
	v_lshlrev_b32_e32 v2, 12, v23
	v_lshl_add_u64 v[86:87], v[20:21], 0, v[2:3]
	global_load_dword v189, v[86:87], off
	v_lshlrev_b32_e32 v23, 2, v23
	global_load_dword v190, v23, s[6:7]
	v_or_b32_e32 v23, s30, v78
	v_lshlrev_b32_e32 v2, 12, v23
	v_lshl_add_u64 v[86:87], v[20:21], 0, v[2:3]
	global_load_dword v191, v[86:87], off
	v_lshlrev_b32_e32 v23, 2, v23
	global_load_dword v192, v23, s[6:7]
	v_or_b32_e32 v23, s30, v79
	v_lshlrev_b32_e32 v2, 12, v23
	v_lshl_add_u64 v[20:21], v[20:21], 0, v[2:3]
	global_load_dword v193, v[20:21], off
	v_lshlrev_b32_e32 v20, 2, v23
	global_load_dword v194, v20, s[6:7]
	s_waitcnt vmcnt(0)
	v_mul_f32_e32 v88, v88, v89
	v_add_u32_e32 v195, v5, v24
	ds_write_b32 v195, v88
	v_mul_f32_e32 v90, v90, v91
	v_add_u32_e32 v196, v5, v26
	ds_write_b32 v196, v90
	v_mul_f32_e32 v92, v92, v93
	v_add_u32_e32 v197, v5, v28
	ds_write_b32 v197, v92
	v_mul_f32_e32 v94, v94, v95
	v_add_u32_e32 v198, v5, v30
	ds_write_b32 v198, v94
	v_mul_f32_e32 v96, v96, v97
	v_add_u32_e32 v199, v5, v32
	ds_write_b32 v199, v96
	v_mul_f32_e32 v98, v98, v99
	v_add_u32_e32 v200, v5, v34
	ds_write_b32 v200, v98
	v_mul_f32_e32 v100, v100, v101
	v_add_u32_e32 v201, v5, v36
	ds_write_b32 v201, v100
	v_mul_f32_e32 v102, v102, v103
	v_add_u32_e32 v202, v5, v38
	ds_write_b32 v202, v102
	v_mul_f32_e32 v104, v104, v105
	v_add_u32_e32 v203, v5, v40
	ds_write_b32 v203, v104
	v_mul_f32_e32 v148, v148, v149
	v_add_u32_e32 v204, v5, v42
	ds_write_b32 v204, v148
	v_mul_f32_e32 v150, v150, v151
	v_add_u32_e32 v205, v5, v44
	ds_write_b32 v205, v150
	v_mul_f32_e32 v152, v152, v153
	v_add_u32_e32 v206, v5, v46
	ds_write_b32 v206, v152
	v_mul_f32_e32 v154, v154, v155
	v_add_u32_e32 v207, v5, v48
	ds_write_b32 v207, v154
	v_mul_f32_e32 v156, v156, v157
	v_add_u32_e32 v210, v5, v50
	ds_write_b32 v210, v156
	v_mul_f32_e32 v158, v158, v159
	v_add_u32_e32 v211, v5, v52
	ds_write_b32 v211, v158
	v_mul_f32_e32 v160, v160, v161
	v_add_u32_e32 v212, v5, v54
	ds_write_b32 v212, v160
	v_mul_f32_e32 v162, v162, v163
	v_add_u32_e32 v213, v5, v56
	ds_write_b32 v213, v162
	v_mul_f32_e32 v165, v165, v166
	v_add_u32_e32 v217, v5, v58
	ds_write_b32 v217, v165
	v_mul_f32_e32 v167, v167, v168
	v_add_u32_e32 v218, v5, v60
	ds_write_b32 v218, v167
	v_mul_f32_e32 v169, v169, v170
	v_add_u32_e32 v219, v5, v62
	ds_write_b32 v219, v169
	v_mul_f32_e32 v171, v171, v172
	v_add_u32_e32 v220, v5, v64
	ds_write_b32 v220, v171
	v_mul_f32_e32 v173, v173, v174
	v_add_u32_e32 v221, v5, v66
	ds_write_b32 v221, v173
	v_mul_f32_e32 v175, v175, v176
	v_add_u32_e32 v222, v5, v68
	ds_write_b32 v222, v175
	v_mul_f32_e32 v177, v177, v178
	v_add_u32_e32 v223, v5, v70
	ds_write_b32 v223, v177
	v_mul_f32_e32 v179, v179, v180
	v_add_u32_e32 v224, v5, v72
	ds_write_b32 v224, v179
	v_mul_f32_e32 v181, v181, v182
	ds_write_b32 v224, v181 offset:264
	v_mul_f32_e32 v183, v183, v184
	ds_write_b32 v224, v183 offset:528
	v_mul_f32_e32 v185, v185, v186
	ds_write_b32 v224, v185 offset:792
	v_mul_f32_e32 v187, v187, v188
	ds_write_b32 v224, v187 offset:1056
	v_mul_f32_e32 v189, v189, v190
	ds_write_b32 v224, v189 offset:1320
	v_mul_f32_e32 v191, v191, v192
	ds_write_b32 v224, v191 offset:1584
	v_mul_f32_e32 v193, v193, v194
	ds_write_b32 v224, v193 offset:1848
	s_branch .Lladder_done_7
.Lladder_ng_7:
	global_load_dword v88, v[86:87], off
	v_or_b32_e32 v22, s30, v25
	v_lshlrev_b32_e32 v2, 12, v22
	v_lshl_add_u64 v[86:87], v[20:21], 0, v[2:3]
	global_load_dword v89, v[86:87], off
	v_or_b32_e32 v22, s30, v27
	v_lshlrev_b32_e32 v2, 12, v22
	v_lshl_add_u64 v[86:87], v[20:21], 0, v[2:3]
	global_load_dword v90, v[86:87], off
	v_or_b32_e32 v22, s30, v29
	v_lshlrev_b32_e32 v2, 12, v22
	v_lshl_add_u64 v[86:87], v[20:21], 0, v[2:3]
	global_load_dword v91, v[86:87], off
	v_or_b32_e32 v22, s30, v31
	v_lshlrev_b32_e32 v2, 12, v22
	v_lshl_add_u64 v[86:87], v[20:21], 0, v[2:3]
	global_load_dword v92, v[86:87], off
	v_or_b32_e32 v22, s30, v33
	v_lshlrev_b32_e32 v2, 12, v22
	v_lshl_add_u64 v[86:87], v[20:21], 0, v[2:3]
	global_load_dword v93, v[86:87], off
	v_or_b32_e32 v22, s30, v35
	v_lshlrev_b32_e32 v2, 12, v22
	v_lshl_add_u64 v[86:87], v[20:21], 0, v[2:3]
	global_load_dword v94, v[86:87], off
	v_or_b32_e32 v22, s30, v37
	v_lshlrev_b32_e32 v2, 12, v22
	v_lshl_add_u64 v[86:87], v[20:21], 0, v[2:3]
	global_load_dword v95, v[86:87], off
	v_or_b32_e32 v22, s30, v39
	v_lshlrev_b32_e32 v2, 12, v22
	v_lshl_add_u64 v[86:87], v[20:21], 0, v[2:3]
	global_load_dword v96, v[86:87], off
	v_or_b32_e32 v22, s30, v41
	v_lshlrev_b32_e32 v2, 12, v22
	v_lshl_add_u64 v[86:87], v[20:21], 0, v[2:3]
	global_load_dword v97, v[86:87], off
	v_or_b32_e32 v22, s30, v43
	v_lshlrev_b32_e32 v2, 12, v22
	v_lshl_add_u64 v[86:87], v[20:21], 0, v[2:3]
	global_load_dword v98, v[86:87], off
	v_or_b32_e32 v22, s30, v45
	v_lshlrev_b32_e32 v2, 12, v22
	v_lshl_add_u64 v[86:87], v[20:21], 0, v[2:3]
	global_load_dword v99, v[86:87], off
	v_or_b32_e32 v22, s30, v47
	v_lshlrev_b32_e32 v2, 12, v22
	v_lshl_add_u64 v[86:87], v[20:21], 0, v[2:3]
	global_load_dword v100, v[86:87], off
	v_or_b32_e32 v22, s30, v49
	v_lshlrev_b32_e32 v2, 12, v22
	v_lshl_add_u64 v[86:87], v[20:21], 0, v[2:3]
	global_load_dword v101, v[86:87], off
	v_or_b32_e32 v22, s30, v51
	v_lshlrev_b32_e32 v2, 12, v22
	v_lshl_add_u64 v[86:87], v[20:21], 0, v[2:3]
	global_load_dword v102, v[86:87], off
	v_or_b32_e32 v22, s30, v53
	v_lshlrev_b32_e32 v2, 12, v22
	v_lshl_add_u64 v[86:87], v[20:21], 0, v[2:3]
	global_load_dword v103, v[86:87], off
	v_or_b32_e32 v22, s30, v55
	v_lshlrev_b32_e32 v2, 12, v22
	v_lshl_add_u64 v[86:87], v[20:21], 0, v[2:3]
	global_load_dword v104, v[86:87], off
	v_or_b32_e32 v22, s30, v57
	v_lshlrev_b32_e32 v2, 12, v22
	v_lshl_add_u64 v[86:87], v[20:21], 0, v[2:3]
	global_load_dword v105, v[86:87], off
	v_or_b32_e32 v22, s30, v59
	v_lshlrev_b32_e32 v2, 12, v22
	v_lshl_add_u64 v[86:87], v[20:21], 0, v[2:3]
	global_load_dword v148, v[86:87], off
	v_or_b32_e32 v22, s30, v61
	v_lshlrev_b32_e32 v2, 12, v22
	v_lshl_add_u64 v[86:87], v[20:21], 0, v[2:3]
	global_load_dword v149, v[86:87], off
	v_or_b32_e32 v22, s30, v63
	v_lshlrev_b32_e32 v2, 12, v22
	v_lshl_add_u64 v[86:87], v[20:21], 0, v[2:3]
	global_load_dword v150, v[86:87], off
	v_or_b32_e32 v22, s30, v65
	v_lshlrev_b32_e32 v2, 12, v22
	v_lshl_add_u64 v[86:87], v[20:21], 0, v[2:3]
	global_load_dword v151, v[86:87], off
	v_or_b32_e32 v22, s30, v67
	v_lshlrev_b32_e32 v2, 12, v22
	v_lshl_add_u64 v[86:87], v[20:21], 0, v[2:3]
	global_load_dword v152, v[86:87], off
	v_or_b32_e32 v22, s30, v69
	v_lshlrev_b32_e32 v2, 12, v22
	v_lshl_add_u64 v[86:87], v[20:21], 0, v[2:3]
	global_load_dword v153, v[86:87], off
	v_or_b32_e32 v22, s30, v71
	v_lshlrev_b32_e32 v2, 12, v22
	v_lshl_add_u64 v[86:87], v[20:21], 0, v[2:3]
	global_load_dword v154, v[86:87], off
	v_or_b32_e32 v85, s30, v73
	v_lshlrev_b32_e32 v2, 12, v85
	v_lshl_add_u64 v[86:87], v[20:21], 0, v[2:3]
	global_load_dword v155, v[86:87], off
	v_or_b32_e32 v23, s30, v74
	v_lshlrev_b32_e32 v2, 12, v23
	v_lshl_add_u64 v[86:87], v[20:21], 0, v[2:3]
	global_load_dword v156, v[86:87], off
	v_or_b32_e32 v23, s30, v75
	v_lshlrev_b32_e32 v2, 12, v23
	v_lshl_add_u64 v[86:87], v[20:21], 0, v[2:3]
	global_load_dword v157, v[86:87], off
	v_or_b32_e32 v23, s30, v76
	v_lshlrev_b32_e32 v2, 12, v23
	v_lshl_add_u64 v[86:87], v[20:21], 0, v[2:3]
	global_load_dword v158, v[86:87], off
	v_or_b32_e32 v23, s30, v77
	v_lshlrev_b32_e32 v2, 12, v23
	v_lshl_add_u64 v[86:87], v[20:21], 0, v[2:3]
	global_load_dword v159, v[86:87], off
	v_or_b32_e32 v23, s30, v78
	v_lshlrev_b32_e32 v2, 12, v23
	v_lshl_add_u64 v[86:87], v[20:21], 0, v[2:3]
	global_load_dword v160, v[86:87], off
	v_or_b32_e32 v23, s30, v79
	v_lshlrev_b32_e32 v2, 12, v23
	v_lshl_add_u64 v[20:21], v[20:21], 0, v[2:3]
	global_load_dword v161, v[20:21], off
	s_waitcnt vmcnt(0)
	v_add_u32_e32 v162, v5, v24
	ds_write_b32 v162, v88
	v_add_u32_e32 v163, v5, v26
	ds_write_b32 v163, v89
	v_add_u32_e32 v165, v5, v28
	ds_write_b32 v165, v90
	v_add_u32_e32 v166, v5, v30
	ds_write_b32 v166, v91
	v_add_u32_e32 v167, v5, v32
	ds_write_b32 v167, v92
	v_add_u32_e32 v168, v5, v34
	ds_write_b32 v168, v93
	v_add_u32_e32 v169, v5, v36
	ds_write_b32 v169, v94
	v_add_u32_e32 v170, v5, v38
	ds_write_b32 v170, v95
	v_add_u32_e32 v171, v5, v40
	ds_write_b32 v171, v96
	v_add_u32_e32 v172, v5, v42
	ds_write_b32 v172, v97
	v_add_u32_e32 v173, v5, v44
	ds_write_b32 v173, v98
	v_add_u32_e32 v174, v5, v46
	ds_write_b32 v174, v99
	v_add_u32_e32 v175, v5, v48
	ds_write_b32 v175, v100
	v_add_u32_e32 v176, v5, v50
	ds_write_b32 v176, v101
	v_add_u32_e32 v177, v5, v52
	ds_write_b32 v177, v102
	v_add_u32_e32 v178, v5, v54
	ds_write_b32 v178, v103
	v_add_u32_e32 v179, v5, v56
	ds_write_b32 v179, v104
	v_add_u32_e32 v180, v5, v58
	ds_write_b32 v180, v105
	v_add_u32_e32 v181, v5, v60
	ds_write_b32 v181, v148
	v_add_u32_e32 v182, v5, v62
	ds_write_b32 v182, v149
	v_add_u32_e32 v183, v5, v64
	ds_write_b32 v183, v150
	v_add_u32_e32 v184, v5, v66
	ds_write_b32 v184, v151
	v_add_u32_e32 v185, v5, v68
	ds_write_b32 v185, v152
	v_add_u32_e32 v186, v5, v70
	ds_write_b32 v186, v153
	v_add_u32_e32 v187, v5, v72
	ds_write_b32 v187, v154
	ds_write_b32 v187, v155 offset:264
	ds_write_b32 v187, v156 offset:528
	ds_write_b32 v187, v157 offset:792
	ds_write_b32 v187, v158 offset:1056
	ds_write_b32 v187, v159 offset:1320
	ds_write_b32 v187, v160 offset:1584
	ds_write_b32 v187, v161 offset:1848
.Lladder_done_7:
	s_waitcnt lgkmcnt(0)
	ds_read2_b32 v[86:87], v81 offset1:8
	ds_read2_b32 v[90:91], v81 offset0:33 offset1:41
	ds_read2_b32 v[92:93], v81 offset0:66 offset1:74
	ds_read2_b32 v[94:95], v81 offset0:99 offset1:107
	ds_read2_b32 v[96:97], v81 offset0:132 offset1:140
	ds_read2_b32 v[98:99], v81 offset0:165 offset1:173
	s_waitcnt lgkmcnt(5)
	v_bfe_u32 v2, v86, 16, 1
	v_add3_u32 v2, v86, v2, s93
	s_waitcnt lgkmcnt(4)
	v_bfe_u32 v20, v90, 16, 1
	v_lshrrev_b32_e32 v2, 16, v2
	v_add3_u32 v20, v90, v20, s93
	v_and_or_b32 v20, v20, s33, v2
	s_waitcnt lgkmcnt(3)
	v_bfe_u32 v2, v92, 16, 1
	v_add3_u32 v2, v92, v2, s93
	s_waitcnt lgkmcnt(2)
	v_bfe_u32 v21, v94, 16, 1
	ds_read2_b32 v[100:101], v81 offset0:198 offset1:206
	v_lshrrev_b32_e32 v2, 16, v2
	v_add3_u32 v21, v94, v21, s93
	ds_read2_b32 v[102:103], v81 offset0:231 offset1:239
	v_and_or_b32 v21, v21, s33, v2
	s_waitcnt lgkmcnt(3)
	v_bfe_u32 v2, v96, 16, 1
	v_add3_u32 v2, v96, v2, s93
	s_waitcnt lgkmcnt(2)
	v_bfe_u32 v22, v98, 16, 1
	v_lshrrev_b32_e32 v2, 16, v2
	v_add3_u32 v22, v98, v22, s93
	v_and_or_b32 v22, v22, s33, v2
	s_waitcnt lgkmcnt(1)
	v_bfe_u32 v2, v100, 16, 1
	v_add3_u32 v2, v100, v2, s93
	s_waitcnt lgkmcnt(0)
	v_bfe_u32 v23, v102, 16, 1
	v_lshrrev_b32_e32 v2, 16, v2
	v_add3_u32 v23, v102, v23, s93
	s_lshl_b32 s46, s30, 1
	v_and_or_b32 v23, v23, s33, v2
	v_or_b32_e32 v2, s28, v80
	v_lshl_add_u64 v[88:89], v[14:15], 0, s[46:47]
	v_lshlrev_b32_e32 v2, 11, v2
	v_lshl_add_u64 v[104:105], v[88:89], 0, v[2:3]
	v_bfe_u32 v2, v87, 16, 1
	global_store_dwordx4 v[104:105], v[20:23], off
	v_add3_u32 v2, v87, v2, s93
	v_lshrrev_b32_e32 v2, 16, v2
	v_bfe_u32 v20, v91, 16, 1
	v_add3_u32 v20, v91, v20, s93
	v_and_or_b32 v20, v20, s33, v2
	v_bfe_u32 v2, v93, 16, 1
	v_add3_u32 v2, v93, v2, s93
	v_bfe_u32 v21, v95, 16, 1
	v_lshrrev_b32_e32 v2, 16, v2
	v_add3_u32 v21, v95, v21, s93
	v_and_or_b32 v21, v21, s33, v2
	v_bfe_u32 v2, v97, 16, 1
	v_add3_u32 v2, v97, v2, s93
	v_bfe_u32 v22, v99, 16, 1
	v_lshrrev_b32_e32 v2, 16, v2
	v_add3_u32 v22, v99, v22, s93
	v_and_or_b32 v22, v22, s33, v2
	v_bfe_u32 v2, v101, 16, 1
	v_add3_u32 v2, v101, v2, s93
	v_bfe_u32 v23, v103, 16, 1
	v_lshrrev_b32_e32 v2, 16, v2
	v_add3_u32 v23, v103, v23, s93
	v_and_or_b32 v23, v23, s33, v2
	v_or_b32_e32 v2, s28, v82
	v_lshlrev_b32_e32 v2, 11, v2
	ds_read2_b32 v[86:87], v81 offset0:16 offset1:24
	v_lshl_add_u64 v[90:91], v[88:89], 0, v[2:3]
	global_store_dwordx4 v[90:91], v[20:23], off
	ds_read2_b32 v[90:91], v81 offset0:49 offset1:57
	ds_read2_b32 v[92:93], v81 offset0:82 offset1:90
	ds_read2_b32 v[94:95], v81 offset0:115 offset1:123
	s_waitcnt lgkmcnt(3)
	v_bfe_u32 v2, v86, 16, 1
	v_add3_u32 v2, v86, v2, s93
	s_waitcnt lgkmcnt(2)
	v_bfe_u32 v20, v90, 16, 1
	ds_read2_b32 v[96:97], v81 offset0:148 offset1:156
	v_lshrrev_b32_e32 v2, 16, v2
	v_add3_u32 v20, v90, v20, s93
	ds_read2_b32 v[98:99], v81 offset0:181 offset1:189
	v_and_or_b32 v20, v20, s33, v2
	s_waitcnt lgkmcnt(3)
	v_bfe_u32 v2, v92, 16, 1
	v_add3_u32 v2, v92, v2, s93
	s_waitcnt lgkmcnt(2)
	v_bfe_u32 v21, v94, 16, 1
	ds_read2_b32 v[100:101], v81 offset0:214 offset1:222
	v_lshrrev_b32_e32 v2, 16, v2
	v_add3_u32 v21, v94, v21, s93
	ds_read2_b32 v[102:103], v81 offset0:247 offset1:255
	v_and_or_b32 v21, v21, s33, v2
	s_waitcnt lgkmcnt(3)
	v_bfe_u32 v2, v96, 16, 1
	v_add3_u32 v2, v96, v2, s93
	s_waitcnt lgkmcnt(2)
	v_bfe_u32 v22, v98, 16, 1
	v_lshrrev_b32_e32 v2, 16, v2
	v_add3_u32 v22, v98, v22, s93
	v_and_or_b32 v22, v22, s33, v2
	s_waitcnt lgkmcnt(1)
	v_bfe_u32 v2, v100, 16, 1
	v_add3_u32 v2, v100, v2, s93
	s_waitcnt lgkmcnt(0)
	v_bfe_u32 v23, v102, 16, 1
	v_lshrrev_b32_e32 v2, 16, v2
	v_add3_u32 v23, v102, v23, s93
	v_and_or_b32 v23, v23, s33, v2
	v_or_b32_e32 v2, s28, v83
	v_lshlrev_b32_e32 v2, 11, v2
	v_lshl_add_u64 v[104:105], v[88:89], 0, v[2:3]
	v_bfe_u32 v2, v87, 16, 1
	global_store_dwordx4 v[104:105], v[20:23], off
	v_add3_u32 v2, v87, v2, s93
	v_lshrrev_b32_e32 v2, 16, v2
	v_bfe_u32 v20, v91, 16, 1
	v_add3_u32 v20, v91, v20, s93
	v_and_or_b32 v20, v20, s33, v2
	v_bfe_u32 v2, v93, 16, 1
	v_add3_u32 v2, v93, v2, s93
	v_bfe_u32 v21, v95, 16, 1
	v_lshrrev_b32_e32 v2, 16, v2
	v_add3_u32 v21, v95, v21, s93
	v_and_or_b32 v21, v21, s33, v2
	v_bfe_u32 v2, v97, 16, 1
	v_add3_u32 v2, v97, v2, s93
	v_bfe_u32 v22, v99, 16, 1
	v_lshrrev_b32_e32 v2, 16, v2
	v_add3_u32 v22, v99, v22, s93
	v_and_or_b32 v22, v22, s33, v2
	v_bfe_u32 v2, v101, 16, 1
	v_add3_u32 v2, v101, v2, s93
	v_bfe_u32 v23, v103, 16, 1
	v_lshrrev_b32_e32 v2, 16, v2
	v_add3_u32 v23, v103, v23, s93
	v_and_or_b32 v23, v23, s33, v2
	v_or_b32_e32 v2, s28, v84
	v_lshlrev_b32_e32 v2, 11, v2
	v_lshl_add_u64 v[86:87], v[88:89], 0, v[2:3]
	global_store_dwordx4 v[86:87], v[20:23], off
	s_waitcnt lgkmcnt(0)
	s_mov_b64 s[30:31], 0x4000
